# grid barrier: 2-level protocol polling TOP directly (no XGEN hop), L1 invalidate issued at arrival instead of after completion
# speedup vs baseline: 1.0689x; 1.0327x over previous
; DI unsigned xb_add(unsigned* p, unsigned v) { return __hip_atomic_fetch_add(p, v, __ATOMIC_RELAXED, __HIP_MEMORY_SCOPE_AGENT); }
; DI unsigned xb_xcc_id() { return (unsigned)__builtin_amdgcn_s_getreg((3 << 11) | 20) & 0xFu; }
; DI XcdBarrier xcd_barrier_post(unsigned* bar, volatile unsigned* st) {
;   XcdBarrier b; b.bar = bar; b.x = xb_xcc_id(); b.st = st;
;   if (threadIdx.x == 0) (void)xb_add(&bar[XB_XCNT(b.x)], 1u);
;   return b;
; }
; __global__ void __launch_bounds__(NT, 2) fwd_kernel(Params p) {
;   cg::grid_group grid = cg::this_grid();
;   __shared__ __attribute__((aligned(16))) bf16 lds[GEMM_LDS_BF16 + 256];
;   float* sm = (float*)lds;
;   unsigned char* ws = p.ws;
;   Ctx c{p, sm};
;   __shared__ unsigned bar_st[2];
;   if (threadIdx.x == 0) { bar_st[0] = 0u; bar_st[1] = 0u; }
;   __syncthreads();
;   (void)xcd_barrier_post((unsigned*)(ws + WS_BAR), bar_st);
_Z10fwd_kernel6Params:
	s_load_dwordx2 s[88:89], s[0:1], 0xb0
	s_load_dwordx4 s[4:7], s[0:1], 0xa0
	s_mov_b32 s38, s2
	s_add_u32 s2, s0, 0xb8
	s_addc_u32 s3, s1, 0
	v_and_b32_e32 v172, 0x3ff, v0
	v_writelane_b32 v255, 1, 1
	s_waitcnt lgkmcnt(0)
	v_writelane_b32 v252, s4, 0
	s_nop 1
	v_writelane_b32 v252, s5, 1
	v_writelane_b32 v252, s6, 2
	v_writelane_b32 v252, s7, 3
	s_load_dwordx8 s[4:11], s[0:1], 0x80
	s_waitcnt lgkmcnt(0)
	v_writelane_b32 v252, s4, 4
	s_nop 1
	v_writelane_b32 v252, s5, 5
	v_writelane_b32 v252, s6, 6
	v_writelane_b32 v252, s7, 7
	v_writelane_b32 v252, s8, 8
	v_writelane_b32 v252, s9, 9
	v_writelane_b32 v252, s10, 10
	v_writelane_b32 v252, s11, 11
	v_writelane_b32 v252, s2, 12
	v_cmp_eq_u32_e64 s[4:5], 0, v172
	s_nop 0
	v_writelane_b32 v252, s3, 13
	s_mov_b64 s[2:3], exec
	v_writelane_b32 v252, s4, 14
	s_nop 1
	v_writelane_b32 v252, s5, 15
	s_and_b64 s[4:5], s[2:3], s[4:5]
	s_mov_b64 exec, s[4:5]
	v_mov_b32_e32 v2, 0
	v_mov_b32_e32 v3, v2
	v_mov_b32_e32 v1, 0x12200
	ds_write_b64 v1, v[2:3]
	s_or_b64 exec, exec, s[2:3]
	s_load_dwordx2 s[40:41], s[0:1], 0xb8
	s_load_dword s23, s[0:1], 0xc0
	s_waitcnt lgkmcnt(0)
	s_barrier
	s_getreg_b32 s6, hwreg(HW_REG_XCC_ID, 0, 4)
	s_mov_b64 s[2:3], exec
	v_readlane_b32 s4, v252, 14
	v_readlane_b32 s5, v252, 15
	s_and_b64 s[4:5], s[2:3], s[4:5]
	s_mov_b64 exec, s[4:5]
	s_cbranch_execz .LBB0_5
	s_mov_b64 s[4:5], exec
	v_mbcnt_lo_u32_b32 v1, s4, 0
	v_mbcnt_hi_u32_b32 v1, s5, v1
	v_cmp_eq_u32_e32 vcc, 0, v1
	s_and_b64 s[8:9], exec, vcc
	s_mov_b64 exec, s[8:9]
	s_cbranch_execz .LBB0_5
	s_lshl_b32 s6, s6, 8
	s_and_b32 s6, s6, 0xf00
	s_bcnt1_i32_b64 s4, s[4:5]
	v_mov_b32_e32 v1, s6
	v_mov_b32_e32 v2, s4
	global_atomic_add v1, v2, s[88:89] offset:1024

; DI unsigned xb_ld(unsigned* p) { return __hip_atomic_load(p, __ATOMIC_RELAXED, __HIP_MEMORY_SCOPE_AGENT); }
; DI unsigned xb_add(unsigned* p, unsigned v) { return __hip_atomic_fetch_add(p, v, __ATOMIC_RELAXED, __HIP_MEMORY_SCOPE_AGENT); }
; #define XB_SPIN(cond, bar) do { unsigned _sp = 0; while (cond) { __builtin_amdgcn_s_sleep(1); \
;     if ((++_sp & 255u) == 0u) { if (xb_ld(&(bar)[XB_TMO])) break; if (_sp > XB_SPIN_CAP) { atomicAdd(&(bar)[XB_TMO], 1u); break; } } } } while (0)
; DI void xcd_barrier(const XcdBarrier& b) {
;   asm volatile("s_waitcnt vmcnt(0)" ::: "memory");
;   __syncthreads();
;   if (threadIdx.x == 0) {
;     unsigned* bar = b.bar;
;     __builtin_amdgcn_s_waitcnt(0);
;     unsigned nloc = b.st[0], nx = b.st[1];
;     if (nloc == 0u) { xcd_barrier_complete(bar, b.x, nloc, nx); b.st[0] = nloc; b.st[1] = nx; }
;     const unsigned old = xb_add(&bar[XB_XSUB(b.x)], 1u);
;     const unsigned gen = old / nloc;
;     if (old + 1u == (gen + 1u) * nloc) {
;       __builtin_amdgcn_fence(__ATOMIC_RELEASE, "agent");
;       asm volatile("s_waitcnt vmcnt(0)" ::: "memory");
;       const unsigned og = xb_add(&bar[XB_TOP], 1u);
;       const unsigned tg = og / nx;
;       if (og + 1u == (tg + 1u) * nx) xb_add(&bar[XB_TOPGEN], 1u);
;       else XB_SPIN(xb_ld(&bar[XB_TOPGEN]) == tg, bar);
;       __builtin_amdgcn_fence(__ATOMIC_ACQUIRE, "agent");
;       xb_add(&bar[XB_XGEN(b.x)], 1u);
;       asm volatile("s_waitcnt vmcnt(0)" ::: "memory");
;     } else {
;       XB_SPIN(xb_ld(&bar[XB_XGEN(b.x)]) == gen, bar);
;       __builtin_amdgcn_fence(__ATOMIC_ACQUIRE, "agent");
;       asm volatile("s_waitcnt vmcnt(0)" ::: "memory");
;     }
;   }
;   __syncthreads();
; }
.LBB0_142:
	s_or_b64 exec, exec, s[0:1]
	s_getreg_b32 s2, hwreg(HW_REG_XCC_ID, 0, 4)
	s_waitcnt vmcnt(0)
	s_barrier
	s_mov_b64 s[0:1], exec
	v_readlane_b32 s4, v252, 14
	v_readlane_b32 s5, v252, 15
	s_and_b64 s[4:5], s[0:1], s[4:5]
	s_mov_b64 exec, s[4:5]
	s_cbranch_execz .LBB0_194
	s_getreg_b32 s4, hwreg(HW_REG_XCC_ID, 0, 4)
	v_mov_b32_e32 v1, 0x12200
	ds_read_b64 v[2:3], v1
	s_lshl_b32 s4, s4, 8
	s_and_b32 s4, s4, 0xf00
	s_add_u32 s2, s88, s4
	s_addc_u32 s3, s89, 0
	v_mov_b32_e32 v5, 1
	v_mov_b32_e32 v6, 0x1000
	global_atomic_add v5, v6, v5, s[2:3] offset:1024 sc0
	v_readlane_b32 s5, v255, 1
	s_add_i32 s5, s5, 1
	s_nop 0
	v_writelane_b32 v255, s5, 1
	v_mov_b32_e32 v6, 0x3400
	s_waitcnt lgkmcnt(0)
	v_readfirstlane_b32 s6, v2
	v_readfirstlane_b32 s7, v3
	s_mul_i32 s8, s5, s6
	s_mul_i32 s9, s5, s7
	s_mov_b32 s11, 0
	s_waitcnt vmcnt(0)
	v_readfirstlane_b32 s10, v5
	s_add_i32 s10, s10, 1
	s_cmp_lg_u32 s10, s8
	s_cbranch_scc1 .Lsy0_inv
	buffer_wbl2 sc1
	v_mov_b32_e32 v5, 1
	s_waitcnt vmcnt(0)
	global_atomic_add v6, v5, s[88:89]

;   DI bf16* WL() const { return (bf16*)(p.ws + WS_WL); }
;   DI bf16* HY() const { return (bf16*)(p.ws + WS_HY); }
;   DI bf16* P() const { return (bf16*)(p.ws + WS_P); }
; DI unsigned xb_ld(unsigned* p) { return __hip_atomic_load(p, __ATOMIC_RELAXED, __HIP_MEMORY_SCOPE_AGENT); }
; DI unsigned xb_add(unsigned* p, unsigned v) { return __hip_atomic_fetch_add(p, v, __ATOMIC_RELAXED, __HIP_MEMORY_SCOPE_AGENT); }
; #define XB_SPIN(cond, bar) do { unsigned _sp = 0; while (cond) { __builtin_amdgcn_s_sleep(1); \
;     if ((++_sp & 255u) == 0u) { if (xb_ld(&(bar)[XB_TMO])) break; if (_sp > XB_SPIN_CAP) { atomicAdd(&(bar)[XB_TMO], 1u); break; } } } } while (0)
; DI void xcd_barrier(const XcdBarrier& b) {
;   asm volatile("s_waitcnt vmcnt(0)" ::: "memory");
;   __syncthreads();
;   if (threadIdx.x == 0) {
;     unsigned* bar = b.bar;
;     __builtin_amdgcn_s_waitcnt(0);
;     unsigned nloc = b.st[0], nx = b.st[1];
;     if (nloc == 0u) { xcd_barrier_complete(bar, b.x, nloc, nx); b.st[0] = nloc; b.st[1] = nx; }
;     const unsigned old = xb_add(&bar[XB_XSUB(b.x)], 1u);
;     const unsigned gen = old / nloc;
;     if (old + 1u == (gen + 1u) * nloc) {
;       __builtin_amdgcn_fence(__ATOMIC_RELEASE, "agent");
;       asm volatile("s_waitcnt vmcnt(0)" ::: "memory");
;       const unsigned og = xb_add(&bar[XB_TOP], 1u);
;       const unsigned tg = og / nx;
;       if (og + 1u == (tg + 1u) * nx) xb_add(&bar[XB_TOPGEN], 1u);
;       else XB_SPIN(xb_ld(&bar[XB_TOPGEN]) == tg, bar);
;       __builtin_amdgcn_fence(__ATOMIC_ACQUIRE, "agent");
;       xb_add(&bar[XB_XGEN(b.x)], 1u);
;       asm volatile("s_waitcnt vmcnt(0)" ::: "memory");
;     } else {
;       XB_SPIN(xb_ld(&bar[XB_XGEN(b.x)]) == gen, bar);
;       __builtin_amdgcn_fence(__ATOMIC_ACQUIRE, "agent");
;       asm volatile("s_waitcnt vmcnt(0)" ::: "memory");
;     }
;   }
;   __syncthreads();
; }
; __global__ void __launch_bounds__(NT, 2) fwd_kernel(Params p) {
;     ...
;   for (int l = 0; l < 4; ++l) {
;     const int li = l >> 1;
;     const int rows_in = (l <= 2) ? MT : MLAT, rows_out = (l <= 1) ? MT : MLAT;
;     phase_wconv_rest(c, l);
;     if ((l & 1) == 0) {
;       mfma_gemm_big(RowPtr{c.HY(), D}, RowPtr{c.WL() + WL_IN / 2, D}, rows_in, 2560, D, EpiStoreP4{c.P()}, lds);
.Lsy0_poll:
	global_load_dword v5, v6, s[88:89] sc1
	s_waitcnt vmcnt(0)
	v_readfirstlane_b32 s10, v5
	s_sub_i32 s10, s10, s9
	s_cmp_ge_i32 s10, 0
	s_cbranch_scc1 .Lsy0_done
	s_add_i32 s11, s11, 1
	s_sleep 1
	s_cmp_lt_u32 s11, 0x400000
	s_cbranch_scc1 .Lsy0_poll
.Lsy0_done:
.LBB0_194:
	v_writelane_b32 v252, s34, 39
	s_nop 1
	v_writelane_b32 v252, s35, 40
	v_writelane_b32 v252, s44, 41
	s_nop 1
	v_writelane_b32 v252, s45, 42
	v_writelane_b32 v252, s46, 43
	v_writelane_b32 v252, s47, 44
	v_writelane_b32 v252, s48, 45
	v_writelane_b32 v252, s49, 46
	v_writelane_b32 v252, s50, 47
	v_writelane_b32 v252, s51, 48
	v_writelane_b32 v252, s52, 49
	v_writelane_b32 v252, s53, 50
	v_writelane_b32 v252, s54, 51
	v_writelane_b32 v252, s55, 52
	v_writelane_b32 v252, s56, 53
	v_writelane_b32 v252, s57, 54
	v_writelane_b32 v252, s58, 55
	v_writelane_b32 v252, s59, 56
	s_or_b64 exec, exec, s[0:1]
	s_add_u32 s44, s88, 0x728000
	s_addc_u32 s45, s89, 0
	s_add_u32 s56, s88, 0x928000
	s_addc_u32 s57, s89, 0
	s_add_u32 s48, s88, 0x988000
	s_addc_u32 s49, s89, 0
	s_add_u32 s60, s88, 0x1128000
	s_addc_u32 s61, s89, 0
	s_add_u32 s62, s88, 0x3228000
	s_addc_u32 s63, s89, 0
	s_and_b32 s1, s40, 7
	s_cmp_lg_u32 s1, 0
	s_cselect_b64 s[2:3], -1, 0
	v_writelane_b32 v252, s2, 57
	s_mul_i32 s0, s41, s40
	s_ashr_i32 s41, s40, 3
	v_writelane_b32 v252, s3, 58
	s_mul_i32 s71, s0, s23
	v_readlane_b32 s6, v252, 35
	s_lshr_b32 s2, s6, 3
	v_readlane_b32 s7, v252, 36
	v_writelane_b32 v252, s2, 59
	s_and_b32 s2, s6, 7
	s_add_u32 s34, s88, 0x200
	s_addc_u32 s35, s89, 0
	s_add_u32 s58, s88, 0x1000
	s_addc_u32 s59, s89, 0
	s_add_u32 s4, s88, 0x1100
	s_addc_u32 s5, s89, 0
	v_writelane_b32 v252, s4, 60
	v_mov_b32_e32 v1, 0
	v_mov_b32_e32 v175, 1
	v_writelane_b32 v252, s5, 61
	s_add_u32 s4, s88, 0x1200
	s_addc_u32 s5, s89, 0
	v_writelane_b32 v252, s4, 62
	v_mov_b32_e32 v176, 0xbfba00e3
	v_mov_b32_e32 v177, 0x358637bd
	v_writelane_b32 v252, s5, 63
	s_add_u32 s4, s88, 0x1300
	s_addc_u32 s5, s89, 0
	v_writelane_b32 v253, s4, 0
	v_readlane_b32 s8, v252, 4
	v_readlane_b32 s12, v252, 8
	v_writelane_b32 v253, s5, 1
	s_add_u32 s4, s88, 0x3400
	s_addc_u32 s5, s89, 0
	v_writelane_b32 v253, s4, 2
	v_readlane_b32 s13, v252, 9
	v_mov_b32_e32 v158, 0x12200
	v_writelane_b32 v253, s5, 3
	s_add_u32 s4, s88, 0x3500
	s_addc_u32 s5, s89, 0
	v_writelane_b32 v253, s4, 4
	s_ashr_i32 s3, s6, 3
	v_mov_b32_e32 v160, 0x12204
	v_writelane_b32 v253, s5, 5
	v_writelane_b32 v253, s2, 6
	s_mul_i32 s2, s41, s2
	s_add_i32 s4, s2, s3
	s_add_u32 s2, s88, 0x8228000
	v_writelane_b32 v253, s2, 7
	s_addc_u32 s2, s89, 0
	v_writelane_b32 v253, s2, 8
	s_add_u32 s2, s88, 0xa4a8000
	s_addc_u32 s3, s89, 0
	v_writelane_b32 v253, s2, 9
	v_mbcnt_hi_u32_b32 v178, -1, v16
	v_mov_b32_e32 v179, 0x12000
	v_writelane_b32 v253, s3, 10
	s_add_u32 s2, s88, 0x84a8000
	s_addc_u32 s3, s89, 0
	v_writelane_b32 v253, s2, 11
	v_mov_b32_e32 v180, 0x100
	v_mov_b32_e32 v173, 0x1fcf
	v_writelane_b32 v253, s3, 12
	s_add_u32 s2, s88, 0xc5a8000
	v_writelane_b32 v253, s2, 13
	s_addc_u32 s2, s89, 0
	v_writelane_b32 v253, s2, 14
	s_add_u32 s2, s88, 0x9c8000
	s_addc_u32 s3, s89, 0
	s_add_u32 s66, s88, 0xa5a8000
	v_writelane_b32 v253, s2, 15
	s_addc_u32 s64, s89, 0
	v_mov_b32_e32 v174, 0xdf
	v_writelane_b32 v253, s3, 16
	s_add_u32 s2, s88, 0xe7a8000
	s_addc_u32 s3, s89, 0
	v_writelane_b32 v253, s2, 17
	v_mov_b32_e32 v181, 0x1fdf
	v_mov_b32_e32 v186, 0x1fef
	v_writelane_b32 v253, s3, 18
	s_add_u32 s2, s88, 0xc6a8000
	s_addc_u32 s3, s89, 0
	v_writelane_b32 v253, s2, 19
	v_mov_b32_e32 v187, 0xff
	v_mov_b32_e32 v188, 0x1fff
	v_writelane_b32 v253, s3, 20
	s_add_u32 s2, s88, 0x3228e40
	s_addc_u32 s3, s89, 0
	v_writelane_b32 v253, s2, 21
	v_not_b32_e32 v189, 63
	v_mov_b32_e32 v190, 0x4000
	v_writelane_b32 v253, s3, 22
	s_add_u32 s2, s88, 0x9a8000
	s_addc_u32 s3, s89, 0
	v_writelane_b32 v253, s2, 23
	s_movk_i32 s76, 0x2000
	s_movk_i32 s77, 0x4000
	v_writelane_b32 v253, s3, 24
	s_add_u32 s2, s88, 0xb628000
	s_addc_u32 s3, s89, 0
	v_writelane_b32 v253, s2, 25
	s_movk_i32 s83, 0x7fff
	s_movk_i32 s78, 0x1400
	v_writelane_b32 v253, s3, 26
	s_add_u32 s2, s88, 0x9d68000
	s_addc_u32 s3, s89, 0
	v_writelane_b32 v253, s2, 27
	s_movk_i32 s79, 0x110
	s_mov_b32 s81, 0x3228000
	v_writelane_b32 v253, s3, 28
	s_add_u32 s2, s88, 0x3228c40
	s_addc_u32 s3, s89, 0
	v_writelane_b32 v253, s2, 29
	s_mov_b32 s33, 0x41800000
	s_mov_b32 s85, 0
	v_writelane_b32 v253, s3, 30
	s_add_u32 s2, s88, 0xf38400
	s_addc_u32 s3, s89, 0
	s_lshl_b32 s65, s40, 8
	v_writelane_b32 v253, s2, 31
	s_cmpk_lt_i32 s6, 0x200
	s_mov_b64 s[86:87], 0
	v_writelane_b32 v253, s3, 32
	s_cselect_b64 s[2:3], -1, 0
	v_writelane_b32 v253, s2, 33
	s_cmpk_lt_u32 s6, 0x200
	s_mov_b64 s[46:47], 0xc080
	v_writelane_b32 v253, s3, 34
	s_cselect_b64 s[2:3], -1, 0
	v_writelane_b32 v253, s2, 35
	s_mov_b64 s[36:37], 0xc180
	s_mov_b32 s96, 0xbf317218
	v_writelane_b32 v253, s3, 36
	s_lshl_b32 s2, s6, 6
	s_and_b32 s74, s2, 0x1c0
	s_add_u32 s2, s88, 0x9ca8000
	v_writelane_b32 v253, s2, 37
	s_addc_u32 s2, s89, 0
	s_add_u32 s68, s88, 0x28000
	s_addc_u32 s69, s89, 0
	v_writelane_b32 v253, s2, 38
	s_add_u32 s2, s88, 0x4000
	s_addc_u32 s3, s89, 0
	v_writelane_b32 v253, s2, 39
	s_cmp_gt_i32 s6, 31
	s_mov_b64 s[38:39], 0x4ffff
	v_writelane_b32 v253, s3, 40
	s_cselect_b64 s[2:3], -1, 0
	s_lshl_b32 s75, s24, 1
	v_writelane_b32 v253, s2, 41
	s_cmp_eq_u32 s1, 0
	s_mov_b32 s82, 0x3fd744fd
	v_writelane_b32 v253, s3, 42
	s_cselect_b32 s2, s4, s6
	s_cmpk_lt_i32 s2, 0x200
	s_cselect_b64 s[0:1], -1, 0
	v_writelane_b32 v253, s0, 43
	s_mov_b64 s[42:43], 0xc0
	s_mov_b64 s[50:51], 0x30000
	v_writelane_b32 v253, s1, 44
	s_lshl_b64 s[0:1], s[6:7], 10
	s_add_u32 s0, s12, s0
	v_writelane_b32 v253, s0, 45
	s_addc_u32 s0, s13, s1
	s_lshl_b64 s[4:5], s[6:7], 9
	v_writelane_b32 v253, s0, 46
	s_add_u32 s0, s88, s4
	v_writelane_b32 v253, s4, 47
	s_addc_u32 s1, s89, s5
	s_add_u32 s0, s0, 0x9c8000
	v_writelane_b32 v253, s5, 48
	s_addc_u32 s1, s1, 0
	v_writelane_b32 v253, s0, 49
	s_mov_b64 s[54:55], 0x20080
	v_readlane_b32 s9, v252, 5
	v_writelane_b32 v253, s1, 50
	s_lshl_b64 s[0:1], s[6:7], 15
	v_writelane_b32 v253, s0, 51
	v_readlane_b32 s10, v252, 6
	v_readlane_b32 s11, v252, 7
	v_writelane_b32 v253, s1, 52
	s_add_u32 s0, s88, 0x228080
	s_addc_u32 s1, s89, 0
	v_writelane_b32 v253, s0, 53
	v_readlane_b32 s14, v252, 10
	v_readlane_b32 s15, v252, 11
	v_writelane_b32 v253, s1, 54
	s_add_u32 s0, s88, 0x1128080
	s_addc_u32 s1, s89, 0
	v_writelane_b32 v253, s0, 55
	s_waitcnt lgkmcnt(0)
	s_barrier
;   DI bf16* WL() const { return (bf16*)(p.ws + WS_WL); }
;   DI bf16* HY() const { return (bf16*)(p.ws + WS_HY); }
;   DI bf16* P() const { return (bf16*)(p.ws + WS_P); }
; __global__ void __launch_bounds__(NT, 2) fwd_kernel(Params p) {
;     ...
;   for (int l = 0; l < 4; ++l) {
;     const int li = l >> 1;
;     const int rows_in = (l <= 2) ? MT : MLAT, rows_out = (l <= 1) ? MT : MLAT;
;     phase_wconv_rest(c, l);
;     if ((l & 1) == 0) {
;       mfma_gemm_big(RowPtr{c.HY(), D}, RowPtr{c.WL() + WL_IN / 2, D}, rows_in, 2560, D, EpiStoreP4{c.P()}, lds);
	v_writelane_b32 v253, s1, 56
	s_add_u32 s0, s88, 0x3228c00
	s_addc_u32 s1, s89, 0
	v_writelane_b32 v253, s0, 57
	s_lshl_b32 s72, s40, 5
	s_lshl_b32 s73, s40, 7
	v_writelane_b32 v253, s1, 58
	s_lshl_b32 s0, s2, 5
	v_writelane_b32 v253, s0, 59
	v_writelane_b32 v253, s2, 60
	s_lshl_b32 s0, s2, 7
	v_writelane_b32 v253, s0, 61
	s_add_u32 s0, s88, 0x3228c60
	s_addc_u32 s1, s89, 0
	v_writelane_b32 v253, s0, 62
	s_nop 1
	v_writelane_b32 v253, s1, 63
	s_add_u32 s0, s88, 0x728080
	s_addc_u32 s1, s89, 0
	v_writelane_b32 v254, s0, 0
	s_nop 1
	v_writelane_b32 v254, s1, 1
	s_add_u32 s0, s88, 0x728100
	s_addc_u32 s1, s89, 0
	v_writelane_b32 v254, s0, 2
	s_nop 1
	v_writelane_b32 v254, s1, 3
	s_lshl_b32 s0, s6, 7
	v_writelane_b32 v254, s0, 4
	s_add_u32 s0, s88, 0x1128100
	s_addc_u32 s1, s89, 0
	v_writelane_b32 v254, s0, 5
	s_lshl_b32 s67, s40, 4
	s_lshl_b32 s70, s40, 14
	v_writelane_b32 v254, s1, 6
	s_lshl_b32 s0, s6, 4
	v_writelane_b32 v254, s0, 7
	s_lshl_b32 s0, s40, 13
	v_writelane_b32 v254, s0, 8
	v_writelane_b32 v254, s90, 9
	s_nop 1
	v_writelane_b32 v254, s91, 10
	v_writelane_b32 v254, s92, 11
	s_nop 1
	v_writelane_b32 v254, s93, 12
	v_writelane_b32 v254, s94, 13
	s_nop 1
	v_writelane_b32 v254, s95, 14
	v_writelane_b32 v254, s52, 15
	s_nop 1
	v_writelane_b32 v254, s53, 16
	v_writelane_b32 v254, s24, 17
	v_writelane_b32 v254, s44, 18
	s_nop 1
	v_writelane_b32 v254, s45, 19
	v_writelane_b32 v254, s56, 20
	s_nop 1
	v_writelane_b32 v254, s57, 21
	v_writelane_b32 v254, s48, 22
	s_nop 1
	v_writelane_b32 v254, s49, 23
	v_writelane_b32 v254, s41, 24
	v_writelane_b32 v254, s34, 25
	s_nop 1
	v_writelane_b32 v254, s35, 26
	v_writelane_b32 v254, s58, 27
	s_nop 1
	v_writelane_b32 v254, s59, 28
	v_writelane_b32 v254, s40, 29
	s_nop 1
	v_writelane_b32 v254, s41, 30
	v_writelane_b32 v254, s60, 31
	s_nop 1
	v_writelane_b32 v254, s61, 32
	v_writelane_b32 v254, s62, 33
	s_nop 1
	v_writelane_b32 v254, s63, 34
	v_writelane_b32 v254, s66, 35
	v_writelane_b32 v254, s64, 36
	v_writelane_b32 v254, s65, 37
	v_writelane_b32 v254, s74, 38
	v_writelane_b32 v254, s68, 39
	v_writelane_b32 v254, s69, 40
	v_writelane_b32 v254, s75, 41
	v_writelane_b32 v254, s71, 42
	v_writelane_b32 v254, s72, 43
	v_writelane_b32 v254, s73, 44
	v_writelane_b32 v254, s67, 45
	v_writelane_b32 v254, s70, 46
	v_writelane_b32 v254, s88, 47
	s_nop 1
	v_writelane_b32 v254, s89, 48
	s_branch .LBB0_198

; DI unsigned xb_ld(unsigned* p) { return __hip_atomic_load(p, __ATOMIC_RELAXED, __HIP_MEMORY_SCOPE_AGENT); }
; DI unsigned xb_add(unsigned* p, unsigned v) { return __hip_atomic_fetch_add(p, v, __ATOMIC_RELAXED, __HIP_MEMORY_SCOPE_AGENT); }
; #define XB_SPIN(cond, bar) do { unsigned _sp = 0; while (cond) { __builtin_amdgcn_s_sleep(1); \
;     if ((++_sp & 255u) == 0u) { if (xb_ld(&(bar)[XB_TMO])) break; if (_sp > XB_SPIN_CAP) { atomicAdd(&(bar)[XB_TMO], 1u); break; } } } } while (0)
; DI void xcd_barrier(const XcdBarrier& b) {
;   asm volatile("s_waitcnt vmcnt(0)" ::: "memory");
;   __syncthreads();
;   if (threadIdx.x == 0) {
;     unsigned* bar = b.bar;
;     __builtin_amdgcn_s_waitcnt(0);
;     unsigned nloc = b.st[0], nx = b.st[1];
;     if (nloc == 0u) { xcd_barrier_complete(bar, b.x, nloc, nx); b.st[0] = nloc; b.st[1] = nx; }
;     const unsigned old = xb_add(&bar[XB_XSUB(b.x)], 1u);
;     const unsigned gen = old / nloc;
;     if (old + 1u == (gen + 1u) * nloc) {
;       __builtin_amdgcn_fence(__ATOMIC_RELEASE, "agent");
;       asm volatile("s_waitcnt vmcnt(0)" ::: "memory");
;       const unsigned og = xb_add(&bar[XB_TOP], 1u);
;       const unsigned tg = og / nx;
;       if (og + 1u == (tg + 1u) * nx) xb_add(&bar[XB_TOPGEN], 1u);
;       else XB_SPIN(xb_ld(&bar[XB_TOPGEN]) == tg, bar);
;       __builtin_amdgcn_fence(__ATOMIC_ACQUIRE, "agent");
;       xb_add(&bar[XB_XGEN(b.x)], 1u);
;       asm volatile("s_waitcnt vmcnt(0)" ::: "memory");
;     } else {
;       XB_SPIN(xb_ld(&bar[XB_XGEN(b.x)]) == gen, bar);
;       __builtin_amdgcn_fence(__ATOMIC_ACQUIRE, "agent");
;       asm volatile("s_waitcnt vmcnt(0)" ::: "memory");
;     }
;   }
;   __syncthreads();
; }
.LBB0_256:
	s_getreg_b32 s4, hwreg(HW_REG_XCC_ID, 0, 4)
	s_waitcnt vmcnt(0)
	s_barrier
	s_mov_b64 s[0:1], exec
	v_readlane_b32 s6, v252, 14
	v_readlane_b32 s7, v252, 15
	s_and_b64 s[6:7], s[0:1], s[6:7]
	s_mov_b64 exec, s[6:7]
	s_cbranch_execz .LBB0_308
	s_getreg_b32 s4, hwreg(HW_REG_XCC_ID, 0, 4)
	v_mov_b32_e32 v0, 0x12200
	ds_read_b64 v[2:3], v0
	s_lshl_b32 s4, s4, 8
	s_and_b32 s4, s4, 0xf00
	s_add_u32 s2, s88, s4
	s_addc_u32 s3, s89, 0
	v_mov_b32_e32 v5, 1
	v_mov_b32_e32 v6, 0x1000
	global_atomic_add v5, v6, v5, s[2:3] offset:1024 sc0
	v_readlane_b32 s5, v255, 1
	s_add_i32 s5, s5, 1
	s_nop 0
	v_writelane_b32 v255, s5, 1
	v_mov_b32_e32 v6, 0x3400
	s_waitcnt lgkmcnt(0)
	v_readfirstlane_b32 s6, v2
	v_readfirstlane_b32 s7, v3
	s_mul_i32 s8, s5, s6
	s_mul_i32 s9, s5, s7
	s_mov_b32 s11, 0
	s_waitcnt vmcnt(0)
	v_readfirstlane_b32 s10, v5
	s_add_i32 s10, s10, 1
	s_cmp_lg_u32 s10, s8
	s_cbranch_scc1 .Lsy1_inv
	buffer_wbl2 sc1
	v_mov_b32_e32 v5, 1
	s_waitcnt vmcnt(0)
	global_atomic_add v6, v5, s[88:89]

;   DI float* TAB() const { return (float*)(p.ws + WS_TAB); }
; DI int vblock() { const int G = gridDim.x, b = blockIdx.x; return ((G & 7) == 0) ? (b & 7) * (G >> 3) + (b >> 3) : b; }
; DI unsigned xb_ld(unsigned* p) { return __hip_atomic_load(p, __ATOMIC_RELAXED, __HIP_MEMORY_SCOPE_AGENT); }
; DI unsigned xb_add(unsigned* p, unsigned v) { return __hip_atomic_fetch_add(p, v, __ATOMIC_RELAXED, __HIP_MEMORY_SCOPE_AGENT); }
; #define XB_SPIN(cond, bar) do { unsigned _sp = 0; while (cond) { __builtin_amdgcn_s_sleep(1); \
;     if ((++_sp & 255u) == 0u) { if (xb_ld(&(bar)[XB_TMO])) break; if (_sp > XB_SPIN_CAP) { atomicAdd(&(bar)[XB_TMO], 1u); break; } } } } while (0)
; DI void phase_odd_a(const Ctx& c, int l, bf16* lds) {
;   const int ntile_sgu = (l == 1) ? 528 : 512;
;   const int n_lat = 4 * 128 * 2, n_ctx = (l == 1) ? 4 * 4 * 2 : 0;
;   const bf16* cs128 = (const bf16*)((const unsigned char*)c.TAB() + TBB_CS128);
;   const int total = ntile_sgu + n_lat + n_ctx;
;   for (int it = vblock(); it < total; it += gridDim.x) {
; DI void xcd_barrier(const XcdBarrier& b) {
;   asm volatile("s_waitcnt vmcnt(0)" ::: "memory");
;   __syncthreads();
;   if (threadIdx.x == 0) {
;     unsigned* bar = b.bar;
;     __builtin_amdgcn_s_waitcnt(0);
;     unsigned nloc = b.st[0], nx = b.st[1];
;     if (nloc == 0u) { xcd_barrier_complete(bar, b.x, nloc, nx); b.st[0] = nloc; b.st[1] = nx; }
;     const unsigned old = xb_add(&bar[XB_XSUB(b.x)], 1u);
;     const unsigned gen = old / nloc;
;     if (old + 1u == (gen + 1u) * nloc) {
;       __builtin_amdgcn_fence(__ATOMIC_RELEASE, "agent");
;       asm volatile("s_waitcnt vmcnt(0)" ::: "memory");
;       const unsigned og = xb_add(&bar[XB_TOP], 1u);
;       const unsigned tg = og / nx;
;       if (og + 1u == (tg + 1u) * nx) xb_add(&bar[XB_TOPGEN], 1u);
;       else XB_SPIN(xb_ld(&bar[XB_TOPGEN]) == tg, bar);
;       __builtin_amdgcn_fence(__ATOMIC_ACQUIRE, "agent");
;       xb_add(&bar[XB_XGEN(b.x)], 1u);
;       asm volatile("s_waitcnt vmcnt(0)" ::: "memory");
;     } else {
;       XB_SPIN(xb_ld(&bar[XB_XGEN(b.x)]) == gen, bar);
;       __builtin_amdgcn_fence(__ATOMIC_ACQUIRE, "agent");
;       asm volatile("s_waitcnt vmcnt(0)" ::: "memory");
;     }
;   }
;   __syncthreads();
; }
.Lsy1_done:
.LBB0_308:
	s_or_b64 exec, exec, s[0:1]
	s_cmp_eq_u32 s86, 1
	s_cselect_b64 s[0:1], -1, 0
	s_and_b64 s[4:5], s[0:1], exec
	s_movk_i32 s4, 0x210
	s_cselect_b32 s8, s4, 0x200
	s_cselect_b32 s4, 32, 0
	s_or_b32 s9, s8, 0x400
	s_or_b32 s10, s9, s4
	v_readlane_b32 s2, v253, 60
	s_cmp_ge_i32 s2, s10
	v_readlane_b32 s11, v253, 61
	v_readlane_b32 s12, v253, 59
	s_mov_b32 s4, s2
	s_waitcnt lgkmcnt(0)
	s_barrier
	s_cbranch_scc0 .LBB0_313
.LBB0_309:
	s_getreg_b32 s6, hwreg(HW_REG_XCC_ID, 0, 4)
	s_waitcnt vmcnt(0)
	s_barrier
	s_mov_b64 s[4:5], exec
	v_readlane_b32 s8, v252, 14
	v_readlane_b32 s9, v252, 15
	s_and_b64 s[8:9], s[4:5], s[8:9]
	s_mov_b64 exec, s[8:9]
	s_cbranch_execz .LBB0_372
	s_getreg_b32 s6, hwreg(HW_REG_XCC_ID, 0, 4)
	v_mov_b32_e32 v0, 0x12200
	ds_read_b64 v[2:3], v0
	s_lshl_b32 s6, s6, 8
	s_and_b32 s6, s6, 0xf00
	s_add_u32 s2, s88, s6
	s_addc_u32 s3, s89, 0
	v_mov_b32_e32 v5, 1
	v_mov_b32_e32 v6, 0x1000
	global_atomic_add v5, v6, v5, s[2:3] offset:1024 sc0
	v_readlane_b32 s7, v255, 1
	s_add_i32 s7, s7, 1
	s_nop 0
	v_writelane_b32 v255, s7, 1
	v_mov_b32_e32 v6, 0x3400
	s_waitcnt lgkmcnt(0)
	v_readfirstlane_b32 s10, v2
	v_readfirstlane_b32 s12, v3
	s_mul_i32 s15, s7, s10
	s_mul_i32 s20, s7, s12
	s_mov_b32 s24, 0
	s_waitcnt vmcnt(0)
	v_readfirstlane_b32 s22, v5
	s_add_i32 s22, s22, 1
	s_cmp_lg_u32 s22, s15
	s_cbranch_scc1 .Lsy2_inv
	buffer_wbl2 sc1
	v_mov_b32_e32 v5, 1
	s_waitcnt vmcnt(0)
	global_atomic_add v6, v5, s[88:89]

; DI int vblock() { const int G = gridDim.x, b = blockIdx.x; return ((G & 7) == 0) ? (b & 7) * (G >> 3) + (b >> 3) : b; }
; DI unsigned xb_ld(unsigned* p) { return __hip_atomic_load(p, __ATOMIC_RELAXED, __HIP_MEMORY_SCOPE_AGENT); }
; DI unsigned xb_add(unsigned* p, unsigned v) { return __hip_atomic_fetch_add(p, v, __ATOMIC_RELAXED, __HIP_MEMORY_SCOPE_AGENT); }
; #define XB_SPIN(cond, bar) do { unsigned _sp = 0; while (cond) { __builtin_amdgcn_s_sleep(1); \
;     if ((++_sp & 255u) == 0u) { if (xb_ld(&(bar)[XB_TMO])) break; if (_sp > XB_SPIN_CAP) { atomicAdd(&(bar)[XB_TMO], 1u); break; } } } } while (0)
; DI void phase_odd_a(const Ctx& c, int l, bf16* lds) {
;     ...
;   for (int it = vblock(); it < total; it += gridDim.x) {
;     if (it < ntile_sgu) vgt_tile(c, it, lds);
; DI void xcd_barrier(const XcdBarrier& b) {
;   asm volatile("s_waitcnt vmcnt(0)" ::: "memory");
;   __syncthreads();
;   if (threadIdx.x == 0) {
;     unsigned* bar = b.bar;
;     __builtin_amdgcn_s_waitcnt(0);
;     unsigned nloc = b.st[0], nx = b.st[1];
;     if (nloc == 0u) { xcd_barrier_complete(bar, b.x, nloc, nx); b.st[0] = nloc; b.st[1] = nx; }
;     const unsigned old = xb_add(&bar[XB_XSUB(b.x)], 1u);
;     const unsigned gen = old / nloc;
;     if (old + 1u == (gen + 1u) * nloc) {
;       __builtin_amdgcn_fence(__ATOMIC_RELEASE, "agent");
;       asm volatile("s_waitcnt vmcnt(0)" ::: "memory");
;       const unsigned og = xb_add(&bar[XB_TOP], 1u);
;       const unsigned tg = og / nx;
;       if (og + 1u == (tg + 1u) * nx) xb_add(&bar[XB_TOPGEN], 1u);
;       else XB_SPIN(xb_ld(&bar[XB_TOPGEN]) == tg, bar);
;       __builtin_amdgcn_fence(__ATOMIC_ACQUIRE, "agent");
;       xb_add(&bar[XB_XGEN(b.x)], 1u);
;       asm volatile("s_waitcnt vmcnt(0)" ::: "memory");
;     } else {
;       XB_SPIN(xb_ld(&bar[XB_XGEN(b.x)]) == gen, bar);
;       __builtin_amdgcn_fence(__ATOMIC_ACQUIRE, "agent");
;       asm volatile("s_waitcnt vmcnt(0)" ::: "memory");
;     }
;   }
;   __syncthreads();
; }
.Lsy2_poll:
	global_load_dword v5, v6, s[88:89] sc1
	s_waitcnt vmcnt(0)
	v_readfirstlane_b32 s22, v5
	s_sub_i32 s22, s22, s20
	s_cmp_ge_i32 s22, 0
	s_cbranch_scc1 .Lsy2_done
	s_add_i32 s24, s24, 1
	s_sleep 1
	s_cmp_lt_u32 s24, 0x400000
	s_cbranch_scc1 .Lsy2_poll
.Lsy2_done:
	s_branch .LBB0_372
.LBB0_312:
	s_add_i32 s4, s4, s40
	s_add_i32 s12, s12, s72
	s_add_i32 s11, s11, s73
	s_cmp_lt_i32 s4, s10
	s_cbranch_scc0 .LBB0_309

; DI bf16 f2bf(float f) { unsigned u = __float_as_uint(f); u += 0x7fffu + ((u >> 16) & 1u); return (bf16)(u >> 16); }
; DI float gelu(float x) { return 0.5f * x * (1.f + erf_as(x * 0.70710678118654752f)); }
;   DI bf16* P() const { return (bf16*)(p.ws + WS_P); }
; DI void vgt_tile(const Ctx& c, int ti, bf16* lds) {
;     ...
;   for (int rr = 0; rr < 32; ++rr) {
;     const int t = wave * 32 + rr;
;     const unsigned u = *(const unsigned*)(c.P() + (size_t)(row0 + t) * LDP + C_V + g * 128 + 2 * lane);
;     const float a = gelu(__uint_as_float(u << 16)), b = gelu(__uint_as_float(u & 0xffff0000u));
;     const float mean = wave_sum(a + b) * (1.f / 128.f);
;     const float da = a - mean, db = b - mean;
;     const float rstd = rsqrtf(wave_sum(da * da + db * db) * (1.f / 128.f) + LN_EPS);
;     lds[(2 * lane) * LDT + t] = f2bf(da * rstd);
;     lds[(2 * lane + 1) * LDT + t] = f2bf(db * rstd);
;   }
.LBB0_321:
	s_mov_b64 s[6:7], 0x1400
	global_load_dword v20, v[4:5], off
	v_lshl_add_u64 v[4:5], v[4:5], 0, s[6:7]
	global_load_dword v21, v[4:5], off
	v_lshl_add_u64 v[4:5], v[4:5], 0, s[6:7]
	global_load_dword v22, v[4:5], off
	v_lshl_add_u64 v[4:5], v[4:5], 0, s[6:7]
	global_load_dword v23, v[4:5], off
	v_lshl_add_u64 v[4:5], v[4:5], 0, s[6:7]
	global_load_dword v24, v[4:5], off
	v_lshl_add_u64 v[4:5], v[4:5], 0, s[6:7]
	global_load_dword v25, v[4:5], off
	v_lshl_add_u64 v[4:5], v[4:5], 0, s[6:7]
	global_load_dword v26, v[4:5], off
	v_lshl_add_u64 v[4:5], v[4:5], 0, s[6:7]
	global_load_dword v27, v[4:5], off
	v_lshl_add_u64 v[4:5], v[4:5], 0, s[6:7]
	global_load_dword v28, v[4:5], off
	v_lshl_add_u64 v[4:5], v[4:5], 0, s[6:7]
	global_load_dword v29, v[4:5], off
	v_lshl_add_u64 v[4:5], v[4:5], 0, s[6:7]
	global_load_dword v30, v[4:5], off
	v_lshl_add_u64 v[4:5], v[4:5], 0, s[6:7]
	global_load_dword v31, v[4:5], off
	v_lshl_add_u64 v[4:5], v[4:5], 0, s[6:7]
	global_load_dword v32, v[4:5], off
	v_lshl_add_u64 v[4:5], v[4:5], 0, s[6:7]
	global_load_dword v33, v[4:5], off
	v_lshl_add_u64 v[4:5], v[4:5], 0, s[6:7]
	global_load_dword v34, v[4:5], off
	v_lshl_add_u64 v[4:5], v[4:5], 0, s[6:7]
	global_load_dword v35, v[4:5], off
	v_lshl_add_u64 v[4:5], v[4:5], 0, s[6:7]
	global_load_dword v36, v[4:5], off
	v_lshl_add_u64 v[4:5], v[4:5], 0, s[6:7]
	global_load_dword v37, v[4:5], off
	v_lshl_add_u64 v[4:5], v[4:5], 0, s[6:7]
	global_load_dword v38, v[4:5], off
	v_lshl_add_u64 v[4:5], v[4:5], 0, s[6:7]
	global_load_dword v39, v[4:5], off
	v_lshl_add_u64 v[4:5], v[4:5], 0, s[6:7]
	global_load_dword v40, v[4:5], off
	v_lshl_add_u64 v[4:5], v[4:5], 0, s[6:7]
	global_load_dword v41, v[4:5], off
	v_lshl_add_u64 v[4:5], v[4:5], 0, s[6:7]
	global_load_dword v42, v[4:5], off
	v_lshl_add_u64 v[4:5], v[4:5], 0, s[6:7]
	global_load_dword v43, v[4:5], off
	v_lshl_add_u64 v[4:5], v[4:5], 0, s[6:7]
	global_load_dword v44, v[4:5], off
	v_lshl_add_u64 v[4:5], v[4:5], 0, s[6:7]
	global_load_dword v45, v[4:5], off
	v_lshl_add_u64 v[4:5], v[4:5], 0, s[6:7]
	global_load_dword v46, v[4:5], off
	v_lshl_add_u64 v[4:5], v[4:5], 0, s[6:7]
	global_load_dword v47, v[4:5], off
	v_lshl_add_u64 v[4:5], v[4:5], 0, s[6:7]
	global_load_dword v48, v[4:5], off
	v_lshl_add_u64 v[4:5], v[4:5], 0, s[6:7]
	global_load_dword v49, v[4:5], off
	v_lshl_add_u64 v[4:5], v[4:5], 0, s[6:7]
	global_load_dword v50, v[4:5], off
	v_lshl_add_u64 v[4:5], v[4:5], 0, s[6:7]
	global_load_dword v51, v[4:5], off
	v_lshl_add_u64 v[4:5], v[4:5], 0, s[6:7]
	s_waitcnt vmcnt(31)
	v_lshlrev_b32_e32 v8, 16, v20
	v_mul_f32_e32 v9, 0.5, v8
	v_mul_f32_e32 v8, 0x3f3504f3, v8
	v_fma_f32 v10, |v8|, s2, 1.0
	v_rcp_f32_e32 v10, v10
	v_and_b32_e32 v7, 0xffff0000, v20
	v_fmamk_f32 v11, v10, 0x3f87dc22, v176
	v_fmaak_f32 v11, v10, v11, 0x3fb5f0e3
	v_fmaak_f32 v11, v10, v11, 0xbe91a98e
	v_fmaak_f32 v11, v10, v11, 0x3e827906
	v_mul_f32_e32 v10, v10, v11
	v_mul_f32_e64 v11, |v8|, s3
	v_mul_f32_e64 v11, |v8|, v11
	v_exp_f32_e32 v11, v11
	s_nop 0
	v_fma_f32 v10, -v11, v10, 1.0
	v_bfi_b32 v8, s13, v10, v8
	v_mul_f32_e32 v10, 0.5, v7
	v_mul_f32_e32 v7, 0x3f3504f3, v7
	v_fma_f32 v11, |v7|, s2, 1.0
	v_rcp_f32_e32 v11, v11
	v_add_f32_e32 v8, 1.0, v8
	v_fmamk_f32 v12, v11, 0x3f87dc22, v176
	v_fmaak_f32 v12, v11, v12, 0x3fb5f0e3
	v_fmaak_f32 v12, v11, v12, 0xbe91a98e
	v_fmaak_f32 v12, v11, v12, 0x3e827906
	v_mul_f32_e32 v11, v11, v12
	v_mul_f32_e64 v12, |v7|, s3
	v_mul_f32_e64 v12, |v7|, v12
	v_exp_f32_e32 v12, v12
	s_nop 0
	v_fma_f32 v11, -v12, v11, 1.0
	v_bfi_b32 v7, s13, v11, v7
	v_add_f32_e32 v7, 1.0, v7
	v_mul_f32_e32 v11, v10, v7
	v_fmac_f32_e32 v11, v9, v8
	s_nop 1
	v_add_f32_dpp v11, v11, v11 row_ror:8 row_mask:0xf bank_mask:0xf bound_ctrl:1
	s_nop 1
	v_add_f32_dpp v11, v11, v11 row_ror:4 row_mask:0xf bank_mask:0xf bound_ctrl:1
	s_nop 1
	v_add_f32_dpp v11, v11, v11 row_ror:2 row_mask:0xf bank_mask:0xf bound_ctrl:1
	s_nop 1
	v_add_f32_dpp v11, v11, v11 row_ror:1 row_mask:0xf bank_mask:0xf bound_ctrl:1
	ds_bpermute_b32 v12, v3, v11
	s_waitcnt lgkmcnt(0)
	v_add_f32_e32 v11, v11, v12
	v_mov_b32_e32 v12, v11
	s_nop 1
	v_permlane32_swap_b32_e32 v11, v12
	v_add_f32_e32 v11, v11, v12
	v_mul_f32_e32 v11, 0x3c000000, v11
	v_fma_f32 v7, v10, v7, -v11
	v_fma_f32 v8, v9, v8, -v11
	v_mul_f32_e32 v9, v7, v7
	v_fmac_f32_e32 v9, v8, v8
	s_nop 1
	v_add_f32_dpp v9, v9, v9 row_ror:8 row_mask:0xf bank_mask:0xf bound_ctrl:1
	s_nop 1
	v_add_f32_dpp v9, v9, v9 row_ror:4 row_mask:0xf bank_mask:0xf bound_ctrl:1
	s_nop 1
	v_add_f32_dpp v9, v9, v9 row_ror:2 row_mask:0xf bank_mask:0xf bound_ctrl:1
	s_nop 1
	v_add_f32_dpp v9, v9, v9 row_ror:1 row_mask:0xf bank_mask:0xf bound_ctrl:1
	ds_bpermute_b32 v10, v3, v9
	s_waitcnt lgkmcnt(0)
	v_add_f32_e32 v9, v9, v10
	v_mov_b32_e32 v10, v9
	s_nop 1
	v_permlane32_swap_b32_e32 v9, v10
	v_add_f32_e32 v9, v9, v10
	v_fmamk_f32 v9, v9, 0x3c000000, v177
	v_cmp_gt_f32_e32 vcc, s16, v9
	v_mul_f32_e32 v10, 0x4b800000, v9
	s_nop 0
	v_cndmask_b32_e32 v9, v9, v10, vcc
	v_rsq_f32_e32 v9, v9
	s_nop 0
	v_mul_f32_e32 v10, 0x45800000, v9
	v_cndmask_b32_e32 v9, v9, v10, vcc
	v_mul_f32_e32 v8, v8, v9
	v_bfe_u32 v10, v8, 16, 1
	v_add3_u32 v8, v8, v10, s83
	v_add_u32_e32 v10, s5, v6
	v_mul_f32_e32 v7, v7, v9
	ds_write_b16_d16_hi v10, v8
	v_bfe_u32 v8, v7, 16, 1
	s_add_i32 s5, s5, 2
	v_add3_u32 v7, v7, v8, s83
	ds_write_b16_d16_hi v10, v7 offset:272
	s_waitcnt vmcnt(30)
; DI bf16 f2bf(float f) { unsigned u = __float_as_uint(f); u += 0x7fffu + ((u >> 16) & 1u); return (bf16)(u >> 16); }
; DI float gelu(float x) { return 0.5f * x * (1.f + erf_as(x * 0.70710678118654752f)); }
;   DI bf16* P() const { return (bf16*)(p.ws + WS_P); }
; DI void vgt_tile(const Ctx& c, int ti, bf16* lds) {
;     ...
;   for (int rr = 0; rr < 32; ++rr) {
;     const int t = wave * 32 + rr;
;     const unsigned u = *(const unsigned*)(c.P() + (size_t)(row0 + t) * LDP + C_V + g * 128 + 2 * lane);
;     const float a = gelu(__uint_as_float(u << 16)), b = gelu(__uint_as_float(u & 0xffff0000u));
;     const float mean = wave_sum(a + b) * (1.f / 128.f);
;     const float da = a - mean, db = b - mean;
;     const float rstd = rsqrtf(wave_sum(da * da + db * db) * (1.f / 128.f) + LN_EPS);
;     lds[(2 * lane) * LDT + t] = f2bf(da * rstd);
;     lds[(2 * lane + 1) * LDT + t] = f2bf(db * rstd);
;   }
	v_lshlrev_b32_e32 v8, 16, v21
	v_mul_f32_e32 v9, 0.5, v8
	v_mul_f32_e32 v8, 0x3f3504f3, v8
	v_fma_f32 v10, |v8|, s2, 1.0
	v_rcp_f32_e32 v10, v10
	v_and_b32_e32 v7, 0xffff0000, v21
	v_fmamk_f32 v11, v10, 0x3f87dc22, v176
	v_fmaak_f32 v11, v10, v11, 0x3fb5f0e3
	v_fmaak_f32 v11, v10, v11, 0xbe91a98e
	v_fmaak_f32 v11, v10, v11, 0x3e827906
	v_mul_f32_e32 v10, v10, v11
	v_mul_f32_e64 v11, |v8|, s3
	v_mul_f32_e64 v11, |v8|, v11
	v_exp_f32_e32 v11, v11
	s_nop 0
	v_fma_f32 v10, -v11, v10, 1.0
	v_bfi_b32 v8, s13, v10, v8
	v_mul_f32_e32 v10, 0.5, v7
	v_mul_f32_e32 v7, 0x3f3504f3, v7
	v_fma_f32 v11, |v7|, s2, 1.0
	v_rcp_f32_e32 v11, v11
	v_add_f32_e32 v8, 1.0, v8
	v_fmamk_f32 v12, v11, 0x3f87dc22, v176
	v_fmaak_f32 v12, v11, v12, 0x3fb5f0e3
	v_fmaak_f32 v12, v11, v12, 0xbe91a98e
	v_fmaak_f32 v12, v11, v12, 0x3e827906
	v_mul_f32_e32 v11, v11, v12
	v_mul_f32_e64 v12, |v7|, s3
	v_mul_f32_e64 v12, |v7|, v12
	v_exp_f32_e32 v12, v12
	s_nop 0
	v_fma_f32 v11, -v12, v11, 1.0
	v_bfi_b32 v7, s13, v11, v7
	v_add_f32_e32 v7, 1.0, v7
	v_mul_f32_e32 v11, v10, v7
	v_fmac_f32_e32 v11, v9, v8
	s_nop 1
	v_add_f32_dpp v11, v11, v11 row_ror:8 row_mask:0xf bank_mask:0xf bound_ctrl:1
	s_nop 1
	v_add_f32_dpp v11, v11, v11 row_ror:4 row_mask:0xf bank_mask:0xf bound_ctrl:1
	s_nop 1
	v_add_f32_dpp v11, v11, v11 row_ror:2 row_mask:0xf bank_mask:0xf bound_ctrl:1
	s_nop 1
	v_add_f32_dpp v11, v11, v11 row_ror:1 row_mask:0xf bank_mask:0xf bound_ctrl:1
	ds_bpermute_b32 v12, v3, v11
	s_waitcnt lgkmcnt(0)
	v_add_f32_e32 v11, v11, v12
	v_mov_b32_e32 v12, v11
	s_nop 1
	v_permlane32_swap_b32_e32 v11, v12
	v_add_f32_e32 v11, v11, v12
	v_mul_f32_e32 v11, 0x3c000000, v11
	v_fma_f32 v7, v10, v7, -v11
	v_fma_f32 v8, v9, v8, -v11
	v_mul_f32_e32 v9, v7, v7
	v_fmac_f32_e32 v9, v8, v8
	s_nop 1
	v_add_f32_dpp v9, v9, v9 row_ror:8 row_mask:0xf bank_mask:0xf bound_ctrl:1
	s_nop 1
	v_add_f32_dpp v9, v9, v9 row_ror:4 row_mask:0xf bank_mask:0xf bound_ctrl:1
	s_nop 1
	v_add_f32_dpp v9, v9, v9 row_ror:2 row_mask:0xf bank_mask:0xf bound_ctrl:1
	s_nop 1
	v_add_f32_dpp v9, v9, v9 row_ror:1 row_mask:0xf bank_mask:0xf bound_ctrl:1
	ds_bpermute_b32 v10, v3, v9
	s_waitcnt lgkmcnt(0)
	v_add_f32_e32 v9, v9, v10
	v_mov_b32_e32 v10, v9
	s_nop 1
	v_permlane32_swap_b32_e32 v9, v10
	v_add_f32_e32 v9, v9, v10
	v_fmamk_f32 v9, v9, 0x3c000000, v177
	v_cmp_gt_f32_e32 vcc, s16, v9
	v_mul_f32_e32 v10, 0x4b800000, v9
	s_nop 0
	v_cndmask_b32_e32 v9, v9, v10, vcc
	v_rsq_f32_e32 v9, v9
	s_nop 0
	v_mul_f32_e32 v10, 0x45800000, v9
	v_cndmask_b32_e32 v9, v9, v10, vcc
	v_mul_f32_e32 v8, v8, v9
	v_bfe_u32 v10, v8, 16, 1
	v_add3_u32 v8, v8, v10, s83
	v_add_u32_e32 v10, s5, v6
	v_mul_f32_e32 v7, v7, v9
	ds_write_b16_d16_hi v10, v8
	v_bfe_u32 v8, v7, 16, 1
	s_add_i32 s5, s5, 2
	v_add3_u32 v7, v7, v8, s83
	ds_write_b16_d16_hi v10, v7 offset:272
	s_waitcnt vmcnt(29)
	v_lshlrev_b32_e32 v8, 16, v22
	v_mul_f32_e32 v9, 0.5, v8
	v_mul_f32_e32 v8, 0x3f3504f3, v8
	v_fma_f32 v10, |v8|, s2, 1.0
	v_rcp_f32_e32 v10, v10
	v_and_b32_e32 v7, 0xffff0000, v22
	v_fmamk_f32 v11, v10, 0x3f87dc22, v176
	v_fmaak_f32 v11, v10, v11, 0x3fb5f0e3
	v_fmaak_f32 v11, v10, v11, 0xbe91a98e
	v_fmaak_f32 v11, v10, v11, 0x3e827906
	v_mul_f32_e32 v10, v10, v11
	v_mul_f32_e64 v11, |v8|, s3
	v_mul_f32_e64 v11, |v8|, v11
	v_exp_f32_e32 v11, v11
	s_nop 0
	v_fma_f32 v10, -v11, v10, 1.0
	v_bfi_b32 v8, s13, v10, v8
	v_mul_f32_e32 v10, 0.5, v7
	v_mul_f32_e32 v7, 0x3f3504f3, v7
	v_fma_f32 v11, |v7|, s2, 1.0
	v_rcp_f32_e32 v11, v11
	v_add_f32_e32 v8, 1.0, v8
	v_fmamk_f32 v12, v11, 0x3f87dc22, v176
	v_fmaak_f32 v12, v11, v12, 0x3fb5f0e3
	v_fmaak_f32 v12, v11, v12, 0xbe91a98e
	v_fmaak_f32 v12, v11, v12, 0x3e827906
	v_mul_f32_e32 v11, v11, v12
	v_mul_f32_e64 v12, |v7|, s3
	v_mul_f32_e64 v12, |v7|, v12
	v_exp_f32_e32 v12, v12
	s_nop 0
	v_fma_f32 v11, -v12, v11, 1.0
	v_bfi_b32 v7, s13, v11, v7
	v_add_f32_e32 v7, 1.0, v7
	v_mul_f32_e32 v11, v10, v7
	v_fmac_f32_e32 v11, v9, v8
	s_nop 1
	v_add_f32_dpp v11, v11, v11 row_ror:8 row_mask:0xf bank_mask:0xf bound_ctrl:1
	s_nop 1
	v_add_f32_dpp v11, v11, v11 row_ror:4 row_mask:0xf bank_mask:0xf bound_ctrl:1
	s_nop 1
	v_add_f32_dpp v11, v11, v11 row_ror:2 row_mask:0xf bank_mask:0xf bound_ctrl:1
	s_nop 1
	v_add_f32_dpp v11, v11, v11 row_ror:1 row_mask:0xf bank_mask:0xf bound_ctrl:1
	ds_bpermute_b32 v12, v3, v11
	s_waitcnt lgkmcnt(0)
	v_add_f32_e32 v11, v11, v12
	v_mov_b32_e32 v12, v11
	s_nop 1
	v_permlane32_swap_b32_e32 v11, v12
	v_add_f32_e32 v11, v11, v12
	v_mul_f32_e32 v11, 0x3c000000, v11
	v_fma_f32 v7, v10, v7, -v11
	v_fma_f32 v8, v9, v8, -v11
	v_mul_f32_e32 v9, v7, v7
	v_fmac_f32_e32 v9, v8, v8
	s_nop 1
	v_add_f32_dpp v9, v9, v9 row_ror:8 row_mask:0xf bank_mask:0xf bound_ctrl:1
	s_nop 1
	v_add_f32_dpp v9, v9, v9 row_ror:4 row_mask:0xf bank_mask:0xf bound_ctrl:1
	s_nop 1
	v_add_f32_dpp v9, v9, v9 row_ror:2 row_mask:0xf bank_mask:0xf bound_ctrl:1
	s_nop 1
	v_add_f32_dpp v9, v9, v9 row_ror:1 row_mask:0xf bank_mask:0xf bound_ctrl:1
	ds_bpermute_b32 v10, v3, v9
	s_waitcnt lgkmcnt(0)
	v_add_f32_e32 v9, v9, v10
	v_mov_b32_e32 v10, v9
	s_nop 1
	v_permlane32_swap_b32_e32 v9, v10
	v_add_f32_e32 v9, v9, v10
	v_fmamk_f32 v9, v9, 0x3c000000, v177
	v_cmp_gt_f32_e32 vcc, s16, v9
	v_mul_f32_e32 v10, 0x4b800000, v9
	s_nop 0
	v_cndmask_b32_e32 v9, v9, v10, vcc
	v_rsq_f32_e32 v9, v9
	s_nop 0
	v_mul_f32_e32 v10, 0x45800000, v9
	v_cndmask_b32_e32 v9, v9, v10, vcc
	v_mul_f32_e32 v8, v8, v9
	v_bfe_u32 v10, v8, 16, 1
	v_add3_u32 v8, v8, v10, s83
	v_add_u32_e32 v10, s5, v6
	v_mul_f32_e32 v7, v7, v9
	ds_write_b16_d16_hi v10, v8
	v_bfe_u32 v8, v7, 16, 1
	s_add_i32 s5, s5, 2
	v_add3_u32 v7, v7, v8, s83
	ds_write_b16_d16_hi v10, v7 offset:272
	s_waitcnt vmcnt(28)
; DI bf16 f2bf(float f) { unsigned u = __float_as_uint(f); u += 0x7fffu + ((u >> 16) & 1u); return (bf16)(u >> 16); }
; DI float gelu(float x) { return 0.5f * x * (1.f + erf_as(x * 0.70710678118654752f)); }
;   DI bf16* P() const { return (bf16*)(p.ws + WS_P); }
; DI void vgt_tile(const Ctx& c, int ti, bf16* lds) {
;     ...
;   for (int rr = 0; rr < 32; ++rr) {
;     const int t = wave * 32 + rr;
;     const unsigned u = *(const unsigned*)(c.P() + (size_t)(row0 + t) * LDP + C_V + g * 128 + 2 * lane);
;     const float a = gelu(__uint_as_float(u << 16)), b = gelu(__uint_as_float(u & 0xffff0000u));
;     const float mean = wave_sum(a + b) * (1.f / 128.f);
;     const float da = a - mean, db = b - mean;
;     const float rstd = rsqrtf(wave_sum(da * da + db * db) * (1.f / 128.f) + LN_EPS);
;     lds[(2 * lane) * LDT + t] = f2bf(da * rstd);
;     lds[(2 * lane + 1) * LDT + t] = f2bf(db * rstd);
;   }
	v_lshlrev_b32_e32 v8, 16, v23
	v_mul_f32_e32 v9, 0.5, v8
	v_mul_f32_e32 v8, 0x3f3504f3, v8
	v_fma_f32 v10, |v8|, s2, 1.0
	v_rcp_f32_e32 v10, v10
	v_and_b32_e32 v7, 0xffff0000, v23
	v_fmamk_f32 v11, v10, 0x3f87dc22, v176
	v_fmaak_f32 v11, v10, v11, 0x3fb5f0e3
	v_fmaak_f32 v11, v10, v11, 0xbe91a98e
	v_fmaak_f32 v11, v10, v11, 0x3e827906
	v_mul_f32_e32 v10, v10, v11
	v_mul_f32_e64 v11, |v8|, s3
	v_mul_f32_e64 v11, |v8|, v11
	v_exp_f32_e32 v11, v11
	s_nop 0
	v_fma_f32 v10, -v11, v10, 1.0
	v_bfi_b32 v8, s13, v10, v8
	v_mul_f32_e32 v10, 0.5, v7
	v_mul_f32_e32 v7, 0x3f3504f3, v7
	v_fma_f32 v11, |v7|, s2, 1.0
	v_rcp_f32_e32 v11, v11
	v_add_f32_e32 v8, 1.0, v8
	v_fmamk_f32 v12, v11, 0x3f87dc22, v176
	v_fmaak_f32 v12, v11, v12, 0x3fb5f0e3
	v_fmaak_f32 v12, v11, v12, 0xbe91a98e
	v_fmaak_f32 v12, v11, v12, 0x3e827906
	v_mul_f32_e32 v11, v11, v12
	v_mul_f32_e64 v12, |v7|, s3
	v_mul_f32_e64 v12, |v7|, v12
	v_exp_f32_e32 v12, v12
	s_nop 0
	v_fma_f32 v11, -v12, v11, 1.0
	v_bfi_b32 v7, s13, v11, v7
	v_add_f32_e32 v7, 1.0, v7
	v_mul_f32_e32 v11, v10, v7
	v_fmac_f32_e32 v11, v9, v8
	s_nop 1
	v_add_f32_dpp v11, v11, v11 row_ror:8 row_mask:0xf bank_mask:0xf bound_ctrl:1
	s_nop 1
	v_add_f32_dpp v11, v11, v11 row_ror:4 row_mask:0xf bank_mask:0xf bound_ctrl:1
	s_nop 1
	v_add_f32_dpp v11, v11, v11 row_ror:2 row_mask:0xf bank_mask:0xf bound_ctrl:1
	s_nop 1
	v_add_f32_dpp v11, v11, v11 row_ror:1 row_mask:0xf bank_mask:0xf bound_ctrl:1
	ds_bpermute_b32 v12, v3, v11
	s_waitcnt lgkmcnt(0)
	v_add_f32_e32 v11, v11, v12
	v_mov_b32_e32 v12, v11
	s_nop 1
	v_permlane32_swap_b32_e32 v11, v12
	v_add_f32_e32 v11, v11, v12
	v_mul_f32_e32 v11, 0x3c000000, v11
	v_fma_f32 v7, v10, v7, -v11
	v_fma_f32 v8, v9, v8, -v11
	v_mul_f32_e32 v9, v7, v7
	v_fmac_f32_e32 v9, v8, v8
	s_nop 1
	v_add_f32_dpp v9, v9, v9 row_ror:8 row_mask:0xf bank_mask:0xf bound_ctrl:1
	s_nop 1
	v_add_f32_dpp v9, v9, v9 row_ror:4 row_mask:0xf bank_mask:0xf bound_ctrl:1
	s_nop 1
	v_add_f32_dpp v9, v9, v9 row_ror:2 row_mask:0xf bank_mask:0xf bound_ctrl:1
	s_nop 1
	v_add_f32_dpp v9, v9, v9 row_ror:1 row_mask:0xf bank_mask:0xf bound_ctrl:1
	ds_bpermute_b32 v10, v3, v9
	s_waitcnt lgkmcnt(0)
	v_add_f32_e32 v9, v9, v10
	v_mov_b32_e32 v10, v9
	s_nop 1
	v_permlane32_swap_b32_e32 v9, v10
	v_add_f32_e32 v9, v9, v10
	v_fmamk_f32 v9, v9, 0x3c000000, v177
	v_cmp_gt_f32_e32 vcc, s16, v9
	v_mul_f32_e32 v10, 0x4b800000, v9
	s_nop 0
	v_cndmask_b32_e32 v9, v9, v10, vcc
	v_rsq_f32_e32 v9, v9
	s_nop 0
	v_mul_f32_e32 v10, 0x45800000, v9
	v_cndmask_b32_e32 v9, v9, v10, vcc
	v_mul_f32_e32 v8, v8, v9
	v_bfe_u32 v10, v8, 16, 1
	v_add3_u32 v8, v8, v10, s83
	v_add_u32_e32 v10, s5, v6
	v_mul_f32_e32 v7, v7, v9
	ds_write_b16_d16_hi v10, v8
	v_bfe_u32 v8, v7, 16, 1
	s_add_i32 s5, s5, 2
	v_add3_u32 v7, v7, v8, s83
	ds_write_b16_d16_hi v10, v7 offset:272
	s_waitcnt vmcnt(27)
	v_lshlrev_b32_e32 v8, 16, v24
	v_mul_f32_e32 v9, 0.5, v8
	v_mul_f32_e32 v8, 0x3f3504f3, v8
	v_fma_f32 v10, |v8|, s2, 1.0
	v_rcp_f32_e32 v10, v10
	v_and_b32_e32 v7, 0xffff0000, v24
	v_fmamk_f32 v11, v10, 0x3f87dc22, v176
	v_fmaak_f32 v11, v10, v11, 0x3fb5f0e3
	v_fmaak_f32 v11, v10, v11, 0xbe91a98e
	v_fmaak_f32 v11, v10, v11, 0x3e827906
	v_mul_f32_e32 v10, v10, v11
	v_mul_f32_e64 v11, |v8|, s3
	v_mul_f32_e64 v11, |v8|, v11
	v_exp_f32_e32 v11, v11
	s_nop 0
	v_fma_f32 v10, -v11, v10, 1.0
	v_bfi_b32 v8, s13, v10, v8
	v_mul_f32_e32 v10, 0.5, v7
	v_mul_f32_e32 v7, 0x3f3504f3, v7
	v_fma_f32 v11, |v7|, s2, 1.0
	v_rcp_f32_e32 v11, v11
	v_add_f32_e32 v8, 1.0, v8
	v_fmamk_f32 v12, v11, 0x3f87dc22, v176
	v_fmaak_f32 v12, v11, v12, 0x3fb5f0e3
	v_fmaak_f32 v12, v11, v12, 0xbe91a98e
	v_fmaak_f32 v12, v11, v12, 0x3e827906
	v_mul_f32_e32 v11, v11, v12
	v_mul_f32_e64 v12, |v7|, s3
	v_mul_f32_e64 v12, |v7|, v12
	v_exp_f32_e32 v12, v12
	s_nop 0
	v_fma_f32 v11, -v12, v11, 1.0
	v_bfi_b32 v7, s13, v11, v7
	v_add_f32_e32 v7, 1.0, v7
	v_mul_f32_e32 v11, v10, v7
	v_fmac_f32_e32 v11, v9, v8
	s_nop 1
	v_add_f32_dpp v11, v11, v11 row_ror:8 row_mask:0xf bank_mask:0xf bound_ctrl:1
	s_nop 1
	v_add_f32_dpp v11, v11, v11 row_ror:4 row_mask:0xf bank_mask:0xf bound_ctrl:1
	s_nop 1
	v_add_f32_dpp v11, v11, v11 row_ror:2 row_mask:0xf bank_mask:0xf bound_ctrl:1
	s_nop 1
	v_add_f32_dpp v11, v11, v11 row_ror:1 row_mask:0xf bank_mask:0xf bound_ctrl:1
	ds_bpermute_b32 v12, v3, v11
	s_waitcnt lgkmcnt(0)
	v_add_f32_e32 v11, v11, v12
	v_mov_b32_e32 v12, v11
	s_nop 1
	v_permlane32_swap_b32_e32 v11, v12
	v_add_f32_e32 v11, v11, v12
	v_mul_f32_e32 v11, 0x3c000000, v11
	v_fma_f32 v7, v10, v7, -v11
	v_fma_f32 v8, v9, v8, -v11
	v_mul_f32_e32 v9, v7, v7
	v_fmac_f32_e32 v9, v8, v8
	s_nop 1
	v_add_f32_dpp v9, v9, v9 row_ror:8 row_mask:0xf bank_mask:0xf bound_ctrl:1
	s_nop 1
	v_add_f32_dpp v9, v9, v9 row_ror:4 row_mask:0xf bank_mask:0xf bound_ctrl:1
	s_nop 1
	v_add_f32_dpp v9, v9, v9 row_ror:2 row_mask:0xf bank_mask:0xf bound_ctrl:1
	s_nop 1
	v_add_f32_dpp v9, v9, v9 row_ror:1 row_mask:0xf bank_mask:0xf bound_ctrl:1
	ds_bpermute_b32 v10, v3, v9
	s_waitcnt lgkmcnt(0)
	v_add_f32_e32 v9, v9, v10
	v_mov_b32_e32 v10, v9
	s_nop 1
	v_permlane32_swap_b32_e32 v9, v10
	v_add_f32_e32 v9, v9, v10
	v_fmamk_f32 v9, v9, 0x3c000000, v177
	v_cmp_gt_f32_e32 vcc, s16, v9
	v_mul_f32_e32 v10, 0x4b800000, v9
	s_nop 0
	v_cndmask_b32_e32 v9, v9, v10, vcc
	v_rsq_f32_e32 v9, v9
	s_nop 0
	v_mul_f32_e32 v10, 0x45800000, v9
	v_cndmask_b32_e32 v9, v9, v10, vcc
	v_mul_f32_e32 v8, v8, v9
	v_bfe_u32 v10, v8, 16, 1
	v_add3_u32 v8, v8, v10, s83
	v_add_u32_e32 v10, s5, v6
	v_mul_f32_e32 v7, v7, v9
	ds_write_b16_d16_hi v10, v8
	v_bfe_u32 v8, v7, 16, 1
	s_add_i32 s5, s5, 2
	v_add3_u32 v7, v7, v8, s83
	ds_write_b16_d16_hi v10, v7 offset:272
	s_waitcnt vmcnt(26)
; DI bf16 f2bf(float f) { unsigned u = __float_as_uint(f); u += 0x7fffu + ((u >> 16) & 1u); return (bf16)(u >> 16); }
; DI float gelu(float x) { return 0.5f * x * (1.f + erf_as(x * 0.70710678118654752f)); }
;   DI bf16* P() const { return (bf16*)(p.ws + WS_P); }
; DI void vgt_tile(const Ctx& c, int ti, bf16* lds) {
;     ...
;   for (int rr = 0; rr < 32; ++rr) {
;     const int t = wave * 32 + rr;
;     const unsigned u = *(const unsigned*)(c.P() + (size_t)(row0 + t) * LDP + C_V + g * 128 + 2 * lane);
;     const float a = gelu(__uint_as_float(u << 16)), b = gelu(__uint_as_float(u & 0xffff0000u));
;     const float mean = wave_sum(a + b) * (1.f / 128.f);
;     const float da = a - mean, db = b - mean;
;     const float rstd = rsqrtf(wave_sum(da * da + db * db) * (1.f / 128.f) + LN_EPS);
;     lds[(2 * lane) * LDT + t] = f2bf(da * rstd);
;     lds[(2 * lane + 1) * LDT + t] = f2bf(db * rstd);
;   }
	v_lshlrev_b32_e32 v8, 16, v25
	v_mul_f32_e32 v9, 0.5, v8
	v_mul_f32_e32 v8, 0x3f3504f3, v8
	v_fma_f32 v10, |v8|, s2, 1.0
	v_rcp_f32_e32 v10, v10
	v_and_b32_e32 v7, 0xffff0000, v25
	v_fmamk_f32 v11, v10, 0x3f87dc22, v176
	v_fmaak_f32 v11, v10, v11, 0x3fb5f0e3
	v_fmaak_f32 v11, v10, v11, 0xbe91a98e
	v_fmaak_f32 v11, v10, v11, 0x3e827906
	v_mul_f32_e32 v10, v10, v11
	v_mul_f32_e64 v11, |v8|, s3
	v_mul_f32_e64 v11, |v8|, v11
	v_exp_f32_e32 v11, v11
	s_nop 0
	v_fma_f32 v10, -v11, v10, 1.0
	v_bfi_b32 v8, s13, v10, v8
	v_mul_f32_e32 v10, 0.5, v7
	v_mul_f32_e32 v7, 0x3f3504f3, v7
	v_fma_f32 v11, |v7|, s2, 1.0
	v_rcp_f32_e32 v11, v11
	v_add_f32_e32 v8, 1.0, v8
	v_fmamk_f32 v12, v11, 0x3f87dc22, v176
	v_fmaak_f32 v12, v11, v12, 0x3fb5f0e3
	v_fmaak_f32 v12, v11, v12, 0xbe91a98e
	v_fmaak_f32 v12, v11, v12, 0x3e827906
	v_mul_f32_e32 v11, v11, v12
	v_mul_f32_e64 v12, |v7|, s3
	v_mul_f32_e64 v12, |v7|, v12
	v_exp_f32_e32 v12, v12
	s_nop 0
	v_fma_f32 v11, -v12, v11, 1.0
	v_bfi_b32 v7, s13, v11, v7
	v_add_f32_e32 v7, 1.0, v7
	v_mul_f32_e32 v11, v10, v7
	v_fmac_f32_e32 v11, v9, v8
	s_nop 1
	v_add_f32_dpp v11, v11, v11 row_ror:8 row_mask:0xf bank_mask:0xf bound_ctrl:1
	s_nop 1
	v_add_f32_dpp v11, v11, v11 row_ror:4 row_mask:0xf bank_mask:0xf bound_ctrl:1
	s_nop 1
	v_add_f32_dpp v11, v11, v11 row_ror:2 row_mask:0xf bank_mask:0xf bound_ctrl:1
	s_nop 1
	v_add_f32_dpp v11, v11, v11 row_ror:1 row_mask:0xf bank_mask:0xf bound_ctrl:1
	ds_bpermute_b32 v12, v3, v11
	s_waitcnt lgkmcnt(0)
	v_add_f32_e32 v11, v11, v12
	v_mov_b32_e32 v12, v11
	s_nop 1
	v_permlane32_swap_b32_e32 v11, v12
	v_add_f32_e32 v11, v11, v12
	v_mul_f32_e32 v11, 0x3c000000, v11
	v_fma_f32 v7, v10, v7, -v11
	v_fma_f32 v8, v9, v8, -v11
	v_mul_f32_e32 v9, v7, v7
	v_fmac_f32_e32 v9, v8, v8
	s_nop 1
	v_add_f32_dpp v9, v9, v9 row_ror:8 row_mask:0xf bank_mask:0xf bound_ctrl:1
	s_nop 1
	v_add_f32_dpp v9, v9, v9 row_ror:4 row_mask:0xf bank_mask:0xf bound_ctrl:1
	s_nop 1
	v_add_f32_dpp v9, v9, v9 row_ror:2 row_mask:0xf bank_mask:0xf bound_ctrl:1
	s_nop 1
	v_add_f32_dpp v9, v9, v9 row_ror:1 row_mask:0xf bank_mask:0xf bound_ctrl:1
	ds_bpermute_b32 v10, v3, v9
	s_waitcnt lgkmcnt(0)
	v_add_f32_e32 v9, v9, v10
	v_mov_b32_e32 v10, v9
	s_nop 1
	v_permlane32_swap_b32_e32 v9, v10
	v_add_f32_e32 v9, v9, v10
	v_fmamk_f32 v9, v9, 0x3c000000, v177
	v_cmp_gt_f32_e32 vcc, s16, v9
	v_mul_f32_e32 v10, 0x4b800000, v9
	s_nop 0
	v_cndmask_b32_e32 v9, v9, v10, vcc
	v_rsq_f32_e32 v9, v9
	s_nop 0
	v_mul_f32_e32 v10, 0x45800000, v9
	v_cndmask_b32_e32 v9, v9, v10, vcc
	v_mul_f32_e32 v8, v8, v9
	v_bfe_u32 v10, v8, 16, 1
	v_add3_u32 v8, v8, v10, s83
	v_add_u32_e32 v10, s5, v6
	v_mul_f32_e32 v7, v7, v9
	ds_write_b16_d16_hi v10, v8
	v_bfe_u32 v8, v7, 16, 1
	s_add_i32 s5, s5, 2
	v_add3_u32 v7, v7, v8, s83
	ds_write_b16_d16_hi v10, v7 offset:272
	s_waitcnt vmcnt(25)
	v_lshlrev_b32_e32 v8, 16, v26
	v_mul_f32_e32 v9, 0.5, v8
	v_mul_f32_e32 v8, 0x3f3504f3, v8
	v_fma_f32 v10, |v8|, s2, 1.0
	v_rcp_f32_e32 v10, v10
	v_and_b32_e32 v7, 0xffff0000, v26
	v_fmamk_f32 v11, v10, 0x3f87dc22, v176
	v_fmaak_f32 v11, v10, v11, 0x3fb5f0e3
	v_fmaak_f32 v11, v10, v11, 0xbe91a98e
	v_fmaak_f32 v11, v10, v11, 0x3e827906
	v_mul_f32_e32 v10, v10, v11
	v_mul_f32_e64 v11, |v8|, s3
	v_mul_f32_e64 v11, |v8|, v11
	v_exp_f32_e32 v11, v11
	s_nop 0
	v_fma_f32 v10, -v11, v10, 1.0
	v_bfi_b32 v8, s13, v10, v8
	v_mul_f32_e32 v10, 0.5, v7
	v_mul_f32_e32 v7, 0x3f3504f3, v7
	v_fma_f32 v11, |v7|, s2, 1.0
	v_rcp_f32_e32 v11, v11
	v_add_f32_e32 v8, 1.0, v8
	v_fmamk_f32 v12, v11, 0x3f87dc22, v176
	v_fmaak_f32 v12, v11, v12, 0x3fb5f0e3
	v_fmaak_f32 v12, v11, v12, 0xbe91a98e
	v_fmaak_f32 v12, v11, v12, 0x3e827906
	v_mul_f32_e32 v11, v11, v12
	v_mul_f32_e64 v12, |v7|, s3
	v_mul_f32_e64 v12, |v7|, v12
	v_exp_f32_e32 v12, v12
	s_nop 0
	v_fma_f32 v11, -v12, v11, 1.0
	v_bfi_b32 v7, s13, v11, v7
	v_add_f32_e32 v7, 1.0, v7
	v_mul_f32_e32 v11, v10, v7
	v_fmac_f32_e32 v11, v9, v8
	s_nop 1
	v_add_f32_dpp v11, v11, v11 row_ror:8 row_mask:0xf bank_mask:0xf bound_ctrl:1
	s_nop 1
	v_add_f32_dpp v11, v11, v11 row_ror:4 row_mask:0xf bank_mask:0xf bound_ctrl:1
	s_nop 1
	v_add_f32_dpp v11, v11, v11 row_ror:2 row_mask:0xf bank_mask:0xf bound_ctrl:1
	s_nop 1
	v_add_f32_dpp v11, v11, v11 row_ror:1 row_mask:0xf bank_mask:0xf bound_ctrl:1
	ds_bpermute_b32 v12, v3, v11
	s_waitcnt lgkmcnt(0)
	v_add_f32_e32 v11, v11, v12
	v_mov_b32_e32 v12, v11
	s_nop 1
	v_permlane32_swap_b32_e32 v11, v12
	v_add_f32_e32 v11, v11, v12
	v_mul_f32_e32 v11, 0x3c000000, v11
	v_fma_f32 v7, v10, v7, -v11
	v_fma_f32 v8, v9, v8, -v11
	v_mul_f32_e32 v9, v7, v7
	v_fmac_f32_e32 v9, v8, v8
	s_nop 1
	v_add_f32_dpp v9, v9, v9 row_ror:8 row_mask:0xf bank_mask:0xf bound_ctrl:1
	s_nop 1
	v_add_f32_dpp v9, v9, v9 row_ror:4 row_mask:0xf bank_mask:0xf bound_ctrl:1
	s_nop 1
	v_add_f32_dpp v9, v9, v9 row_ror:2 row_mask:0xf bank_mask:0xf bound_ctrl:1
	s_nop 1
	v_add_f32_dpp v9, v9, v9 row_ror:1 row_mask:0xf bank_mask:0xf bound_ctrl:1
	ds_bpermute_b32 v10, v3, v9
	s_waitcnt lgkmcnt(0)
	v_add_f32_e32 v9, v9, v10
	v_mov_b32_e32 v10, v9
	s_nop 1
	v_permlane32_swap_b32_e32 v9, v10
	v_add_f32_e32 v9, v9, v10
	v_fmamk_f32 v9, v9, 0x3c000000, v177
	v_cmp_gt_f32_e32 vcc, s16, v9
	v_mul_f32_e32 v10, 0x4b800000, v9
	s_nop 0
	v_cndmask_b32_e32 v9, v9, v10, vcc
	v_rsq_f32_e32 v9, v9
	s_nop 0
	v_mul_f32_e32 v10, 0x45800000, v9
	v_cndmask_b32_e32 v9, v9, v10, vcc
	v_mul_f32_e32 v8, v8, v9
	v_bfe_u32 v10, v8, 16, 1
	v_add3_u32 v8, v8, v10, s83
	v_add_u32_e32 v10, s5, v6
	v_mul_f32_e32 v7, v7, v9
	ds_write_b16_d16_hi v10, v8
	v_bfe_u32 v8, v7, 16, 1
	s_add_i32 s5, s5, 2
	v_add3_u32 v7, v7, v8, s83
	ds_write_b16_d16_hi v10, v7 offset:272
	s_waitcnt vmcnt(24)
; DI bf16 f2bf(float f) { unsigned u = __float_as_uint(f); u += 0x7fffu + ((u >> 16) & 1u); return (bf16)(u >> 16); }
;   DI bf16* P() const { return (bf16*)(p.ws + WS_P); }
; DI float erf_as(float x) {
;   const float ax = fabsf(x);
;   const float t = __builtin_amdgcn_rcpf(1.f + 0.3275911f * ax);
;   const float poly = t * (0.254829592f + t * (-0.284496736f + t * (1.421413741f + t * (-1.453152027f + t * 1.061405429f))));
;   const float y = 1.f - poly * __builtin_amdgcn_exp2f(-1.4426950408889634f * ax * ax);
;   return copysignf(y, x);
; }
; DI float gelu(float x) { return 0.5f * x * (1.f + erf_as(x * 0.70710678118654752f)); }
; DI void vgt_tile(const Ctx& c, int ti, bf16* lds) {
;     ...
;   for (int rr = 0; rr < 32; ++rr) {
;     const int t = wave * 32 + rr;
;     const unsigned u = *(const unsigned*)(c.P() + (size_t)(row0 + t) * LDP + C_V + g * 128 + 2 * lane);
;     const float a = gelu(__uint_as_float(u << 16)), b = gelu(__uint_as_float(u & 0xffff0000u));
;     const float mean = wave_sum(a + b) * (1.f / 128.f);
;     const float da = a - mean, db = b - mean;
;     const float rstd = rsqrtf(wave_sum(da * da + db * db) * (1.f / 128.f) + LN_EPS);
;     lds[(2 * lane) * LDT + t] = f2bf(da * rstd);
;     lds[(2 * lane + 1) * LDT + t] = f2bf(db * rstd);
;   }
	v_lshlrev_b32_e32 v8, 16, v27
	v_mul_f32_e32 v9, 0.5, v8
	v_mul_f32_e32 v8, 0x3f3504f3, v8
	v_fma_f32 v10, |v8|, s2, 1.0
	v_rcp_f32_e32 v10, v10
	v_and_b32_e32 v7, 0xffff0000, v27
	v_fmamk_f32 v11, v10, 0x3f87dc22, v176
	v_fmaak_f32 v11, v10, v11, 0x3fb5f0e3
	v_fmaak_f32 v11, v10, v11, 0xbe91a98e
	v_fmaak_f32 v11, v10, v11, 0x3e827906
	v_mul_f32_e32 v10, v10, v11
	v_mul_f32_e64 v11, |v8|, s3
	v_mul_f32_e64 v11, |v8|, v11
	v_exp_f32_e32 v11, v11
	s_nop 0
	v_fma_f32 v10, -v11, v10, 1.0
	v_bfi_b32 v8, s13, v10, v8
	v_mul_f32_e32 v10, 0.5, v7
	v_mul_f32_e32 v7, 0x3f3504f3, v7
	v_fma_f32 v11, |v7|, s2, 1.0
	v_rcp_f32_e32 v11, v11
	v_add_f32_e32 v8, 1.0, v8
	v_fmamk_f32 v12, v11, 0x3f87dc22, v176
	v_fmaak_f32 v12, v11, v12, 0x3fb5f0e3
	v_fmaak_f32 v12, v11, v12, 0xbe91a98e
	v_fmaak_f32 v12, v11, v12, 0x3e827906
	v_mul_f32_e32 v11, v11, v12
	v_mul_f32_e64 v12, |v7|, s3
	v_mul_f32_e64 v12, |v7|, v12
	v_exp_f32_e32 v12, v12
	s_nop 0
	v_fma_f32 v11, -v12, v11, 1.0
	v_bfi_b32 v7, s13, v11, v7
	v_add_f32_e32 v7, 1.0, v7
	v_mul_f32_e32 v11, v10, v7
	v_fmac_f32_e32 v11, v9, v8
	s_nop 1
	v_add_f32_dpp v11, v11, v11 row_ror:8 row_mask:0xf bank_mask:0xf bound_ctrl:1
	s_nop 1
	v_add_f32_dpp v11, v11, v11 row_ror:4 row_mask:0xf bank_mask:0xf bound_ctrl:1
	s_nop 1
	v_add_f32_dpp v11, v11, v11 row_ror:2 row_mask:0xf bank_mask:0xf bound_ctrl:1
	s_nop 1
	v_add_f32_dpp v11, v11, v11 row_ror:1 row_mask:0xf bank_mask:0xf bound_ctrl:1
	ds_bpermute_b32 v12, v3, v11
	s_waitcnt lgkmcnt(0)
	v_add_f32_e32 v11, v11, v12
	v_mov_b32_e32 v12, v11
	s_nop 1
	v_permlane32_swap_b32_e32 v11, v12
	v_add_f32_e32 v11, v11, v12
	v_mul_f32_e32 v11, 0x3c000000, v11
	v_fma_f32 v7, v10, v7, -v11
	v_fma_f32 v8, v9, v8, -v11
	v_mul_f32_e32 v9, v7, v7
	v_fmac_f32_e32 v9, v8, v8
	s_nop 1
	v_add_f32_dpp v9, v9, v9 row_ror:8 row_mask:0xf bank_mask:0xf bound_ctrl:1
	s_nop 1
	v_add_f32_dpp v9, v9, v9 row_ror:4 row_mask:0xf bank_mask:0xf bound_ctrl:1
	s_nop 1
	v_add_f32_dpp v9, v9, v9 row_ror:2 row_mask:0xf bank_mask:0xf bound_ctrl:1
	s_nop 1
	v_add_f32_dpp v9, v9, v9 row_ror:1 row_mask:0xf bank_mask:0xf bound_ctrl:1
	ds_bpermute_b32 v10, v3, v9
	s_waitcnt lgkmcnt(0)
	v_add_f32_e32 v9, v9, v10
	v_mov_b32_e32 v10, v9
	s_nop 1
	v_permlane32_swap_b32_e32 v9, v10
	v_add_f32_e32 v9, v9, v10
	v_fmamk_f32 v9, v9, 0x3c000000, v177
	v_cmp_gt_f32_e32 vcc, s16, v9
	v_mul_f32_e32 v10, 0x4b800000, v9
	s_nop 0
	v_cndmask_b32_e32 v9, v9, v10, vcc
	v_rsq_f32_e32 v9, v9
	s_nop 0
	v_mul_f32_e32 v10, 0x45800000, v9
	v_cndmask_b32_e32 v9, v9, v10, vcc
	v_mul_f32_e32 v8, v8, v9
	v_bfe_u32 v10, v8, 16, 1
	v_add3_u32 v8, v8, v10, s83
	v_add_u32_e32 v10, s5, v6
	v_mul_f32_e32 v7, v7, v9
	ds_write_b16_d16_hi v10, v8
	v_bfe_u32 v8, v7, 16, 1
	s_add_i32 s5, s5, 2
	v_add3_u32 v7, v7, v8, s83
	ds_write_b16_d16_hi v10, v7 offset:272
	s_waitcnt vmcnt(23)
	v_lshlrev_b32_e32 v8, 16, v28
	v_mul_f32_e32 v9, 0.5, v8
	v_mul_f32_e32 v8, 0x3f3504f3, v8
	v_fma_f32 v10, |v8|, s2, 1.0
	v_rcp_f32_e32 v10, v10
	v_and_b32_e32 v7, 0xffff0000, v28
	v_fmamk_f32 v11, v10, 0x3f87dc22, v176
	v_fmaak_f32 v11, v10, v11, 0x3fb5f0e3
	v_fmaak_f32 v11, v10, v11, 0xbe91a98e
	v_fmaak_f32 v11, v10, v11, 0x3e827906
	v_mul_f32_e32 v10, v10, v11
	v_mul_f32_e64 v11, |v8|, s3
	v_mul_f32_e64 v11, |v8|, v11
	v_exp_f32_e32 v11, v11
	s_nop 0
	v_fma_f32 v10, -v11, v10, 1.0
	v_bfi_b32 v8, s13, v10, v8
	v_mul_f32_e32 v10, 0.5, v7
	v_mul_f32_e32 v7, 0x3f3504f3, v7
	v_fma_f32 v11, |v7|, s2, 1.0
	v_rcp_f32_e32 v11, v11
	v_add_f32_e32 v8, 1.0, v8
	v_fmamk_f32 v12, v11, 0x3f87dc22, v176
	v_fmaak_f32 v12, v11, v12, 0x3fb5f0e3
	v_fmaak_f32 v12, v11, v12, 0xbe91a98e
	v_fmaak_f32 v12, v11, v12, 0x3e827906
	v_mul_f32_e32 v11, v11, v12
	v_mul_f32_e64 v12, |v7|, s3
	v_mul_f32_e64 v12, |v7|, v12
	v_exp_f32_e32 v12, v12
	s_nop 0
	v_fma_f32 v11, -v12, v11, 1.0
	v_bfi_b32 v7, s13, v11, v7
	v_add_f32_e32 v7, 1.0, v7
	v_mul_f32_e32 v11, v10, v7
	v_fmac_f32_e32 v11, v9, v8
	s_nop 1
	v_add_f32_dpp v11, v11, v11 row_ror:8 row_mask:0xf bank_mask:0xf bound_ctrl:1
	s_nop 1
	v_add_f32_dpp v11, v11, v11 row_ror:4 row_mask:0xf bank_mask:0xf bound_ctrl:1
	s_nop 1
	v_add_f32_dpp v11, v11, v11 row_ror:2 row_mask:0xf bank_mask:0xf bound_ctrl:1
	s_nop 1
	v_add_f32_dpp v11, v11, v11 row_ror:1 row_mask:0xf bank_mask:0xf bound_ctrl:1
	ds_bpermute_b32 v12, v3, v11
	s_waitcnt lgkmcnt(0)
	v_add_f32_e32 v11, v11, v12
	v_mov_b32_e32 v12, v11
	s_nop 1
	v_permlane32_swap_b32_e32 v11, v12
	v_add_f32_e32 v11, v11, v12
	v_mul_f32_e32 v11, 0x3c000000, v11
	v_fma_f32 v7, v10, v7, -v11
	v_fma_f32 v8, v9, v8, -v11
	v_mul_f32_e32 v9, v7, v7
	v_fmac_f32_e32 v9, v8, v8
	s_nop 1
	v_add_f32_dpp v9, v9, v9 row_ror:8 row_mask:0xf bank_mask:0xf bound_ctrl:1
	s_nop 1
	v_add_f32_dpp v9, v9, v9 row_ror:4 row_mask:0xf bank_mask:0xf bound_ctrl:1
	s_nop 1
	v_add_f32_dpp v9, v9, v9 row_ror:2 row_mask:0xf bank_mask:0xf bound_ctrl:1
	s_nop 1
	v_add_f32_dpp v9, v9, v9 row_ror:1 row_mask:0xf bank_mask:0xf bound_ctrl:1
	ds_bpermute_b32 v10, v3, v9
	s_waitcnt lgkmcnt(0)
	v_add_f32_e32 v9, v9, v10
	v_mov_b32_e32 v10, v9
	s_nop 1
	v_permlane32_swap_b32_e32 v9, v10
	v_add_f32_e32 v9, v9, v10
	v_fmamk_f32 v9, v9, 0x3c000000, v177
	v_cmp_gt_f32_e32 vcc, s16, v9
	v_mul_f32_e32 v10, 0x4b800000, v9
	s_nop 0
	v_cndmask_b32_e32 v9, v9, v10, vcc
	v_rsq_f32_e32 v9, v9
	s_nop 0
	v_mul_f32_e32 v10, 0x45800000, v9
	v_cndmask_b32_e32 v9, v9, v10, vcc
	v_mul_f32_e32 v8, v8, v9
	v_bfe_u32 v10, v8, 16, 1
	v_add3_u32 v8, v8, v10, s83
	v_add_u32_e32 v10, s5, v6
	v_mul_f32_e32 v7, v7, v9
	ds_write_b16_d16_hi v10, v8
	v_bfe_u32 v8, v7, 16, 1
	s_add_i32 s5, s5, 2
	v_add3_u32 v7, v7, v8, s83
	ds_write_b16_d16_hi v10, v7 offset:272
	s_waitcnt vmcnt(22)
; DI bf16 f2bf(float f) { unsigned u = __float_as_uint(f); u += 0x7fffu + ((u >> 16) & 1u); return (bf16)(u >> 16); }
;   DI bf16* P() const { return (bf16*)(p.ws + WS_P); }
; DI float erf_as(float x) {
;   const float ax = fabsf(x);
;   const float t = __builtin_amdgcn_rcpf(1.f + 0.3275911f * ax);
;   const float poly = t * (0.254829592f + t * (-0.284496736f + t * (1.421413741f + t * (-1.453152027f + t * 1.061405429f))));
;   const float y = 1.f - poly * __builtin_amdgcn_exp2f(-1.4426950408889634f * ax * ax);
;   return copysignf(y, x);
; }
; DI float gelu(float x) { return 0.5f * x * (1.f + erf_as(x * 0.70710678118654752f)); }
; DI void vgt_tile(const Ctx& c, int ti, bf16* lds) {
;     ...
;   for (int rr = 0; rr < 32; ++rr) {
;     const int t = wave * 32 + rr;
;     const unsigned u = *(const unsigned*)(c.P() + (size_t)(row0 + t) * LDP + C_V + g * 128 + 2 * lane);
;     const float a = gelu(__uint_as_float(u << 16)), b = gelu(__uint_as_float(u & 0xffff0000u));
;     const float mean = wave_sum(a + b) * (1.f / 128.f);
;     const float da = a - mean, db = b - mean;
;     const float rstd = rsqrtf(wave_sum(da * da + db * db) * (1.f / 128.f) + LN_EPS);
;     lds[(2 * lane) * LDT + t] = f2bf(da * rstd);
;     lds[(2 * lane + 1) * LDT + t] = f2bf(db * rstd);
;   }
	v_lshlrev_b32_e32 v8, 16, v29
	v_mul_f32_e32 v9, 0.5, v8
	v_mul_f32_e32 v8, 0x3f3504f3, v8
	v_fma_f32 v10, |v8|, s2, 1.0
	v_rcp_f32_e32 v10, v10
	v_and_b32_e32 v7, 0xffff0000, v29
	v_fmamk_f32 v11, v10, 0x3f87dc22, v176
	v_fmaak_f32 v11, v10, v11, 0x3fb5f0e3
	v_fmaak_f32 v11, v10, v11, 0xbe91a98e
	v_fmaak_f32 v11, v10, v11, 0x3e827906
	v_mul_f32_e32 v10, v10, v11
	v_mul_f32_e64 v11, |v8|, s3
	v_mul_f32_e64 v11, |v8|, v11
	v_exp_f32_e32 v11, v11
	s_nop 0
	v_fma_f32 v10, -v11, v10, 1.0
	v_bfi_b32 v8, s13, v10, v8
	v_mul_f32_e32 v10, 0.5, v7
	v_mul_f32_e32 v7, 0x3f3504f3, v7
	v_fma_f32 v11, |v7|, s2, 1.0
	v_rcp_f32_e32 v11, v11
	v_add_f32_e32 v8, 1.0, v8
	v_fmamk_f32 v12, v11, 0x3f87dc22, v176
	v_fmaak_f32 v12, v11, v12, 0x3fb5f0e3
	v_fmaak_f32 v12, v11, v12, 0xbe91a98e
	v_fmaak_f32 v12, v11, v12, 0x3e827906
	v_mul_f32_e32 v11, v11, v12
	v_mul_f32_e64 v12, |v7|, s3
	v_mul_f32_e64 v12, |v7|, v12
	v_exp_f32_e32 v12, v12
	s_nop 0
	v_fma_f32 v11, -v12, v11, 1.0
	v_bfi_b32 v7, s13, v11, v7
	v_add_f32_e32 v7, 1.0, v7
	v_mul_f32_e32 v11, v10, v7
	v_fmac_f32_e32 v11, v9, v8
	s_nop 1
	v_add_f32_dpp v11, v11, v11 row_ror:8 row_mask:0xf bank_mask:0xf bound_ctrl:1
	s_nop 1
	v_add_f32_dpp v11, v11, v11 row_ror:4 row_mask:0xf bank_mask:0xf bound_ctrl:1
	s_nop 1
	v_add_f32_dpp v11, v11, v11 row_ror:2 row_mask:0xf bank_mask:0xf bound_ctrl:1
	s_nop 1
	v_add_f32_dpp v11, v11, v11 row_ror:1 row_mask:0xf bank_mask:0xf bound_ctrl:1
	ds_bpermute_b32 v12, v3, v11
	s_waitcnt lgkmcnt(0)
	v_add_f32_e32 v11, v11, v12
	v_mov_b32_e32 v12, v11
	s_nop 1
	v_permlane32_swap_b32_e32 v11, v12
	v_add_f32_e32 v11, v11, v12
	v_mul_f32_e32 v11, 0x3c000000, v11
	v_fma_f32 v7, v10, v7, -v11
	v_fma_f32 v8, v9, v8, -v11
	v_mul_f32_e32 v9, v7, v7
	v_fmac_f32_e32 v9, v8, v8
	s_nop 1
	v_add_f32_dpp v9, v9, v9 row_ror:8 row_mask:0xf bank_mask:0xf bound_ctrl:1
	s_nop 1
	v_add_f32_dpp v9, v9, v9 row_ror:4 row_mask:0xf bank_mask:0xf bound_ctrl:1
	s_nop 1
	v_add_f32_dpp v9, v9, v9 row_ror:2 row_mask:0xf bank_mask:0xf bound_ctrl:1
	s_nop 1
	v_add_f32_dpp v9, v9, v9 row_ror:1 row_mask:0xf bank_mask:0xf bound_ctrl:1
	ds_bpermute_b32 v10, v3, v9
	s_waitcnt lgkmcnt(0)
	v_add_f32_e32 v9, v9, v10
	v_mov_b32_e32 v10, v9
	s_nop 1
	v_permlane32_swap_b32_e32 v9, v10
	v_add_f32_e32 v9, v9, v10
	v_fmamk_f32 v9, v9, 0x3c000000, v177
	v_cmp_gt_f32_e32 vcc, s16, v9
	v_mul_f32_e32 v10, 0x4b800000, v9
	s_nop 0
	v_cndmask_b32_e32 v9, v9, v10, vcc
	v_rsq_f32_e32 v9, v9
	s_nop 0
	v_mul_f32_e32 v10, 0x45800000, v9
	v_cndmask_b32_e32 v9, v9, v10, vcc
	v_mul_f32_e32 v8, v8, v9
	v_bfe_u32 v10, v8, 16, 1
	v_add3_u32 v8, v8, v10, s83
	v_add_u32_e32 v10, s5, v6
	v_mul_f32_e32 v7, v7, v9
	ds_write_b16_d16_hi v10, v8
	v_bfe_u32 v8, v7, 16, 1
	s_add_i32 s5, s5, 2
	v_add3_u32 v7, v7, v8, s83
	ds_write_b16_d16_hi v10, v7 offset:272
	s_waitcnt vmcnt(21)
	v_lshlrev_b32_e32 v8, 16, v30
	v_mul_f32_e32 v9, 0.5, v8
	v_mul_f32_e32 v8, 0x3f3504f3, v8
	v_fma_f32 v10, |v8|, s2, 1.0
	v_rcp_f32_e32 v10, v10
	v_and_b32_e32 v7, 0xffff0000, v30
	v_fmamk_f32 v11, v10, 0x3f87dc22, v176
	v_fmaak_f32 v11, v10, v11, 0x3fb5f0e3
	v_fmaak_f32 v11, v10, v11, 0xbe91a98e
	v_fmaak_f32 v11, v10, v11, 0x3e827906
	v_mul_f32_e32 v10, v10, v11
	v_mul_f32_e64 v11, |v8|, s3
	v_mul_f32_e64 v11, |v8|, v11
	v_exp_f32_e32 v11, v11
	s_nop 0
	v_fma_f32 v10, -v11, v10, 1.0
	v_bfi_b32 v8, s13, v10, v8
	v_mul_f32_e32 v10, 0.5, v7
	v_mul_f32_e32 v7, 0x3f3504f3, v7
	v_fma_f32 v11, |v7|, s2, 1.0
	v_rcp_f32_e32 v11, v11
	v_add_f32_e32 v8, 1.0, v8
	v_fmamk_f32 v12, v11, 0x3f87dc22, v176
	v_fmaak_f32 v12, v11, v12, 0x3fb5f0e3
	v_fmaak_f32 v12, v11, v12, 0xbe91a98e
	v_fmaak_f32 v12, v11, v12, 0x3e827906
	v_mul_f32_e32 v11, v11, v12
	v_mul_f32_e64 v12, |v7|, s3
	v_mul_f32_e64 v12, |v7|, v12
	v_exp_f32_e32 v12, v12
	s_nop 0
	v_fma_f32 v11, -v12, v11, 1.0
	v_bfi_b32 v7, s13, v11, v7
	v_add_f32_e32 v7, 1.0, v7
	v_mul_f32_e32 v11, v10, v7
	v_fmac_f32_e32 v11, v9, v8
	s_nop 1
	v_add_f32_dpp v11, v11, v11 row_ror:8 row_mask:0xf bank_mask:0xf bound_ctrl:1
	s_nop 1
	v_add_f32_dpp v11, v11, v11 row_ror:4 row_mask:0xf bank_mask:0xf bound_ctrl:1
	s_nop 1
	v_add_f32_dpp v11, v11, v11 row_ror:2 row_mask:0xf bank_mask:0xf bound_ctrl:1
	s_nop 1
	v_add_f32_dpp v11, v11, v11 row_ror:1 row_mask:0xf bank_mask:0xf bound_ctrl:1
	ds_bpermute_b32 v12, v3, v11
	s_waitcnt lgkmcnt(0)
	v_add_f32_e32 v11, v11, v12
	v_mov_b32_e32 v12, v11
	s_nop 1
	v_permlane32_swap_b32_e32 v11, v12
	v_add_f32_e32 v11, v11, v12
	v_mul_f32_e32 v11, 0x3c000000, v11
	v_fma_f32 v7, v10, v7, -v11
	v_fma_f32 v8, v9, v8, -v11
	v_mul_f32_e32 v9, v7, v7
	v_fmac_f32_e32 v9, v8, v8
	s_nop 1
	v_add_f32_dpp v9, v9, v9 row_ror:8 row_mask:0xf bank_mask:0xf bound_ctrl:1
	s_nop 1
	v_add_f32_dpp v9, v9, v9 row_ror:4 row_mask:0xf bank_mask:0xf bound_ctrl:1
	s_nop 1
	v_add_f32_dpp v9, v9, v9 row_ror:2 row_mask:0xf bank_mask:0xf bound_ctrl:1
	s_nop 1
	v_add_f32_dpp v9, v9, v9 row_ror:1 row_mask:0xf bank_mask:0xf bound_ctrl:1
	ds_bpermute_b32 v10, v3, v9
	s_waitcnt lgkmcnt(0)
	v_add_f32_e32 v9, v9, v10
	v_mov_b32_e32 v10, v9
	s_nop 1
	v_permlane32_swap_b32_e32 v9, v10
	v_add_f32_e32 v9, v9, v10
	v_fmamk_f32 v9, v9, 0x3c000000, v177
	v_cmp_gt_f32_e32 vcc, s16, v9
	v_mul_f32_e32 v10, 0x4b800000, v9
	s_nop 0
	v_cndmask_b32_e32 v9, v9, v10, vcc
	v_rsq_f32_e32 v9, v9
	s_nop 0
	v_mul_f32_e32 v10, 0x45800000, v9
	v_cndmask_b32_e32 v9, v9, v10, vcc
	v_mul_f32_e32 v8, v8, v9
	v_bfe_u32 v10, v8, 16, 1
	v_add3_u32 v8, v8, v10, s83
	v_add_u32_e32 v10, s5, v6
	v_mul_f32_e32 v7, v7, v9
	ds_write_b16_d16_hi v10, v8
	v_bfe_u32 v8, v7, 16, 1
	s_add_i32 s5, s5, 2
	v_add3_u32 v7, v7, v8, s83
	ds_write_b16_d16_hi v10, v7 offset:272
	s_waitcnt vmcnt(20)
; DI bf16 f2bf(float f) { unsigned u = __float_as_uint(f); u += 0x7fffu + ((u >> 16) & 1u); return (bf16)(u >> 16); }
;   DI bf16* P() const { return (bf16*)(p.ws + WS_P); }
; DI float erf_as(float x) {
;   const float ax = fabsf(x);
;   const float t = __builtin_amdgcn_rcpf(1.f + 0.3275911f * ax);
;   const float poly = t * (0.254829592f + t * (-0.284496736f + t * (1.421413741f + t * (-1.453152027f + t * 1.061405429f))));
;   const float y = 1.f - poly * __builtin_amdgcn_exp2f(-1.4426950408889634f * ax * ax);
;   return copysignf(y, x);
; }
; DI float gelu(float x) { return 0.5f * x * (1.f + erf_as(x * 0.70710678118654752f)); }
; DI void vgt_tile(const Ctx& c, int ti, bf16* lds) {
;     ...
;   for (int rr = 0; rr < 32; ++rr) {
;     const int t = wave * 32 + rr;
;     const unsigned u = *(const unsigned*)(c.P() + (size_t)(row0 + t) * LDP + C_V + g * 128 + 2 * lane);
;     const float a = gelu(__uint_as_float(u << 16)), b = gelu(__uint_as_float(u & 0xffff0000u));
;     const float mean = wave_sum(a + b) * (1.f / 128.f);
;     const float da = a - mean, db = b - mean;
;     const float rstd = rsqrtf(wave_sum(da * da + db * db) * (1.f / 128.f) + LN_EPS);
;     lds[(2 * lane) * LDT + t] = f2bf(da * rstd);
;     lds[(2 * lane + 1) * LDT + t] = f2bf(db * rstd);
;   }
	v_lshlrev_b32_e32 v8, 16, v31
	v_mul_f32_e32 v9, 0.5, v8
	v_mul_f32_e32 v8, 0x3f3504f3, v8
	v_fma_f32 v10, |v8|, s2, 1.0
	v_rcp_f32_e32 v10, v10
	v_and_b32_e32 v7, 0xffff0000, v31
	v_fmamk_f32 v11, v10, 0x3f87dc22, v176
	v_fmaak_f32 v11, v10, v11, 0x3fb5f0e3
	v_fmaak_f32 v11, v10, v11, 0xbe91a98e
	v_fmaak_f32 v11, v10, v11, 0x3e827906
	v_mul_f32_e32 v10, v10, v11
	v_mul_f32_e64 v11, |v8|, s3
	v_mul_f32_e64 v11, |v8|, v11
	v_exp_f32_e32 v11, v11
	s_nop 0
	v_fma_f32 v10, -v11, v10, 1.0
	v_bfi_b32 v8, s13, v10, v8
	v_mul_f32_e32 v10, 0.5, v7
	v_mul_f32_e32 v7, 0x3f3504f3, v7
	v_fma_f32 v11, |v7|, s2, 1.0
	v_rcp_f32_e32 v11, v11
	v_add_f32_e32 v8, 1.0, v8
	v_fmamk_f32 v12, v11, 0x3f87dc22, v176
	v_fmaak_f32 v12, v11, v12, 0x3fb5f0e3
	v_fmaak_f32 v12, v11, v12, 0xbe91a98e
	v_fmaak_f32 v12, v11, v12, 0x3e827906
	v_mul_f32_e32 v11, v11, v12
	v_mul_f32_e64 v12, |v7|, s3
	v_mul_f32_e64 v12, |v7|, v12
	v_exp_f32_e32 v12, v12
	s_nop 0
	v_fma_f32 v11, -v12, v11, 1.0
	v_bfi_b32 v7, s13, v11, v7
	v_add_f32_e32 v7, 1.0, v7
	v_mul_f32_e32 v11, v10, v7
	v_fmac_f32_e32 v11, v9, v8
	s_nop 1
	v_add_f32_dpp v11, v11, v11 row_ror:8 row_mask:0xf bank_mask:0xf bound_ctrl:1
	s_nop 1
	v_add_f32_dpp v11, v11, v11 row_ror:4 row_mask:0xf bank_mask:0xf bound_ctrl:1
	s_nop 1
	v_add_f32_dpp v11, v11, v11 row_ror:2 row_mask:0xf bank_mask:0xf bound_ctrl:1
	s_nop 1
	v_add_f32_dpp v11, v11, v11 row_ror:1 row_mask:0xf bank_mask:0xf bound_ctrl:1
	ds_bpermute_b32 v12, v3, v11
	s_waitcnt lgkmcnt(0)
	v_add_f32_e32 v11, v11, v12
	v_mov_b32_e32 v12, v11
	s_nop 1
	v_permlane32_swap_b32_e32 v11, v12
	v_add_f32_e32 v11, v11, v12
	v_mul_f32_e32 v11, 0x3c000000, v11
	v_fma_f32 v7, v10, v7, -v11
	v_fma_f32 v8, v9, v8, -v11
	v_mul_f32_e32 v9, v7, v7
	v_fmac_f32_e32 v9, v8, v8
	s_nop 1
	v_add_f32_dpp v9, v9, v9 row_ror:8 row_mask:0xf bank_mask:0xf bound_ctrl:1
	s_nop 1
	v_add_f32_dpp v9, v9, v9 row_ror:4 row_mask:0xf bank_mask:0xf bound_ctrl:1
	s_nop 1
	v_add_f32_dpp v9, v9, v9 row_ror:2 row_mask:0xf bank_mask:0xf bound_ctrl:1
	s_nop 1
	v_add_f32_dpp v9, v9, v9 row_ror:1 row_mask:0xf bank_mask:0xf bound_ctrl:1
	ds_bpermute_b32 v10, v3, v9
	s_waitcnt lgkmcnt(0)
	v_add_f32_e32 v9, v9, v10
	v_mov_b32_e32 v10, v9
	s_nop 1
	v_permlane32_swap_b32_e32 v9, v10
	v_add_f32_e32 v9, v9, v10
	v_fmamk_f32 v9, v9, 0x3c000000, v177
	v_cmp_gt_f32_e32 vcc, s16, v9
	v_mul_f32_e32 v10, 0x4b800000, v9
	s_nop 0
	v_cndmask_b32_e32 v9, v9, v10, vcc
	v_rsq_f32_e32 v9, v9
	s_nop 0
	v_mul_f32_e32 v10, 0x45800000, v9
	v_cndmask_b32_e32 v9, v9, v10, vcc
	v_mul_f32_e32 v8, v8, v9
	v_bfe_u32 v10, v8, 16, 1
	v_add3_u32 v8, v8, v10, s83
	v_add_u32_e32 v10, s5, v6
	v_mul_f32_e32 v7, v7, v9
	ds_write_b16_d16_hi v10, v8
	v_bfe_u32 v8, v7, 16, 1
	s_add_i32 s5, s5, 2
	v_add3_u32 v7, v7, v8, s83
	ds_write_b16_d16_hi v10, v7 offset:272
	s_waitcnt vmcnt(19)
	v_lshlrev_b32_e32 v8, 16, v32
	v_mul_f32_e32 v9, 0.5, v8
	v_mul_f32_e32 v8, 0x3f3504f3, v8
	v_fma_f32 v10, |v8|, s2, 1.0
	v_rcp_f32_e32 v10, v10
	v_and_b32_e32 v7, 0xffff0000, v32
	v_fmamk_f32 v11, v10, 0x3f87dc22, v176
	v_fmaak_f32 v11, v10, v11, 0x3fb5f0e3
	v_fmaak_f32 v11, v10, v11, 0xbe91a98e
	v_fmaak_f32 v11, v10, v11, 0x3e827906
	v_mul_f32_e32 v10, v10, v11
	v_mul_f32_e64 v11, |v8|, s3
	v_mul_f32_e64 v11, |v8|, v11
	v_exp_f32_e32 v11, v11
	s_nop 0
	v_fma_f32 v10, -v11, v10, 1.0
	v_bfi_b32 v8, s13, v10, v8
	v_mul_f32_e32 v10, 0.5, v7
	v_mul_f32_e32 v7, 0x3f3504f3, v7
	v_fma_f32 v11, |v7|, s2, 1.0
	v_rcp_f32_e32 v11, v11
	v_add_f32_e32 v8, 1.0, v8
	v_fmamk_f32 v12, v11, 0x3f87dc22, v176
	v_fmaak_f32 v12, v11, v12, 0x3fb5f0e3
	v_fmaak_f32 v12, v11, v12, 0xbe91a98e
	v_fmaak_f32 v12, v11, v12, 0x3e827906
	v_mul_f32_e32 v11, v11, v12
	v_mul_f32_e64 v12, |v7|, s3
	v_mul_f32_e64 v12, |v7|, v12
	v_exp_f32_e32 v12, v12
	s_nop 0
	v_fma_f32 v11, -v12, v11, 1.0
	v_bfi_b32 v7, s13, v11, v7
	v_add_f32_e32 v7, 1.0, v7
	v_mul_f32_e32 v11, v10, v7
	v_fmac_f32_e32 v11, v9, v8
	s_nop 1
	v_add_f32_dpp v11, v11, v11 row_ror:8 row_mask:0xf bank_mask:0xf bound_ctrl:1
	s_nop 1
	v_add_f32_dpp v11, v11, v11 row_ror:4 row_mask:0xf bank_mask:0xf bound_ctrl:1
	s_nop 1
	v_add_f32_dpp v11, v11, v11 row_ror:2 row_mask:0xf bank_mask:0xf bound_ctrl:1
	s_nop 1
	v_add_f32_dpp v11, v11, v11 row_ror:1 row_mask:0xf bank_mask:0xf bound_ctrl:1
	ds_bpermute_b32 v12, v3, v11
	s_waitcnt lgkmcnt(0)
	v_add_f32_e32 v11, v11, v12
	v_mov_b32_e32 v12, v11
	s_nop 1
	v_permlane32_swap_b32_e32 v11, v12
	v_add_f32_e32 v11, v11, v12
	v_mul_f32_e32 v11, 0x3c000000, v11
	v_fma_f32 v7, v10, v7, -v11
	v_fma_f32 v8, v9, v8, -v11
	v_mul_f32_e32 v9, v7, v7
	v_fmac_f32_e32 v9, v8, v8
	s_nop 1
	v_add_f32_dpp v9, v9, v9 row_ror:8 row_mask:0xf bank_mask:0xf bound_ctrl:1
	s_nop 1
	v_add_f32_dpp v9, v9, v9 row_ror:4 row_mask:0xf bank_mask:0xf bound_ctrl:1
	s_nop 1
	v_add_f32_dpp v9, v9, v9 row_ror:2 row_mask:0xf bank_mask:0xf bound_ctrl:1
	s_nop 1
	v_add_f32_dpp v9, v9, v9 row_ror:1 row_mask:0xf bank_mask:0xf bound_ctrl:1
	ds_bpermute_b32 v10, v3, v9
	s_waitcnt lgkmcnt(0)
	v_add_f32_e32 v9, v9, v10
	v_mov_b32_e32 v10, v9
	s_nop 1
	v_permlane32_swap_b32_e32 v9, v10
	v_add_f32_e32 v9, v9, v10
	v_fmamk_f32 v9, v9, 0x3c000000, v177
	v_cmp_gt_f32_e32 vcc, s16, v9
	v_mul_f32_e32 v10, 0x4b800000, v9
	s_nop 0
	v_cndmask_b32_e32 v9, v9, v10, vcc
	v_rsq_f32_e32 v9, v9
	s_nop 0
	v_mul_f32_e32 v10, 0x45800000, v9
	v_cndmask_b32_e32 v9, v9, v10, vcc
	v_mul_f32_e32 v8, v8, v9
	v_bfe_u32 v10, v8, 16, 1
	v_add3_u32 v8, v8, v10, s83
	v_add_u32_e32 v10, s5, v6
	v_mul_f32_e32 v7, v7, v9
	ds_write_b16_d16_hi v10, v8
	v_bfe_u32 v8, v7, 16, 1
	s_add_i32 s5, s5, 2
	v_add3_u32 v7, v7, v8, s83
	ds_write_b16_d16_hi v10, v7 offset:272
	s_waitcnt vmcnt(18)
; DI bf16 f2bf(float f) { unsigned u = __float_as_uint(f); u += 0x7fffu + ((u >> 16) & 1u); return (bf16)(u >> 16); }
;   DI bf16* P() const { return (bf16*)(p.ws + WS_P); }
; DI float erf_as(float x) {
;   const float ax = fabsf(x);
;   const float t = __builtin_amdgcn_rcpf(1.f + 0.3275911f * ax);
;   const float poly = t * (0.254829592f + t * (-0.284496736f + t * (1.421413741f + t * (-1.453152027f + t * 1.061405429f))));
;   const float y = 1.f - poly * __builtin_amdgcn_exp2f(-1.4426950408889634f * ax * ax);
;   return copysignf(y, x);
; }
; DI float gelu(float x) { return 0.5f * x * (1.f + erf_as(x * 0.70710678118654752f)); }
; DI void vgt_tile(const Ctx& c, int ti, bf16* lds) {
;     ...
;   for (int rr = 0; rr < 32; ++rr) {
;     const int t = wave * 32 + rr;
;     const unsigned u = *(const unsigned*)(c.P() + (size_t)(row0 + t) * LDP + C_V + g * 128 + 2 * lane);
;     const float a = gelu(__uint_as_float(u << 16)), b = gelu(__uint_as_float(u & 0xffff0000u));
;     const float mean = wave_sum(a + b) * (1.f / 128.f);
;     const float da = a - mean, db = b - mean;
;     const float rstd = rsqrtf(wave_sum(da * da + db * db) * (1.f / 128.f) + LN_EPS);
;     lds[(2 * lane) * LDT + t] = f2bf(da * rstd);
;     lds[(2 * lane + 1) * LDT + t] = f2bf(db * rstd);
;   }
	v_lshlrev_b32_e32 v8, 16, v33
	v_mul_f32_e32 v9, 0.5, v8
	v_mul_f32_e32 v8, 0x3f3504f3, v8
	v_fma_f32 v10, |v8|, s2, 1.0
	v_rcp_f32_e32 v10, v10
	v_and_b32_e32 v7, 0xffff0000, v33
	v_fmamk_f32 v11, v10, 0x3f87dc22, v176
	v_fmaak_f32 v11, v10, v11, 0x3fb5f0e3
	v_fmaak_f32 v11, v10, v11, 0xbe91a98e
	v_fmaak_f32 v11, v10, v11, 0x3e827906
	v_mul_f32_e32 v10, v10, v11
	v_mul_f32_e64 v11, |v8|, s3
	v_mul_f32_e64 v11, |v8|, v11
	v_exp_f32_e32 v11, v11
	s_nop 0
	v_fma_f32 v10, -v11, v10, 1.0
	v_bfi_b32 v8, s13, v10, v8
	v_mul_f32_e32 v10, 0.5, v7
	v_mul_f32_e32 v7, 0x3f3504f3, v7
	v_fma_f32 v11, |v7|, s2, 1.0
	v_rcp_f32_e32 v11, v11
	v_add_f32_e32 v8, 1.0, v8
	v_fmamk_f32 v12, v11, 0x3f87dc22, v176
	v_fmaak_f32 v12, v11, v12, 0x3fb5f0e3
	v_fmaak_f32 v12, v11, v12, 0xbe91a98e
	v_fmaak_f32 v12, v11, v12, 0x3e827906
	v_mul_f32_e32 v11, v11, v12
	v_mul_f32_e64 v12, |v7|, s3
	v_mul_f32_e64 v12, |v7|, v12
	v_exp_f32_e32 v12, v12
	s_nop 0
	v_fma_f32 v11, -v12, v11, 1.0
	v_bfi_b32 v7, s13, v11, v7
	v_add_f32_e32 v7, 1.0, v7
	v_mul_f32_e32 v11, v10, v7
	v_fmac_f32_e32 v11, v9, v8
	s_nop 1
	v_add_f32_dpp v11, v11, v11 row_ror:8 row_mask:0xf bank_mask:0xf bound_ctrl:1
	s_nop 1
	v_add_f32_dpp v11, v11, v11 row_ror:4 row_mask:0xf bank_mask:0xf bound_ctrl:1
	s_nop 1
	v_add_f32_dpp v11, v11, v11 row_ror:2 row_mask:0xf bank_mask:0xf bound_ctrl:1
	s_nop 1
	v_add_f32_dpp v11, v11, v11 row_ror:1 row_mask:0xf bank_mask:0xf bound_ctrl:1
	ds_bpermute_b32 v12, v3, v11
	s_waitcnt lgkmcnt(0)
	v_add_f32_e32 v11, v11, v12
	v_mov_b32_e32 v12, v11
	s_nop 1
	v_permlane32_swap_b32_e32 v11, v12
	v_add_f32_e32 v11, v11, v12
	v_mul_f32_e32 v11, 0x3c000000, v11
	v_fma_f32 v7, v10, v7, -v11
	v_fma_f32 v8, v9, v8, -v11
	v_mul_f32_e32 v9, v7, v7
	v_fmac_f32_e32 v9, v8, v8
	s_nop 1
	v_add_f32_dpp v9, v9, v9 row_ror:8 row_mask:0xf bank_mask:0xf bound_ctrl:1
	s_nop 1
	v_add_f32_dpp v9, v9, v9 row_ror:4 row_mask:0xf bank_mask:0xf bound_ctrl:1
	s_nop 1
	v_add_f32_dpp v9, v9, v9 row_ror:2 row_mask:0xf bank_mask:0xf bound_ctrl:1
	s_nop 1
	v_add_f32_dpp v9, v9, v9 row_ror:1 row_mask:0xf bank_mask:0xf bound_ctrl:1
	ds_bpermute_b32 v10, v3, v9
	s_waitcnt lgkmcnt(0)
	v_add_f32_e32 v9, v9, v10
	v_mov_b32_e32 v10, v9
	s_nop 1
	v_permlane32_swap_b32_e32 v9, v10
	v_add_f32_e32 v9, v9, v10
	v_fmamk_f32 v9, v9, 0x3c000000, v177
	v_cmp_gt_f32_e32 vcc, s16, v9
	v_mul_f32_e32 v10, 0x4b800000, v9
	s_nop 0
	v_cndmask_b32_e32 v9, v9, v10, vcc
	v_rsq_f32_e32 v9, v9
	s_nop 0
	v_mul_f32_e32 v10, 0x45800000, v9
	v_cndmask_b32_e32 v9, v9, v10, vcc
	v_mul_f32_e32 v8, v8, v9
	v_bfe_u32 v10, v8, 16, 1
	v_add3_u32 v8, v8, v10, s83
	v_add_u32_e32 v10, s5, v6
	v_mul_f32_e32 v7, v7, v9
	ds_write_b16_d16_hi v10, v8
	v_bfe_u32 v8, v7, 16, 1
	s_add_i32 s5, s5, 2
	v_add3_u32 v7, v7, v8, s83
	ds_write_b16_d16_hi v10, v7 offset:272
	s_waitcnt vmcnt(17)
	v_lshlrev_b32_e32 v8, 16, v34
	v_mul_f32_e32 v9, 0.5, v8
	v_mul_f32_e32 v8, 0x3f3504f3, v8
	v_fma_f32 v10, |v8|, s2, 1.0
	v_rcp_f32_e32 v10, v10
	v_and_b32_e32 v7, 0xffff0000, v34
	v_fmamk_f32 v11, v10, 0x3f87dc22, v176
	v_fmaak_f32 v11, v10, v11, 0x3fb5f0e3
	v_fmaak_f32 v11, v10, v11, 0xbe91a98e
	v_fmaak_f32 v11, v10, v11, 0x3e827906
	v_mul_f32_e32 v10, v10, v11
	v_mul_f32_e64 v11, |v8|, s3
	v_mul_f32_e64 v11, |v8|, v11
	v_exp_f32_e32 v11, v11
	s_nop 0
	v_fma_f32 v10, -v11, v10, 1.0
	v_bfi_b32 v8, s13, v10, v8
	v_mul_f32_e32 v10, 0.5, v7
	v_mul_f32_e32 v7, 0x3f3504f3, v7
	v_fma_f32 v11, |v7|, s2, 1.0
	v_rcp_f32_e32 v11, v11
	v_add_f32_e32 v8, 1.0, v8
	v_fmamk_f32 v12, v11, 0x3f87dc22, v176
	v_fmaak_f32 v12, v11, v12, 0x3fb5f0e3
	v_fmaak_f32 v12, v11, v12, 0xbe91a98e
	v_fmaak_f32 v12, v11, v12, 0x3e827906
	v_mul_f32_e32 v11, v11, v12
	v_mul_f32_e64 v12, |v7|, s3
	v_mul_f32_e64 v12, |v7|, v12
	v_exp_f32_e32 v12, v12
	s_nop 0
	v_fma_f32 v11, -v12, v11, 1.0
	v_bfi_b32 v7, s13, v11, v7
	v_add_f32_e32 v7, 1.0, v7
	v_mul_f32_e32 v11, v10, v7
	v_fmac_f32_e32 v11, v9, v8
	s_nop 1
	v_add_f32_dpp v11, v11, v11 row_ror:8 row_mask:0xf bank_mask:0xf bound_ctrl:1
	s_nop 1
	v_add_f32_dpp v11, v11, v11 row_ror:4 row_mask:0xf bank_mask:0xf bound_ctrl:1
	s_nop 1
	v_add_f32_dpp v11, v11, v11 row_ror:2 row_mask:0xf bank_mask:0xf bound_ctrl:1
	s_nop 1
	v_add_f32_dpp v11, v11, v11 row_ror:1 row_mask:0xf bank_mask:0xf bound_ctrl:1
	ds_bpermute_b32 v12, v3, v11
	s_waitcnt lgkmcnt(0)
	v_add_f32_e32 v11, v11, v12
	v_mov_b32_e32 v12, v11
	s_nop 1
	v_permlane32_swap_b32_e32 v11, v12
	v_add_f32_e32 v11, v11, v12
	v_mul_f32_e32 v11, 0x3c000000, v11
	v_fma_f32 v7, v10, v7, -v11
	v_fma_f32 v8, v9, v8, -v11
	v_mul_f32_e32 v9, v7, v7
	v_fmac_f32_e32 v9, v8, v8
	s_nop 1
	v_add_f32_dpp v9, v9, v9 row_ror:8 row_mask:0xf bank_mask:0xf bound_ctrl:1
	s_nop 1
	v_add_f32_dpp v9, v9, v9 row_ror:4 row_mask:0xf bank_mask:0xf bound_ctrl:1
	s_nop 1
	v_add_f32_dpp v9, v9, v9 row_ror:2 row_mask:0xf bank_mask:0xf bound_ctrl:1
	s_nop 1
	v_add_f32_dpp v9, v9, v9 row_ror:1 row_mask:0xf bank_mask:0xf bound_ctrl:1
	ds_bpermute_b32 v10, v3, v9
	s_waitcnt lgkmcnt(0)
	v_add_f32_e32 v9, v9, v10
	v_mov_b32_e32 v10, v9
	s_nop 1
	v_permlane32_swap_b32_e32 v9, v10
	v_add_f32_e32 v9, v9, v10
	v_fmamk_f32 v9, v9, 0x3c000000, v177
	v_cmp_gt_f32_e32 vcc, s16, v9
	v_mul_f32_e32 v10, 0x4b800000, v9
	s_nop 0
	v_cndmask_b32_e32 v9, v9, v10, vcc
	v_rsq_f32_e32 v9, v9
	s_nop 0
	v_mul_f32_e32 v10, 0x45800000, v9
	v_cndmask_b32_e32 v9, v9, v10, vcc
	v_mul_f32_e32 v8, v8, v9
	v_bfe_u32 v10, v8, 16, 1
	v_add3_u32 v8, v8, v10, s83
	v_add_u32_e32 v10, s5, v6
	v_mul_f32_e32 v7, v7, v9
	ds_write_b16_d16_hi v10, v8
	v_bfe_u32 v8, v7, 16, 1
	s_add_i32 s5, s5, 2
	v_add3_u32 v7, v7, v8, s83
	ds_write_b16_d16_hi v10, v7 offset:272
	s_waitcnt vmcnt(16)
; DI bf16 f2bf(float f) { unsigned u = __float_as_uint(f); u += 0x7fffu + ((u >> 16) & 1u); return (bf16)(u >> 16); }
;   DI bf16* P() const { return (bf16*)(p.ws + WS_P); }
; DI float erf_as(float x) {
;   const float ax = fabsf(x);
;   const float t = __builtin_amdgcn_rcpf(1.f + 0.3275911f * ax);
;   const float poly = t * (0.254829592f + t * (-0.284496736f + t * (1.421413741f + t * (-1.453152027f + t * 1.061405429f))));
;   const float y = 1.f - poly * __builtin_amdgcn_exp2f(-1.4426950408889634f * ax * ax);
;   return copysignf(y, x);
; }
; DI float gelu(float x) { return 0.5f * x * (1.f + erf_as(x * 0.70710678118654752f)); }
; DI void vgt_tile(const Ctx& c, int ti, bf16* lds) {
;     ...
;   for (int rr = 0; rr < 32; ++rr) {
;     const int t = wave * 32 + rr;
;     const unsigned u = *(const unsigned*)(c.P() + (size_t)(row0 + t) * LDP + C_V + g * 128 + 2 * lane);
;     const float a = gelu(__uint_as_float(u << 16)), b = gelu(__uint_as_float(u & 0xffff0000u));
;     const float mean = wave_sum(a + b) * (1.f / 128.f);
;     const float da = a - mean, db = b - mean;
;     const float rstd = rsqrtf(wave_sum(da * da + db * db) * (1.f / 128.f) + LN_EPS);
;     lds[(2 * lane) * LDT + t] = f2bf(da * rstd);
;     lds[(2 * lane + 1) * LDT + t] = f2bf(db * rstd);
;   }
	v_lshlrev_b32_e32 v8, 16, v35
	v_mul_f32_e32 v9, 0.5, v8
	v_mul_f32_e32 v8, 0x3f3504f3, v8
	v_fma_f32 v10, |v8|, s2, 1.0
	v_rcp_f32_e32 v10, v10
	v_and_b32_e32 v7, 0xffff0000, v35
	v_fmamk_f32 v11, v10, 0x3f87dc22, v176
	v_fmaak_f32 v11, v10, v11, 0x3fb5f0e3
	v_fmaak_f32 v11, v10, v11, 0xbe91a98e
	v_fmaak_f32 v11, v10, v11, 0x3e827906
	v_mul_f32_e32 v10, v10, v11
	v_mul_f32_e64 v11, |v8|, s3
	v_mul_f32_e64 v11, |v8|, v11
	v_exp_f32_e32 v11, v11
	s_nop 0
	v_fma_f32 v10, -v11, v10, 1.0
	v_bfi_b32 v8, s13, v10, v8
	v_mul_f32_e32 v10, 0.5, v7
	v_mul_f32_e32 v7, 0x3f3504f3, v7
	v_fma_f32 v11, |v7|, s2, 1.0
	v_rcp_f32_e32 v11, v11
	v_add_f32_e32 v8, 1.0, v8
	v_fmamk_f32 v12, v11, 0x3f87dc22, v176
	v_fmaak_f32 v12, v11, v12, 0x3fb5f0e3
	v_fmaak_f32 v12, v11, v12, 0xbe91a98e
	v_fmaak_f32 v12, v11, v12, 0x3e827906
	v_mul_f32_e32 v11, v11, v12
	v_mul_f32_e64 v12, |v7|, s3
	v_mul_f32_e64 v12, |v7|, v12
	v_exp_f32_e32 v12, v12
	s_nop 0
	v_fma_f32 v11, -v12, v11, 1.0
	v_bfi_b32 v7, s13, v11, v7
	v_add_f32_e32 v7, 1.0, v7
	v_mul_f32_e32 v11, v10, v7
	v_fmac_f32_e32 v11, v9, v8
	s_nop 1
	v_add_f32_dpp v11, v11, v11 row_ror:8 row_mask:0xf bank_mask:0xf bound_ctrl:1
	s_nop 1
	v_add_f32_dpp v11, v11, v11 row_ror:4 row_mask:0xf bank_mask:0xf bound_ctrl:1
	s_nop 1
	v_add_f32_dpp v11, v11, v11 row_ror:2 row_mask:0xf bank_mask:0xf bound_ctrl:1
	s_nop 1
	v_add_f32_dpp v11, v11, v11 row_ror:1 row_mask:0xf bank_mask:0xf bound_ctrl:1
	ds_bpermute_b32 v12, v3, v11
	s_waitcnt lgkmcnt(0)
	v_add_f32_e32 v11, v11, v12
	v_mov_b32_e32 v12, v11
	s_nop 1
	v_permlane32_swap_b32_e32 v11, v12
	v_add_f32_e32 v11, v11, v12
	v_mul_f32_e32 v11, 0x3c000000, v11
	v_fma_f32 v7, v10, v7, -v11
	v_fma_f32 v8, v9, v8, -v11
	v_mul_f32_e32 v9, v7, v7
	v_fmac_f32_e32 v9, v8, v8
	s_nop 1
	v_add_f32_dpp v9, v9, v9 row_ror:8 row_mask:0xf bank_mask:0xf bound_ctrl:1
	s_nop 1
	v_add_f32_dpp v9, v9, v9 row_ror:4 row_mask:0xf bank_mask:0xf bound_ctrl:1
	s_nop 1
	v_add_f32_dpp v9, v9, v9 row_ror:2 row_mask:0xf bank_mask:0xf bound_ctrl:1
	s_nop 1
	v_add_f32_dpp v9, v9, v9 row_ror:1 row_mask:0xf bank_mask:0xf bound_ctrl:1
	ds_bpermute_b32 v10, v3, v9
	s_waitcnt lgkmcnt(0)
	v_add_f32_e32 v9, v9, v10
	v_mov_b32_e32 v10, v9
	s_nop 1
	v_permlane32_swap_b32_e32 v9, v10
	v_add_f32_e32 v9, v9, v10
	v_fmamk_f32 v9, v9, 0x3c000000, v177
	v_cmp_gt_f32_e32 vcc, s16, v9
	v_mul_f32_e32 v10, 0x4b800000, v9
	s_nop 0
	v_cndmask_b32_e32 v9, v9, v10, vcc
	v_rsq_f32_e32 v9, v9
	s_nop 0
	v_mul_f32_e32 v10, 0x45800000, v9
	v_cndmask_b32_e32 v9, v9, v10, vcc
	v_mul_f32_e32 v8, v8, v9
	v_bfe_u32 v10, v8, 16, 1
	v_add3_u32 v8, v8, v10, s83
	v_add_u32_e32 v10, s5, v6
	v_mul_f32_e32 v7, v7, v9
	ds_write_b16_d16_hi v10, v8
	v_bfe_u32 v8, v7, 16, 1
	s_add_i32 s5, s5, 2
	v_add3_u32 v7, v7, v8, s83
	ds_write_b16_d16_hi v10, v7 offset:272
	s_waitcnt vmcnt(15)
	v_lshlrev_b32_e32 v8, 16, v36
	v_mul_f32_e32 v9, 0.5, v8
	v_mul_f32_e32 v8, 0x3f3504f3, v8
	v_fma_f32 v10, |v8|, s2, 1.0
	v_rcp_f32_e32 v10, v10
	v_and_b32_e32 v7, 0xffff0000, v36
	v_fmamk_f32 v11, v10, 0x3f87dc22, v176
	v_fmaak_f32 v11, v10, v11, 0x3fb5f0e3
	v_fmaak_f32 v11, v10, v11, 0xbe91a98e
	v_fmaak_f32 v11, v10, v11, 0x3e827906
	v_mul_f32_e32 v10, v10, v11
	v_mul_f32_e64 v11, |v8|, s3
	v_mul_f32_e64 v11, |v8|, v11
	v_exp_f32_e32 v11, v11
	s_nop 0
	v_fma_f32 v10, -v11, v10, 1.0
	v_bfi_b32 v8, s13, v10, v8
	v_mul_f32_e32 v10, 0.5, v7
	v_mul_f32_e32 v7, 0x3f3504f3, v7
	v_fma_f32 v11, |v7|, s2, 1.0
	v_rcp_f32_e32 v11, v11
	v_add_f32_e32 v8, 1.0, v8
	v_fmamk_f32 v12, v11, 0x3f87dc22, v176
	v_fmaak_f32 v12, v11, v12, 0x3fb5f0e3
	v_fmaak_f32 v12, v11, v12, 0xbe91a98e
	v_fmaak_f32 v12, v11, v12, 0x3e827906
	v_mul_f32_e32 v11, v11, v12
	v_mul_f32_e64 v12, |v7|, s3
	v_mul_f32_e64 v12, |v7|, v12
	v_exp_f32_e32 v12, v12
	s_nop 0
	v_fma_f32 v11, -v12, v11, 1.0
	v_bfi_b32 v7, s13, v11, v7
	v_add_f32_e32 v7, 1.0, v7
	v_mul_f32_e32 v11, v10, v7
	v_fmac_f32_e32 v11, v9, v8
	s_nop 1
	v_add_f32_dpp v11, v11, v11 row_ror:8 row_mask:0xf bank_mask:0xf bound_ctrl:1
	s_nop 1
	v_add_f32_dpp v11, v11, v11 row_ror:4 row_mask:0xf bank_mask:0xf bound_ctrl:1
	s_nop 1
	v_add_f32_dpp v11, v11, v11 row_ror:2 row_mask:0xf bank_mask:0xf bound_ctrl:1
	s_nop 1
	v_add_f32_dpp v11, v11, v11 row_ror:1 row_mask:0xf bank_mask:0xf bound_ctrl:1
	ds_bpermute_b32 v12, v3, v11
	s_waitcnt lgkmcnt(0)
	v_add_f32_e32 v11, v11, v12
	v_mov_b32_e32 v12, v11
	s_nop 1
	v_permlane32_swap_b32_e32 v11, v12
	v_add_f32_e32 v11, v11, v12
	v_mul_f32_e32 v11, 0x3c000000, v11
	v_fma_f32 v7, v10, v7, -v11
	v_fma_f32 v8, v9, v8, -v11
	v_mul_f32_e32 v9, v7, v7
	v_fmac_f32_e32 v9, v8, v8
	s_nop 1
	v_add_f32_dpp v9, v9, v9 row_ror:8 row_mask:0xf bank_mask:0xf bound_ctrl:1
	s_nop 1
	v_add_f32_dpp v9, v9, v9 row_ror:4 row_mask:0xf bank_mask:0xf bound_ctrl:1
	s_nop 1
	v_add_f32_dpp v9, v9, v9 row_ror:2 row_mask:0xf bank_mask:0xf bound_ctrl:1
	s_nop 1
	v_add_f32_dpp v9, v9, v9 row_ror:1 row_mask:0xf bank_mask:0xf bound_ctrl:1
	ds_bpermute_b32 v10, v3, v9
	s_waitcnt lgkmcnt(0)
	v_add_f32_e32 v9, v9, v10
	v_mov_b32_e32 v10, v9
	s_nop 1
	v_permlane32_swap_b32_e32 v9, v10
	v_add_f32_e32 v9, v9, v10
	v_fmamk_f32 v9, v9, 0x3c000000, v177
	v_cmp_gt_f32_e32 vcc, s16, v9
	v_mul_f32_e32 v10, 0x4b800000, v9
	s_nop 0
	v_cndmask_b32_e32 v9, v9, v10, vcc
	v_rsq_f32_e32 v9, v9
	s_nop 0
	v_mul_f32_e32 v10, 0x45800000, v9
	v_cndmask_b32_e32 v9, v9, v10, vcc
	v_mul_f32_e32 v8, v8, v9
	v_bfe_u32 v10, v8, 16, 1
	v_add3_u32 v8, v8, v10, s83
	v_add_u32_e32 v10, s5, v6
	v_mul_f32_e32 v7, v7, v9
	ds_write_b16_d16_hi v10, v8
	v_bfe_u32 v8, v7, 16, 1
	s_add_i32 s5, s5, 2
	v_add3_u32 v7, v7, v8, s83
	ds_write_b16_d16_hi v10, v7 offset:272
	s_waitcnt vmcnt(14)
; DI bf16 f2bf(float f) { unsigned u = __float_as_uint(f); u += 0x7fffu + ((u >> 16) & 1u); return (bf16)(u >> 16); }
;   DI bf16* P() const { return (bf16*)(p.ws + WS_P); }
; DI float erf_as(float x) {
;   const float ax = fabsf(x);
;   const float t = __builtin_amdgcn_rcpf(1.f + 0.3275911f * ax);
;   const float poly = t * (0.254829592f + t * (-0.284496736f + t * (1.421413741f + t * (-1.453152027f + t * 1.061405429f))));
;   const float y = 1.f - poly * __builtin_amdgcn_exp2f(-1.4426950408889634f * ax * ax);
;   return copysignf(y, x);
; }
; DI float gelu(float x) { return 0.5f * x * (1.f + erf_as(x * 0.70710678118654752f)); }
; DI void vgt_tile(const Ctx& c, int ti, bf16* lds) {
;     ...
;   for (int rr = 0; rr < 32; ++rr) {
;     const int t = wave * 32 + rr;
;     const unsigned u = *(const unsigned*)(c.P() + (size_t)(row0 + t) * LDP + C_V + g * 128 + 2 * lane);
;     const float a = gelu(__uint_as_float(u << 16)), b = gelu(__uint_as_float(u & 0xffff0000u));
;     const float mean = wave_sum(a + b) * (1.f / 128.f);
;     const float da = a - mean, db = b - mean;
;     const float rstd = rsqrtf(wave_sum(da * da + db * db) * (1.f / 128.f) + LN_EPS);
;     lds[(2 * lane) * LDT + t] = f2bf(da * rstd);
;     lds[(2 * lane + 1) * LDT + t] = f2bf(db * rstd);
;   }
	v_lshlrev_b32_e32 v8, 16, v37
	v_mul_f32_e32 v9, 0.5, v8
	v_mul_f32_e32 v8, 0x3f3504f3, v8
	v_fma_f32 v10, |v8|, s2, 1.0
	v_rcp_f32_e32 v10, v10
	v_and_b32_e32 v7, 0xffff0000, v37
	v_fmamk_f32 v11, v10, 0x3f87dc22, v176
	v_fmaak_f32 v11, v10, v11, 0x3fb5f0e3
	v_fmaak_f32 v11, v10, v11, 0xbe91a98e
	v_fmaak_f32 v11, v10, v11, 0x3e827906
	v_mul_f32_e32 v10, v10, v11
	v_mul_f32_e64 v11, |v8|, s3
	v_mul_f32_e64 v11, |v8|, v11
	v_exp_f32_e32 v11, v11
	s_nop 0
	v_fma_f32 v10, -v11, v10, 1.0
	v_bfi_b32 v8, s13, v10, v8
	v_mul_f32_e32 v10, 0.5, v7
	v_mul_f32_e32 v7, 0x3f3504f3, v7
	v_fma_f32 v11, |v7|, s2, 1.0
	v_rcp_f32_e32 v11, v11
	v_add_f32_e32 v8, 1.0, v8
	v_fmamk_f32 v12, v11, 0x3f87dc22, v176
	v_fmaak_f32 v12, v11, v12, 0x3fb5f0e3
	v_fmaak_f32 v12, v11, v12, 0xbe91a98e
	v_fmaak_f32 v12, v11, v12, 0x3e827906
	v_mul_f32_e32 v11, v11, v12
	v_mul_f32_e64 v12, |v7|, s3
	v_mul_f32_e64 v12, |v7|, v12
	v_exp_f32_e32 v12, v12
	s_nop 0
	v_fma_f32 v11, -v12, v11, 1.0
	v_bfi_b32 v7, s13, v11, v7
	v_add_f32_e32 v7, 1.0, v7
	v_mul_f32_e32 v11, v10, v7
	v_fmac_f32_e32 v11, v9, v8
	s_nop 1
	v_add_f32_dpp v11, v11, v11 row_ror:8 row_mask:0xf bank_mask:0xf bound_ctrl:1
	s_nop 1
	v_add_f32_dpp v11, v11, v11 row_ror:4 row_mask:0xf bank_mask:0xf bound_ctrl:1
	s_nop 1
	v_add_f32_dpp v11, v11, v11 row_ror:2 row_mask:0xf bank_mask:0xf bound_ctrl:1
	s_nop 1
	v_add_f32_dpp v11, v11, v11 row_ror:1 row_mask:0xf bank_mask:0xf bound_ctrl:1
	ds_bpermute_b32 v12, v3, v11
	s_waitcnt lgkmcnt(0)
	v_add_f32_e32 v11, v11, v12
	v_mov_b32_e32 v12, v11
	s_nop 1
	v_permlane32_swap_b32_e32 v11, v12
	v_add_f32_e32 v11, v11, v12
	v_mul_f32_e32 v11, 0x3c000000, v11
	v_fma_f32 v7, v10, v7, -v11
	v_fma_f32 v8, v9, v8, -v11
	v_mul_f32_e32 v9, v7, v7
	v_fmac_f32_e32 v9, v8, v8
	s_nop 1
	v_add_f32_dpp v9, v9, v9 row_ror:8 row_mask:0xf bank_mask:0xf bound_ctrl:1
	s_nop 1
	v_add_f32_dpp v9, v9, v9 row_ror:4 row_mask:0xf bank_mask:0xf bound_ctrl:1
	s_nop 1
	v_add_f32_dpp v9, v9, v9 row_ror:2 row_mask:0xf bank_mask:0xf bound_ctrl:1
	s_nop 1
	v_add_f32_dpp v9, v9, v9 row_ror:1 row_mask:0xf bank_mask:0xf bound_ctrl:1
	ds_bpermute_b32 v10, v3, v9
	s_waitcnt lgkmcnt(0)
	v_add_f32_e32 v9, v9, v10
	v_mov_b32_e32 v10, v9
	s_nop 1
	v_permlane32_swap_b32_e32 v9, v10
	v_add_f32_e32 v9, v9, v10
	v_fmamk_f32 v9, v9, 0x3c000000, v177
	v_cmp_gt_f32_e32 vcc, s16, v9
	v_mul_f32_e32 v10, 0x4b800000, v9
	s_nop 0
	v_cndmask_b32_e32 v9, v9, v10, vcc
	v_rsq_f32_e32 v9, v9
	s_nop 0
	v_mul_f32_e32 v10, 0x45800000, v9
	v_cndmask_b32_e32 v9, v9, v10, vcc
	v_mul_f32_e32 v8, v8, v9
	v_bfe_u32 v10, v8, 16, 1
	v_add3_u32 v8, v8, v10, s83
	v_add_u32_e32 v10, s5, v6
	v_mul_f32_e32 v7, v7, v9
	ds_write_b16_d16_hi v10, v8
	v_bfe_u32 v8, v7, 16, 1
	s_add_i32 s5, s5, 2
	v_add3_u32 v7, v7, v8, s83
	ds_write_b16_d16_hi v10, v7 offset:272
	s_waitcnt vmcnt(13)
	v_lshlrev_b32_e32 v8, 16, v38
	v_mul_f32_e32 v9, 0.5, v8
	v_mul_f32_e32 v8, 0x3f3504f3, v8
	v_fma_f32 v10, |v8|, s2, 1.0
	v_rcp_f32_e32 v10, v10
	v_and_b32_e32 v7, 0xffff0000, v38
	v_fmamk_f32 v11, v10, 0x3f87dc22, v176
	v_fmaak_f32 v11, v10, v11, 0x3fb5f0e3
	v_fmaak_f32 v11, v10, v11, 0xbe91a98e
	v_fmaak_f32 v11, v10, v11, 0x3e827906
	v_mul_f32_e32 v10, v10, v11
	v_mul_f32_e64 v11, |v8|, s3
	v_mul_f32_e64 v11, |v8|, v11
	v_exp_f32_e32 v11, v11
	s_nop 0
	v_fma_f32 v10, -v11, v10, 1.0
	v_bfi_b32 v8, s13, v10, v8
	v_mul_f32_e32 v10, 0.5, v7
	v_mul_f32_e32 v7, 0x3f3504f3, v7
	v_fma_f32 v11, |v7|, s2, 1.0
	v_rcp_f32_e32 v11, v11
	v_add_f32_e32 v8, 1.0, v8
	v_fmamk_f32 v12, v11, 0x3f87dc22, v176
	v_fmaak_f32 v12, v11, v12, 0x3fb5f0e3
	v_fmaak_f32 v12, v11, v12, 0xbe91a98e
	v_fmaak_f32 v12, v11, v12, 0x3e827906
	v_mul_f32_e32 v11, v11, v12
	v_mul_f32_e64 v12, |v7|, s3
	v_mul_f32_e64 v12, |v7|, v12
	v_exp_f32_e32 v12, v12
	s_nop 0
	v_fma_f32 v11, -v12, v11, 1.0
	v_bfi_b32 v7, s13, v11, v7
	v_add_f32_e32 v7, 1.0, v7
	v_mul_f32_e32 v11, v10, v7
	v_fmac_f32_e32 v11, v9, v8
	s_nop 1
	v_add_f32_dpp v11, v11, v11 row_ror:8 row_mask:0xf bank_mask:0xf bound_ctrl:1
	s_nop 1
	v_add_f32_dpp v11, v11, v11 row_ror:4 row_mask:0xf bank_mask:0xf bound_ctrl:1
	s_nop 1
	v_add_f32_dpp v11, v11, v11 row_ror:2 row_mask:0xf bank_mask:0xf bound_ctrl:1
	s_nop 1
	v_add_f32_dpp v11, v11, v11 row_ror:1 row_mask:0xf bank_mask:0xf bound_ctrl:1
	ds_bpermute_b32 v12, v3, v11
	s_waitcnt lgkmcnt(0)
	v_add_f32_e32 v11, v11, v12
	v_mov_b32_e32 v12, v11
	s_nop 1
	v_permlane32_swap_b32_e32 v11, v12
	v_add_f32_e32 v11, v11, v12
	v_mul_f32_e32 v11, 0x3c000000, v11
	v_fma_f32 v7, v10, v7, -v11
	v_fma_f32 v8, v9, v8, -v11
	v_mul_f32_e32 v9, v7, v7
	v_fmac_f32_e32 v9, v8, v8
	s_nop 1
	v_add_f32_dpp v9, v9, v9 row_ror:8 row_mask:0xf bank_mask:0xf bound_ctrl:1
	s_nop 1
	v_add_f32_dpp v9, v9, v9 row_ror:4 row_mask:0xf bank_mask:0xf bound_ctrl:1
	s_nop 1
	v_add_f32_dpp v9, v9, v9 row_ror:2 row_mask:0xf bank_mask:0xf bound_ctrl:1
	s_nop 1
	v_add_f32_dpp v9, v9, v9 row_ror:1 row_mask:0xf bank_mask:0xf bound_ctrl:1
	ds_bpermute_b32 v10, v3, v9
	s_waitcnt lgkmcnt(0)
	v_add_f32_e32 v9, v9, v10
	v_mov_b32_e32 v10, v9
	s_nop 1
	v_permlane32_swap_b32_e32 v9, v10
	v_add_f32_e32 v9, v9, v10
	v_fmamk_f32 v9, v9, 0x3c000000, v177
	v_cmp_gt_f32_e32 vcc, s16, v9
	v_mul_f32_e32 v10, 0x4b800000, v9
	s_nop 0
	v_cndmask_b32_e32 v9, v9, v10, vcc
	v_rsq_f32_e32 v9, v9
	s_nop 0
	v_mul_f32_e32 v10, 0x45800000, v9
	v_cndmask_b32_e32 v9, v9, v10, vcc
	v_mul_f32_e32 v8, v8, v9
	v_bfe_u32 v10, v8, 16, 1
	v_add3_u32 v8, v8, v10, s83
	v_add_u32_e32 v10, s5, v6
	v_mul_f32_e32 v7, v7, v9
	ds_write_b16_d16_hi v10, v8
	v_bfe_u32 v8, v7, 16, 1
	s_add_i32 s5, s5, 2
	v_add3_u32 v7, v7, v8, s83
	ds_write_b16_d16_hi v10, v7 offset:272
	s_waitcnt vmcnt(12)
; DI bf16 f2bf(float f) { unsigned u = __float_as_uint(f); u += 0x7fffu + ((u >> 16) & 1u); return (bf16)(u >> 16); }
;   DI bf16* P() const { return (bf16*)(p.ws + WS_P); }
; DI float erf_as(float x) {
;   const float ax = fabsf(x);
;   const float t = __builtin_amdgcn_rcpf(1.f + 0.3275911f * ax);
;   const float poly = t * (0.254829592f + t * (-0.284496736f + t * (1.421413741f + t * (-1.453152027f + t * 1.061405429f))));
;   const float y = 1.f - poly * __builtin_amdgcn_exp2f(-1.4426950408889634f * ax * ax);
;   return copysignf(y, x);
; }
; DI float gelu(float x) { return 0.5f * x * (1.f + erf_as(x * 0.70710678118654752f)); }
; DI void vgt_tile(const Ctx& c, int ti, bf16* lds) {
;     ...
;   for (int rr = 0; rr < 32; ++rr) {
;     const int t = wave * 32 + rr;
;     const unsigned u = *(const unsigned*)(c.P() + (size_t)(row0 + t) * LDP + C_V + g * 128 + 2 * lane);
;     const float a = gelu(__uint_as_float(u << 16)), b = gelu(__uint_as_float(u & 0xffff0000u));
;     const float mean = wave_sum(a + b) * (1.f / 128.f);
;     const float da = a - mean, db = b - mean;
;     const float rstd = rsqrtf(wave_sum(da * da + db * db) * (1.f / 128.f) + LN_EPS);
;     lds[(2 * lane) * LDT + t] = f2bf(da * rstd);
;     lds[(2 * lane + 1) * LDT + t] = f2bf(db * rstd);
;   }
	v_lshlrev_b32_e32 v8, 16, v39
	v_mul_f32_e32 v9, 0.5, v8
	v_mul_f32_e32 v8, 0x3f3504f3, v8
	v_fma_f32 v10, |v8|, s2, 1.0
	v_rcp_f32_e32 v10, v10
	v_and_b32_e32 v7, 0xffff0000, v39
	v_fmamk_f32 v11, v10, 0x3f87dc22, v176
	v_fmaak_f32 v11, v10, v11, 0x3fb5f0e3
	v_fmaak_f32 v11, v10, v11, 0xbe91a98e
	v_fmaak_f32 v11, v10, v11, 0x3e827906
	v_mul_f32_e32 v10, v10, v11
	v_mul_f32_e64 v11, |v8|, s3
	v_mul_f32_e64 v11, |v8|, v11
	v_exp_f32_e32 v11, v11
	s_nop 0
	v_fma_f32 v10, -v11, v10, 1.0
	v_bfi_b32 v8, s13, v10, v8
	v_mul_f32_e32 v10, 0.5, v7
	v_mul_f32_e32 v7, 0x3f3504f3, v7
	v_fma_f32 v11, |v7|, s2, 1.0
	v_rcp_f32_e32 v11, v11
	v_add_f32_e32 v8, 1.0, v8
	v_fmamk_f32 v12, v11, 0x3f87dc22, v176
	v_fmaak_f32 v12, v11, v12, 0x3fb5f0e3
	v_fmaak_f32 v12, v11, v12, 0xbe91a98e
	v_fmaak_f32 v12, v11, v12, 0x3e827906
	v_mul_f32_e32 v11, v11, v12
	v_mul_f32_e64 v12, |v7|, s3
	v_mul_f32_e64 v12, |v7|, v12
	v_exp_f32_e32 v12, v12
	s_nop 0
	v_fma_f32 v11, -v12, v11, 1.0
	v_bfi_b32 v7, s13, v11, v7
	v_add_f32_e32 v7, 1.0, v7
	v_mul_f32_e32 v11, v10, v7
	v_fmac_f32_e32 v11, v9, v8
	s_nop 1
	v_add_f32_dpp v11, v11, v11 row_ror:8 row_mask:0xf bank_mask:0xf bound_ctrl:1
	s_nop 1
	v_add_f32_dpp v11, v11, v11 row_ror:4 row_mask:0xf bank_mask:0xf bound_ctrl:1
	s_nop 1
	v_add_f32_dpp v11, v11, v11 row_ror:2 row_mask:0xf bank_mask:0xf bound_ctrl:1
	s_nop 1
	v_add_f32_dpp v11, v11, v11 row_ror:1 row_mask:0xf bank_mask:0xf bound_ctrl:1
	ds_bpermute_b32 v12, v3, v11
	s_waitcnt lgkmcnt(0)
	v_add_f32_e32 v11, v11, v12
	v_mov_b32_e32 v12, v11
	s_nop 1
	v_permlane32_swap_b32_e32 v11, v12
	v_add_f32_e32 v11, v11, v12
	v_mul_f32_e32 v11, 0x3c000000, v11
	v_fma_f32 v7, v10, v7, -v11
	v_fma_f32 v8, v9, v8, -v11
	v_mul_f32_e32 v9, v7, v7
	v_fmac_f32_e32 v9, v8, v8
	s_nop 1
	v_add_f32_dpp v9, v9, v9 row_ror:8 row_mask:0xf bank_mask:0xf bound_ctrl:1
	s_nop 1
	v_add_f32_dpp v9, v9, v9 row_ror:4 row_mask:0xf bank_mask:0xf bound_ctrl:1
	s_nop 1
	v_add_f32_dpp v9, v9, v9 row_ror:2 row_mask:0xf bank_mask:0xf bound_ctrl:1
	s_nop 1
	v_add_f32_dpp v9, v9, v9 row_ror:1 row_mask:0xf bank_mask:0xf bound_ctrl:1
	ds_bpermute_b32 v10, v3, v9
	s_waitcnt lgkmcnt(0)
	v_add_f32_e32 v9, v9, v10
	v_mov_b32_e32 v10, v9
	s_nop 1
	v_permlane32_swap_b32_e32 v9, v10
	v_add_f32_e32 v9, v9, v10
	v_fmamk_f32 v9, v9, 0x3c000000, v177
	v_cmp_gt_f32_e32 vcc, s16, v9
	v_mul_f32_e32 v10, 0x4b800000, v9
	s_nop 0
	v_cndmask_b32_e32 v9, v9, v10, vcc
	v_rsq_f32_e32 v9, v9
	s_nop 0
	v_mul_f32_e32 v10, 0x45800000, v9
	v_cndmask_b32_e32 v9, v9, v10, vcc
	v_mul_f32_e32 v8, v8, v9
	v_bfe_u32 v10, v8, 16, 1
	v_add3_u32 v8, v8, v10, s83
	v_add_u32_e32 v10, s5, v6
	v_mul_f32_e32 v7, v7, v9
	ds_write_b16_d16_hi v10, v8
	v_bfe_u32 v8, v7, 16, 1
	s_add_i32 s5, s5, 2
	v_add3_u32 v7, v7, v8, s83
	ds_write_b16_d16_hi v10, v7 offset:272
	s_waitcnt vmcnt(11)
	v_lshlrev_b32_e32 v8, 16, v40
	v_mul_f32_e32 v9, 0.5, v8
	v_mul_f32_e32 v8, 0x3f3504f3, v8
	v_fma_f32 v10, |v8|, s2, 1.0
	v_rcp_f32_e32 v10, v10
	v_and_b32_e32 v7, 0xffff0000, v40
	v_fmamk_f32 v11, v10, 0x3f87dc22, v176
	v_fmaak_f32 v11, v10, v11, 0x3fb5f0e3
	v_fmaak_f32 v11, v10, v11, 0xbe91a98e
	v_fmaak_f32 v11, v10, v11, 0x3e827906
	v_mul_f32_e32 v10, v10, v11
	v_mul_f32_e64 v11, |v8|, s3
	v_mul_f32_e64 v11, |v8|, v11
	v_exp_f32_e32 v11, v11
	s_nop 0
	v_fma_f32 v10, -v11, v10, 1.0
	v_bfi_b32 v8, s13, v10, v8
	v_mul_f32_e32 v10, 0.5, v7
	v_mul_f32_e32 v7, 0x3f3504f3, v7
	v_fma_f32 v11, |v7|, s2, 1.0
	v_rcp_f32_e32 v11, v11
	v_add_f32_e32 v8, 1.0, v8
	v_fmamk_f32 v12, v11, 0x3f87dc22, v176
	v_fmaak_f32 v12, v11, v12, 0x3fb5f0e3
	v_fmaak_f32 v12, v11, v12, 0xbe91a98e
	v_fmaak_f32 v12, v11, v12, 0x3e827906
	v_mul_f32_e32 v11, v11, v12
	v_mul_f32_e64 v12, |v7|, s3
	v_mul_f32_e64 v12, |v7|, v12
	v_exp_f32_e32 v12, v12
	s_nop 0
	v_fma_f32 v11, -v12, v11, 1.0
	v_bfi_b32 v7, s13, v11, v7
	v_add_f32_e32 v7, 1.0, v7
	v_mul_f32_e32 v11, v10, v7
	v_fmac_f32_e32 v11, v9, v8
	s_nop 1
	v_add_f32_dpp v11, v11, v11 row_ror:8 row_mask:0xf bank_mask:0xf bound_ctrl:1
	s_nop 1
	v_add_f32_dpp v11, v11, v11 row_ror:4 row_mask:0xf bank_mask:0xf bound_ctrl:1
	s_nop 1
	v_add_f32_dpp v11, v11, v11 row_ror:2 row_mask:0xf bank_mask:0xf bound_ctrl:1
	s_nop 1
	v_add_f32_dpp v11, v11, v11 row_ror:1 row_mask:0xf bank_mask:0xf bound_ctrl:1
	ds_bpermute_b32 v12, v3, v11
	s_waitcnt lgkmcnt(0)
	v_add_f32_e32 v11, v11, v12
	v_mov_b32_e32 v12, v11
	s_nop 1
	v_permlane32_swap_b32_e32 v11, v12
	v_add_f32_e32 v11, v11, v12
	v_mul_f32_e32 v11, 0x3c000000, v11
	v_fma_f32 v7, v10, v7, -v11
	v_fma_f32 v8, v9, v8, -v11
	v_mul_f32_e32 v9, v7, v7
	v_fmac_f32_e32 v9, v8, v8
	s_nop 1
	v_add_f32_dpp v9, v9, v9 row_ror:8 row_mask:0xf bank_mask:0xf bound_ctrl:1
	s_nop 1
	v_add_f32_dpp v9, v9, v9 row_ror:4 row_mask:0xf bank_mask:0xf bound_ctrl:1
	s_nop 1
	v_add_f32_dpp v9, v9, v9 row_ror:2 row_mask:0xf bank_mask:0xf bound_ctrl:1
	s_nop 1
	v_add_f32_dpp v9, v9, v9 row_ror:1 row_mask:0xf bank_mask:0xf bound_ctrl:1
	ds_bpermute_b32 v10, v3, v9
	s_waitcnt lgkmcnt(0)
	v_add_f32_e32 v9, v9, v10
	v_mov_b32_e32 v10, v9
	s_nop 1
	v_permlane32_swap_b32_e32 v9, v10
	v_add_f32_e32 v9, v9, v10
	v_fmamk_f32 v9, v9, 0x3c000000, v177
	v_cmp_gt_f32_e32 vcc, s16, v9
	v_mul_f32_e32 v10, 0x4b800000, v9
	s_nop 0
	v_cndmask_b32_e32 v9, v9, v10, vcc
	v_rsq_f32_e32 v9, v9
	s_nop 0
	v_mul_f32_e32 v10, 0x45800000, v9
	v_cndmask_b32_e32 v9, v9, v10, vcc
	v_mul_f32_e32 v8, v8, v9
	v_bfe_u32 v10, v8, 16, 1
	v_add3_u32 v8, v8, v10, s83
	v_add_u32_e32 v10, s5, v6
	v_mul_f32_e32 v7, v7, v9
	ds_write_b16_d16_hi v10, v8
	v_bfe_u32 v8, v7, 16, 1
	s_add_i32 s5, s5, 2
	v_add3_u32 v7, v7, v8, s83
	ds_write_b16_d16_hi v10, v7 offset:272
	s_waitcnt vmcnt(10)
; DI bf16 f2bf(float f) { unsigned u = __float_as_uint(f); u += 0x7fffu + ((u >> 16) & 1u); return (bf16)(u >> 16); }
;   DI bf16* P() const { return (bf16*)(p.ws + WS_P); }
; DI float erf_as(float x) {
;   const float ax = fabsf(x);
;   const float t = __builtin_amdgcn_rcpf(1.f + 0.3275911f * ax);
;   const float poly = t * (0.254829592f + t * (-0.284496736f + t * (1.421413741f + t * (-1.453152027f + t * 1.061405429f))));
;   const float y = 1.f - poly * __builtin_amdgcn_exp2f(-1.4426950408889634f * ax * ax);
;   return copysignf(y, x);
; }
; DI float gelu(float x) { return 0.5f * x * (1.f + erf_as(x * 0.70710678118654752f)); }
; DI void vgt_tile(const Ctx& c, int ti, bf16* lds) {
;     ...
;   for (int rr = 0; rr < 32; ++rr) {
;     const int t = wave * 32 + rr;
;     const unsigned u = *(const unsigned*)(c.P() + (size_t)(row0 + t) * LDP + C_V + g * 128 + 2 * lane);
;     const float a = gelu(__uint_as_float(u << 16)), b = gelu(__uint_as_float(u & 0xffff0000u));
;     const float mean = wave_sum(a + b) * (1.f / 128.f);
;     const float da = a - mean, db = b - mean;
;     const float rstd = rsqrtf(wave_sum(da * da + db * db) * (1.f / 128.f) + LN_EPS);
;     lds[(2 * lane) * LDT + t] = f2bf(da * rstd);
;     lds[(2 * lane + 1) * LDT + t] = f2bf(db * rstd);
;   }
	v_lshlrev_b32_e32 v8, 16, v41
	v_mul_f32_e32 v9, 0.5, v8
	v_mul_f32_e32 v8, 0x3f3504f3, v8
	v_fma_f32 v10, |v8|, s2, 1.0
	v_rcp_f32_e32 v10, v10
	v_and_b32_e32 v7, 0xffff0000, v41
	v_fmamk_f32 v11, v10, 0x3f87dc22, v176
	v_fmaak_f32 v11, v10, v11, 0x3fb5f0e3
	v_fmaak_f32 v11, v10, v11, 0xbe91a98e
	v_fmaak_f32 v11, v10, v11, 0x3e827906
	v_mul_f32_e32 v10, v10, v11
	v_mul_f32_e64 v11, |v8|, s3
	v_mul_f32_e64 v11, |v8|, v11
	v_exp_f32_e32 v11, v11
	s_nop 0
	v_fma_f32 v10, -v11, v10, 1.0
	v_bfi_b32 v8, s13, v10, v8
	v_mul_f32_e32 v10, 0.5, v7
	v_mul_f32_e32 v7, 0x3f3504f3, v7
	v_fma_f32 v11, |v7|, s2, 1.0
	v_rcp_f32_e32 v11, v11
	v_add_f32_e32 v8, 1.0, v8
	v_fmamk_f32 v12, v11, 0x3f87dc22, v176
	v_fmaak_f32 v12, v11, v12, 0x3fb5f0e3
	v_fmaak_f32 v12, v11, v12, 0xbe91a98e
	v_fmaak_f32 v12, v11, v12, 0x3e827906
	v_mul_f32_e32 v11, v11, v12
	v_mul_f32_e64 v12, |v7|, s3
	v_mul_f32_e64 v12, |v7|, v12
	v_exp_f32_e32 v12, v12
	s_nop 0
	v_fma_f32 v11, -v12, v11, 1.0
	v_bfi_b32 v7, s13, v11, v7
	v_add_f32_e32 v7, 1.0, v7
	v_mul_f32_e32 v11, v10, v7
	v_fmac_f32_e32 v11, v9, v8
	s_nop 1
	v_add_f32_dpp v11, v11, v11 row_ror:8 row_mask:0xf bank_mask:0xf bound_ctrl:1
	s_nop 1
	v_add_f32_dpp v11, v11, v11 row_ror:4 row_mask:0xf bank_mask:0xf bound_ctrl:1
	s_nop 1
	v_add_f32_dpp v11, v11, v11 row_ror:2 row_mask:0xf bank_mask:0xf bound_ctrl:1
	s_nop 1
	v_add_f32_dpp v11, v11, v11 row_ror:1 row_mask:0xf bank_mask:0xf bound_ctrl:1
	ds_bpermute_b32 v12, v3, v11
	s_waitcnt lgkmcnt(0)
	v_add_f32_e32 v11, v11, v12
	v_mov_b32_e32 v12, v11
	s_nop 1
	v_permlane32_swap_b32_e32 v11, v12
	v_add_f32_e32 v11, v11, v12
	v_mul_f32_e32 v11, 0x3c000000, v11
	v_fma_f32 v7, v10, v7, -v11
	v_fma_f32 v8, v9, v8, -v11
	v_mul_f32_e32 v9, v7, v7
	v_fmac_f32_e32 v9, v8, v8
	s_nop 1
	v_add_f32_dpp v9, v9, v9 row_ror:8 row_mask:0xf bank_mask:0xf bound_ctrl:1
	s_nop 1
	v_add_f32_dpp v9, v9, v9 row_ror:4 row_mask:0xf bank_mask:0xf bound_ctrl:1
	s_nop 1
	v_add_f32_dpp v9, v9, v9 row_ror:2 row_mask:0xf bank_mask:0xf bound_ctrl:1
	s_nop 1
	v_add_f32_dpp v9, v9, v9 row_ror:1 row_mask:0xf bank_mask:0xf bound_ctrl:1
	ds_bpermute_b32 v10, v3, v9
	s_waitcnt lgkmcnt(0)
	v_add_f32_e32 v9, v9, v10
	v_mov_b32_e32 v10, v9
	s_nop 1
	v_permlane32_swap_b32_e32 v9, v10
	v_add_f32_e32 v9, v9, v10
	v_fmamk_f32 v9, v9, 0x3c000000, v177
	v_cmp_gt_f32_e32 vcc, s16, v9
	v_mul_f32_e32 v10, 0x4b800000, v9
	s_nop 0
	v_cndmask_b32_e32 v9, v9, v10, vcc
	v_rsq_f32_e32 v9, v9
	s_nop 0
	v_mul_f32_e32 v10, 0x45800000, v9
	v_cndmask_b32_e32 v9, v9, v10, vcc
	v_mul_f32_e32 v8, v8, v9
	v_bfe_u32 v10, v8, 16, 1
	v_add3_u32 v8, v8, v10, s83
	v_add_u32_e32 v10, s5, v6
	v_mul_f32_e32 v7, v7, v9
	ds_write_b16_d16_hi v10, v8
	v_bfe_u32 v8, v7, 16, 1
	s_add_i32 s5, s5, 2
	v_add3_u32 v7, v7, v8, s83
	ds_write_b16_d16_hi v10, v7 offset:272
	s_waitcnt vmcnt(9)
	v_lshlrev_b32_e32 v8, 16, v42
	v_mul_f32_e32 v9, 0.5, v8
	v_mul_f32_e32 v8, 0x3f3504f3, v8
	v_fma_f32 v10, |v8|, s2, 1.0
	v_rcp_f32_e32 v10, v10
	v_and_b32_e32 v7, 0xffff0000, v42
	v_fmamk_f32 v11, v10, 0x3f87dc22, v176
	v_fmaak_f32 v11, v10, v11, 0x3fb5f0e3
	v_fmaak_f32 v11, v10, v11, 0xbe91a98e
	v_fmaak_f32 v11, v10, v11, 0x3e827906
	v_mul_f32_e32 v10, v10, v11
	v_mul_f32_e64 v11, |v8|, s3
	v_mul_f32_e64 v11, |v8|, v11
	v_exp_f32_e32 v11, v11
	s_nop 0
	v_fma_f32 v10, -v11, v10, 1.0
	v_bfi_b32 v8, s13, v10, v8
	v_mul_f32_e32 v10, 0.5, v7
	v_mul_f32_e32 v7, 0x3f3504f3, v7
	v_fma_f32 v11, |v7|, s2, 1.0
	v_rcp_f32_e32 v11, v11
	v_add_f32_e32 v8, 1.0, v8
	v_fmamk_f32 v12, v11, 0x3f87dc22, v176
	v_fmaak_f32 v12, v11, v12, 0x3fb5f0e3
	v_fmaak_f32 v12, v11, v12, 0xbe91a98e
	v_fmaak_f32 v12, v11, v12, 0x3e827906
	v_mul_f32_e32 v11, v11, v12
	v_mul_f32_e64 v12, |v7|, s3
	v_mul_f32_e64 v12, |v7|, v12
	v_exp_f32_e32 v12, v12
	s_nop 0
	v_fma_f32 v11, -v12, v11, 1.0
	v_bfi_b32 v7, s13, v11, v7
	v_add_f32_e32 v7, 1.0, v7
	v_mul_f32_e32 v11, v10, v7
	v_fmac_f32_e32 v11, v9, v8
	s_nop 1
	v_add_f32_dpp v11, v11, v11 row_ror:8 row_mask:0xf bank_mask:0xf bound_ctrl:1
	s_nop 1
	v_add_f32_dpp v11, v11, v11 row_ror:4 row_mask:0xf bank_mask:0xf bound_ctrl:1
	s_nop 1
	v_add_f32_dpp v11, v11, v11 row_ror:2 row_mask:0xf bank_mask:0xf bound_ctrl:1
	s_nop 1
	v_add_f32_dpp v11, v11, v11 row_ror:1 row_mask:0xf bank_mask:0xf bound_ctrl:1
	ds_bpermute_b32 v12, v3, v11
	s_waitcnt lgkmcnt(0)
	v_add_f32_e32 v11, v11, v12
	v_mov_b32_e32 v12, v11
	s_nop 1
	v_permlane32_swap_b32_e32 v11, v12
	v_add_f32_e32 v11, v11, v12
	v_mul_f32_e32 v11, 0x3c000000, v11
	v_fma_f32 v7, v10, v7, -v11
	v_fma_f32 v8, v9, v8, -v11
	v_mul_f32_e32 v9, v7, v7
	v_fmac_f32_e32 v9, v8, v8
	s_nop 1
	v_add_f32_dpp v9, v9, v9 row_ror:8 row_mask:0xf bank_mask:0xf bound_ctrl:1
	s_nop 1
	v_add_f32_dpp v9, v9, v9 row_ror:4 row_mask:0xf bank_mask:0xf bound_ctrl:1
	s_nop 1
	v_add_f32_dpp v9, v9, v9 row_ror:2 row_mask:0xf bank_mask:0xf bound_ctrl:1
	s_nop 1
	v_add_f32_dpp v9, v9, v9 row_ror:1 row_mask:0xf bank_mask:0xf bound_ctrl:1
	ds_bpermute_b32 v10, v3, v9
	s_waitcnt lgkmcnt(0)
	v_add_f32_e32 v9, v9, v10
	v_mov_b32_e32 v10, v9
	s_nop 1
	v_permlane32_swap_b32_e32 v9, v10
	v_add_f32_e32 v9, v9, v10
	v_fmamk_f32 v9, v9, 0x3c000000, v177
	v_cmp_gt_f32_e32 vcc, s16, v9
	v_mul_f32_e32 v10, 0x4b800000, v9
	s_nop 0
	v_cndmask_b32_e32 v9, v9, v10, vcc
	v_rsq_f32_e32 v9, v9
	s_nop 0
	v_mul_f32_e32 v10, 0x45800000, v9
	v_cndmask_b32_e32 v9, v9, v10, vcc
	v_mul_f32_e32 v8, v8, v9
	v_bfe_u32 v10, v8, 16, 1
	v_add3_u32 v8, v8, v10, s83
	v_add_u32_e32 v10, s5, v6
	v_mul_f32_e32 v7, v7, v9
	ds_write_b16_d16_hi v10, v8
	v_bfe_u32 v8, v7, 16, 1
	s_add_i32 s5, s5, 2
	v_add3_u32 v7, v7, v8, s83
	ds_write_b16_d16_hi v10, v7 offset:272
	s_waitcnt vmcnt(8)
; DI bf16 f2bf(float f) { unsigned u = __float_as_uint(f); u += 0x7fffu + ((u >> 16) & 1u); return (bf16)(u >> 16); }
;   DI bf16* P() const { return (bf16*)(p.ws + WS_P); }
; DI float erf_as(float x) {
;   const float ax = fabsf(x);
;   const float t = __builtin_amdgcn_rcpf(1.f + 0.3275911f * ax);
;   const float poly = t * (0.254829592f + t * (-0.284496736f + t * (1.421413741f + t * (-1.453152027f + t * 1.061405429f))));
;   const float y = 1.f - poly * __builtin_amdgcn_exp2f(-1.4426950408889634f * ax * ax);
;   return copysignf(y, x);
; }
; DI float gelu(float x) { return 0.5f * x * (1.f + erf_as(x * 0.70710678118654752f)); }
; DI void vgt_tile(const Ctx& c, int ti, bf16* lds) {
;     ...
;   for (int rr = 0; rr < 32; ++rr) {
;     const int t = wave * 32 + rr;
;     const unsigned u = *(const unsigned*)(c.P() + (size_t)(row0 + t) * LDP + C_V + g * 128 + 2 * lane);
;     const float a = gelu(__uint_as_float(u << 16)), b = gelu(__uint_as_float(u & 0xffff0000u));
;     const float mean = wave_sum(a + b) * (1.f / 128.f);
;     const float da = a - mean, db = b - mean;
;     const float rstd = rsqrtf(wave_sum(da * da + db * db) * (1.f / 128.f) + LN_EPS);
;     lds[(2 * lane) * LDT + t] = f2bf(da * rstd);
;     lds[(2 * lane + 1) * LDT + t] = f2bf(db * rstd);
;   }
	v_lshlrev_b32_e32 v8, 16, v43
	v_mul_f32_e32 v9, 0.5, v8
	v_mul_f32_e32 v8, 0x3f3504f3, v8
	v_fma_f32 v10, |v8|, s2, 1.0
	v_rcp_f32_e32 v10, v10
	v_and_b32_e32 v7, 0xffff0000, v43
	v_fmamk_f32 v11, v10, 0x3f87dc22, v176
	v_fmaak_f32 v11, v10, v11, 0x3fb5f0e3
	v_fmaak_f32 v11, v10, v11, 0xbe91a98e
	v_fmaak_f32 v11, v10, v11, 0x3e827906
	v_mul_f32_e32 v10, v10, v11
	v_mul_f32_e64 v11, |v8|, s3
	v_mul_f32_e64 v11, |v8|, v11
	v_exp_f32_e32 v11, v11
	s_nop 0
	v_fma_f32 v10, -v11, v10, 1.0
	v_bfi_b32 v8, s13, v10, v8
	v_mul_f32_e32 v10, 0.5, v7
	v_mul_f32_e32 v7, 0x3f3504f3, v7
	v_fma_f32 v11, |v7|, s2, 1.0
	v_rcp_f32_e32 v11, v11
	v_add_f32_e32 v8, 1.0, v8
	v_fmamk_f32 v12, v11, 0x3f87dc22, v176
	v_fmaak_f32 v12, v11, v12, 0x3fb5f0e3
	v_fmaak_f32 v12, v11, v12, 0xbe91a98e
	v_fmaak_f32 v12, v11, v12, 0x3e827906
	v_mul_f32_e32 v11, v11, v12
	v_mul_f32_e64 v12, |v7|, s3
	v_mul_f32_e64 v12, |v7|, v12
	v_exp_f32_e32 v12, v12
	s_nop 0
	v_fma_f32 v11, -v12, v11, 1.0
	v_bfi_b32 v7, s13, v11, v7
	v_add_f32_e32 v7, 1.0, v7
	v_mul_f32_e32 v11, v10, v7
	v_fmac_f32_e32 v11, v9, v8
	s_nop 1
	v_add_f32_dpp v11, v11, v11 row_ror:8 row_mask:0xf bank_mask:0xf bound_ctrl:1
	s_nop 1
	v_add_f32_dpp v11, v11, v11 row_ror:4 row_mask:0xf bank_mask:0xf bound_ctrl:1
	s_nop 1
	v_add_f32_dpp v11, v11, v11 row_ror:2 row_mask:0xf bank_mask:0xf bound_ctrl:1
	s_nop 1
	v_add_f32_dpp v11, v11, v11 row_ror:1 row_mask:0xf bank_mask:0xf bound_ctrl:1
	ds_bpermute_b32 v12, v3, v11
	s_waitcnt lgkmcnt(0)
	v_add_f32_e32 v11, v11, v12
	v_mov_b32_e32 v12, v11
	s_nop 1
	v_permlane32_swap_b32_e32 v11, v12
	v_add_f32_e32 v11, v11, v12
	v_mul_f32_e32 v11, 0x3c000000, v11
	v_fma_f32 v7, v10, v7, -v11
	v_fma_f32 v8, v9, v8, -v11
	v_mul_f32_e32 v9, v7, v7
	v_fmac_f32_e32 v9, v8, v8
	s_nop 1
	v_add_f32_dpp v9, v9, v9 row_ror:8 row_mask:0xf bank_mask:0xf bound_ctrl:1
	s_nop 1
	v_add_f32_dpp v9, v9, v9 row_ror:4 row_mask:0xf bank_mask:0xf bound_ctrl:1
	s_nop 1
	v_add_f32_dpp v9, v9, v9 row_ror:2 row_mask:0xf bank_mask:0xf bound_ctrl:1
	s_nop 1
	v_add_f32_dpp v9, v9, v9 row_ror:1 row_mask:0xf bank_mask:0xf bound_ctrl:1
	ds_bpermute_b32 v10, v3, v9
	s_waitcnt lgkmcnt(0)
	v_add_f32_e32 v9, v9, v10
	v_mov_b32_e32 v10, v9
	s_nop 1
	v_permlane32_swap_b32_e32 v9, v10
	v_add_f32_e32 v9, v9, v10
	v_fmamk_f32 v9, v9, 0x3c000000, v177
	v_cmp_gt_f32_e32 vcc, s16, v9
	v_mul_f32_e32 v10, 0x4b800000, v9
	s_nop 0
	v_cndmask_b32_e32 v9, v9, v10, vcc
	v_rsq_f32_e32 v9, v9
	s_nop 0
	v_mul_f32_e32 v10, 0x45800000, v9
	v_cndmask_b32_e32 v9, v9, v10, vcc
	v_mul_f32_e32 v8, v8, v9
	v_bfe_u32 v10, v8, 16, 1
	v_add3_u32 v8, v8, v10, s83
	v_add_u32_e32 v10, s5, v6
	v_mul_f32_e32 v7, v7, v9
	ds_write_b16_d16_hi v10, v8
	v_bfe_u32 v8, v7, 16, 1
	s_add_i32 s5, s5, 2
	v_add3_u32 v7, v7, v8, s83
	ds_write_b16_d16_hi v10, v7 offset:272
	s_waitcnt vmcnt(7)
	v_lshlrev_b32_e32 v8, 16, v44
	v_mul_f32_e32 v9, 0.5, v8
	v_mul_f32_e32 v8, 0x3f3504f3, v8
	v_fma_f32 v10, |v8|, s2, 1.0
	v_rcp_f32_e32 v10, v10
	v_and_b32_e32 v7, 0xffff0000, v44
	v_fmamk_f32 v11, v10, 0x3f87dc22, v176
	v_fmaak_f32 v11, v10, v11, 0x3fb5f0e3
	v_fmaak_f32 v11, v10, v11, 0xbe91a98e
	v_fmaak_f32 v11, v10, v11, 0x3e827906
	v_mul_f32_e32 v10, v10, v11
	v_mul_f32_e64 v11, |v8|, s3
	v_mul_f32_e64 v11, |v8|, v11
	v_exp_f32_e32 v11, v11
	s_nop 0
	v_fma_f32 v10, -v11, v10, 1.0
	v_bfi_b32 v8, s13, v10, v8
	v_mul_f32_e32 v10, 0.5, v7
	v_mul_f32_e32 v7, 0x3f3504f3, v7
	v_fma_f32 v11, |v7|, s2, 1.0
	v_rcp_f32_e32 v11, v11
	v_add_f32_e32 v8, 1.0, v8
	v_fmamk_f32 v12, v11, 0x3f87dc22, v176
	v_fmaak_f32 v12, v11, v12, 0x3fb5f0e3
	v_fmaak_f32 v12, v11, v12, 0xbe91a98e
	v_fmaak_f32 v12, v11, v12, 0x3e827906
	v_mul_f32_e32 v11, v11, v12
	v_mul_f32_e64 v12, |v7|, s3
	v_mul_f32_e64 v12, |v7|, v12
	v_exp_f32_e32 v12, v12
	s_nop 0
	v_fma_f32 v11, -v12, v11, 1.0
	v_bfi_b32 v7, s13, v11, v7
	v_add_f32_e32 v7, 1.0, v7
	v_mul_f32_e32 v11, v10, v7
	v_fmac_f32_e32 v11, v9, v8
	s_nop 1
	v_add_f32_dpp v11, v11, v11 row_ror:8 row_mask:0xf bank_mask:0xf bound_ctrl:1
	s_nop 1
	v_add_f32_dpp v11, v11, v11 row_ror:4 row_mask:0xf bank_mask:0xf bound_ctrl:1
	s_nop 1
	v_add_f32_dpp v11, v11, v11 row_ror:2 row_mask:0xf bank_mask:0xf bound_ctrl:1
	s_nop 1
	v_add_f32_dpp v11, v11, v11 row_ror:1 row_mask:0xf bank_mask:0xf bound_ctrl:1
	ds_bpermute_b32 v12, v3, v11
	s_waitcnt lgkmcnt(0)
	v_add_f32_e32 v11, v11, v12
	v_mov_b32_e32 v12, v11
	s_nop 1
	v_permlane32_swap_b32_e32 v11, v12
	v_add_f32_e32 v11, v11, v12
	v_mul_f32_e32 v11, 0x3c000000, v11
	v_fma_f32 v7, v10, v7, -v11
	v_fma_f32 v8, v9, v8, -v11
	v_mul_f32_e32 v9, v7, v7
	v_fmac_f32_e32 v9, v8, v8
	s_nop 1
	v_add_f32_dpp v9, v9, v9 row_ror:8 row_mask:0xf bank_mask:0xf bound_ctrl:1
	s_nop 1
	v_add_f32_dpp v9, v9, v9 row_ror:4 row_mask:0xf bank_mask:0xf bound_ctrl:1
	s_nop 1
	v_add_f32_dpp v9, v9, v9 row_ror:2 row_mask:0xf bank_mask:0xf bound_ctrl:1
	s_nop 1
	v_add_f32_dpp v9, v9, v9 row_ror:1 row_mask:0xf bank_mask:0xf bound_ctrl:1
	ds_bpermute_b32 v10, v3, v9
	s_waitcnt lgkmcnt(0)
	v_add_f32_e32 v9, v9, v10
	v_mov_b32_e32 v10, v9
	s_nop 1
	v_permlane32_swap_b32_e32 v9, v10
	v_add_f32_e32 v9, v9, v10
	v_fmamk_f32 v9, v9, 0x3c000000, v177
	v_cmp_gt_f32_e32 vcc, s16, v9
	v_mul_f32_e32 v10, 0x4b800000, v9
	s_nop 0
	v_cndmask_b32_e32 v9, v9, v10, vcc
	v_rsq_f32_e32 v9, v9
	s_nop 0
	v_mul_f32_e32 v10, 0x45800000, v9
	v_cndmask_b32_e32 v9, v9, v10, vcc
	v_mul_f32_e32 v8, v8, v9
	v_bfe_u32 v10, v8, 16, 1
	v_add3_u32 v8, v8, v10, s83
	v_add_u32_e32 v10, s5, v6
	v_mul_f32_e32 v7, v7, v9
	ds_write_b16_d16_hi v10, v8
	v_bfe_u32 v8, v7, 16, 1
	s_add_i32 s5, s5, 2
	v_add3_u32 v7, v7, v8, s83
	ds_write_b16_d16_hi v10, v7 offset:272
	s_waitcnt vmcnt(6)
; DI bf16 f2bf(float f) { unsigned u = __float_as_uint(f); u += 0x7fffu + ((u >> 16) & 1u); return (bf16)(u >> 16); }
;   DI bf16* P() const { return (bf16*)(p.ws + WS_P); }
; DI float erf_as(float x) {
;   const float ax = fabsf(x);
;   const float t = __builtin_amdgcn_rcpf(1.f + 0.3275911f * ax);
;   const float poly = t * (0.254829592f + t * (-0.284496736f + t * (1.421413741f + t * (-1.453152027f + t * 1.061405429f))));
;   const float y = 1.f - poly * __builtin_amdgcn_exp2f(-1.4426950408889634f * ax * ax);
;   return copysignf(y, x);
; }
; DI float gelu(float x) { return 0.5f * x * (1.f + erf_as(x * 0.70710678118654752f)); }
; DI void vgt_tile(const Ctx& c, int ti, bf16* lds) {
;     ...
;   for (int rr = 0; rr < 32; ++rr) {
;     const int t = wave * 32 + rr;
;     const unsigned u = *(const unsigned*)(c.P() + (size_t)(row0 + t) * LDP + C_V + g * 128 + 2 * lane);
;     const float a = gelu(__uint_as_float(u << 16)), b = gelu(__uint_as_float(u & 0xffff0000u));
;     const float mean = wave_sum(a + b) * (1.f / 128.f);
;     const float da = a - mean, db = b - mean;
;     const float rstd = rsqrtf(wave_sum(da * da + db * db) * (1.f / 128.f) + LN_EPS);
;     lds[(2 * lane) * LDT + t] = f2bf(da * rstd);
;     lds[(2 * lane + 1) * LDT + t] = f2bf(db * rstd);
;   }
	v_lshlrev_b32_e32 v8, 16, v45
	v_mul_f32_e32 v9, 0.5, v8
	v_mul_f32_e32 v8, 0x3f3504f3, v8
	v_fma_f32 v10, |v8|, s2, 1.0
	v_rcp_f32_e32 v10, v10
	v_and_b32_e32 v7, 0xffff0000, v45
	v_fmamk_f32 v11, v10, 0x3f87dc22, v176
	v_fmaak_f32 v11, v10, v11, 0x3fb5f0e3
	v_fmaak_f32 v11, v10, v11, 0xbe91a98e
	v_fmaak_f32 v11, v10, v11, 0x3e827906
	v_mul_f32_e32 v10, v10, v11
	v_mul_f32_e64 v11, |v8|, s3
	v_mul_f32_e64 v11, |v8|, v11
	v_exp_f32_e32 v11, v11
	s_nop 0
	v_fma_f32 v10, -v11, v10, 1.0
	v_bfi_b32 v8, s13, v10, v8
	v_mul_f32_e32 v10, 0.5, v7
	v_mul_f32_e32 v7, 0x3f3504f3, v7
	v_fma_f32 v11, |v7|, s2, 1.0
	v_rcp_f32_e32 v11, v11
	v_add_f32_e32 v8, 1.0, v8
	v_fmamk_f32 v12, v11, 0x3f87dc22, v176
	v_fmaak_f32 v12, v11, v12, 0x3fb5f0e3
	v_fmaak_f32 v12, v11, v12, 0xbe91a98e
	v_fmaak_f32 v12, v11, v12, 0x3e827906
	v_mul_f32_e32 v11, v11, v12
	v_mul_f32_e64 v12, |v7|, s3
	v_mul_f32_e64 v12, |v7|, v12
	v_exp_f32_e32 v12, v12
	s_nop 0
	v_fma_f32 v11, -v12, v11, 1.0
	v_bfi_b32 v7, s13, v11, v7
	v_add_f32_e32 v7, 1.0, v7
	v_mul_f32_e32 v11, v10, v7
	v_fmac_f32_e32 v11, v9, v8
	s_nop 1
	v_add_f32_dpp v11, v11, v11 row_ror:8 row_mask:0xf bank_mask:0xf bound_ctrl:1
	s_nop 1
	v_add_f32_dpp v11, v11, v11 row_ror:4 row_mask:0xf bank_mask:0xf bound_ctrl:1
	s_nop 1
	v_add_f32_dpp v11, v11, v11 row_ror:2 row_mask:0xf bank_mask:0xf bound_ctrl:1
	s_nop 1
	v_add_f32_dpp v11, v11, v11 row_ror:1 row_mask:0xf bank_mask:0xf bound_ctrl:1
	ds_bpermute_b32 v12, v3, v11
	s_waitcnt lgkmcnt(0)
	v_add_f32_e32 v11, v11, v12
	v_mov_b32_e32 v12, v11
	s_nop 1
	v_permlane32_swap_b32_e32 v11, v12
	v_add_f32_e32 v11, v11, v12
	v_mul_f32_e32 v11, 0x3c000000, v11
	v_fma_f32 v7, v10, v7, -v11
	v_fma_f32 v8, v9, v8, -v11
	v_mul_f32_e32 v9, v7, v7
	v_fmac_f32_e32 v9, v8, v8
	s_nop 1
	v_add_f32_dpp v9, v9, v9 row_ror:8 row_mask:0xf bank_mask:0xf bound_ctrl:1
	s_nop 1
	v_add_f32_dpp v9, v9, v9 row_ror:4 row_mask:0xf bank_mask:0xf bound_ctrl:1
	s_nop 1
	v_add_f32_dpp v9, v9, v9 row_ror:2 row_mask:0xf bank_mask:0xf bound_ctrl:1
	s_nop 1
	v_add_f32_dpp v9, v9, v9 row_ror:1 row_mask:0xf bank_mask:0xf bound_ctrl:1
	ds_bpermute_b32 v10, v3, v9
	s_waitcnt lgkmcnt(0)
	v_add_f32_e32 v9, v9, v10
	v_mov_b32_e32 v10, v9
	s_nop 1
	v_permlane32_swap_b32_e32 v9, v10
	v_add_f32_e32 v9, v9, v10
	v_fmamk_f32 v9, v9, 0x3c000000, v177
	v_cmp_gt_f32_e32 vcc, s16, v9
	v_mul_f32_e32 v10, 0x4b800000, v9
	s_nop 0
	v_cndmask_b32_e32 v9, v9, v10, vcc
	v_rsq_f32_e32 v9, v9
	s_nop 0
	v_mul_f32_e32 v10, 0x45800000, v9
	v_cndmask_b32_e32 v9, v9, v10, vcc
	v_mul_f32_e32 v8, v8, v9
	v_bfe_u32 v10, v8, 16, 1
	v_add3_u32 v8, v8, v10, s83
	v_add_u32_e32 v10, s5, v6
	v_mul_f32_e32 v7, v7, v9
	ds_write_b16_d16_hi v10, v8
	v_bfe_u32 v8, v7, 16, 1
	s_add_i32 s5, s5, 2
	v_add3_u32 v7, v7, v8, s83
	ds_write_b16_d16_hi v10, v7 offset:272
	s_waitcnt vmcnt(5)
	v_lshlrev_b32_e32 v8, 16, v46
	v_mul_f32_e32 v9, 0.5, v8
	v_mul_f32_e32 v8, 0x3f3504f3, v8
	v_fma_f32 v10, |v8|, s2, 1.0
	v_rcp_f32_e32 v10, v10
	v_and_b32_e32 v7, 0xffff0000, v46
	v_fmamk_f32 v11, v10, 0x3f87dc22, v176
	v_fmaak_f32 v11, v10, v11, 0x3fb5f0e3
	v_fmaak_f32 v11, v10, v11, 0xbe91a98e
	v_fmaak_f32 v11, v10, v11, 0x3e827906
	v_mul_f32_e32 v10, v10, v11
	v_mul_f32_e64 v11, |v8|, s3
	v_mul_f32_e64 v11, |v8|, v11
	v_exp_f32_e32 v11, v11
	s_nop 0
	v_fma_f32 v10, -v11, v10, 1.0
	v_bfi_b32 v8, s13, v10, v8
	v_mul_f32_e32 v10, 0.5, v7
	v_mul_f32_e32 v7, 0x3f3504f3, v7
	v_fma_f32 v11, |v7|, s2, 1.0
	v_rcp_f32_e32 v11, v11
	v_add_f32_e32 v8, 1.0, v8
	v_fmamk_f32 v12, v11, 0x3f87dc22, v176
	v_fmaak_f32 v12, v11, v12, 0x3fb5f0e3
	v_fmaak_f32 v12, v11, v12, 0xbe91a98e
	v_fmaak_f32 v12, v11, v12, 0x3e827906
	v_mul_f32_e32 v11, v11, v12
	v_mul_f32_e64 v12, |v7|, s3
	v_mul_f32_e64 v12, |v7|, v12
	v_exp_f32_e32 v12, v12
	s_nop 0
	v_fma_f32 v11, -v12, v11, 1.0
	v_bfi_b32 v7, s13, v11, v7
	v_add_f32_e32 v7, 1.0, v7
	v_mul_f32_e32 v11, v10, v7
	v_fmac_f32_e32 v11, v9, v8
	s_nop 1
	v_add_f32_dpp v11, v11, v11 row_ror:8 row_mask:0xf bank_mask:0xf bound_ctrl:1
	s_nop 1
	v_add_f32_dpp v11, v11, v11 row_ror:4 row_mask:0xf bank_mask:0xf bound_ctrl:1
	s_nop 1
	v_add_f32_dpp v11, v11, v11 row_ror:2 row_mask:0xf bank_mask:0xf bound_ctrl:1
	s_nop 1
	v_add_f32_dpp v11, v11, v11 row_ror:1 row_mask:0xf bank_mask:0xf bound_ctrl:1
	ds_bpermute_b32 v12, v3, v11
	s_waitcnt lgkmcnt(0)
	v_add_f32_e32 v11, v11, v12
	v_mov_b32_e32 v12, v11
	s_nop 1
	v_permlane32_swap_b32_e32 v11, v12
	v_add_f32_e32 v11, v11, v12
	v_mul_f32_e32 v11, 0x3c000000, v11
	v_fma_f32 v7, v10, v7, -v11
	v_fma_f32 v8, v9, v8, -v11
	v_mul_f32_e32 v9, v7, v7
	v_fmac_f32_e32 v9, v8, v8
	s_nop 1
	v_add_f32_dpp v9, v9, v9 row_ror:8 row_mask:0xf bank_mask:0xf bound_ctrl:1
	s_nop 1
	v_add_f32_dpp v9, v9, v9 row_ror:4 row_mask:0xf bank_mask:0xf bound_ctrl:1
	s_nop 1
	v_add_f32_dpp v9, v9, v9 row_ror:2 row_mask:0xf bank_mask:0xf bound_ctrl:1
	s_nop 1
	v_add_f32_dpp v9, v9, v9 row_ror:1 row_mask:0xf bank_mask:0xf bound_ctrl:1
	ds_bpermute_b32 v10, v3, v9
	s_waitcnt lgkmcnt(0)
	v_add_f32_e32 v9, v9, v10
	v_mov_b32_e32 v10, v9
	s_nop 1
	v_permlane32_swap_b32_e32 v9, v10
	v_add_f32_e32 v9, v9, v10
	v_fmamk_f32 v9, v9, 0x3c000000, v177
	v_cmp_gt_f32_e32 vcc, s16, v9
	v_mul_f32_e32 v10, 0x4b800000, v9
	s_nop 0
	v_cndmask_b32_e32 v9, v9, v10, vcc
	v_rsq_f32_e32 v9, v9
	s_nop 0
	v_mul_f32_e32 v10, 0x45800000, v9
	v_cndmask_b32_e32 v9, v9, v10, vcc
	v_mul_f32_e32 v8, v8, v9
	v_bfe_u32 v10, v8, 16, 1
	v_add3_u32 v8, v8, v10, s83
	v_add_u32_e32 v10, s5, v6
	v_mul_f32_e32 v7, v7, v9
	ds_write_b16_d16_hi v10, v8
	v_bfe_u32 v8, v7, 16, 1
	s_add_i32 s5, s5, 2
	v_add3_u32 v7, v7, v8, s83
	ds_write_b16_d16_hi v10, v7 offset:272
	s_waitcnt vmcnt(4)
; DI bf16 f2bf(float f) { unsigned u = __float_as_uint(f); u += 0x7fffu + ((u >> 16) & 1u); return (bf16)(u >> 16); }
;   DI bf16* P() const { return (bf16*)(p.ws + WS_P); }
; DI float erf_as(float x) {
;   const float ax = fabsf(x);
;   const float t = __builtin_amdgcn_rcpf(1.f + 0.3275911f * ax);
;   const float poly = t * (0.254829592f + t * (-0.284496736f + t * (1.421413741f + t * (-1.453152027f + t * 1.061405429f))));
;   const float y = 1.f - poly * __builtin_amdgcn_exp2f(-1.4426950408889634f * ax * ax);
;   return copysignf(y, x);
; }
; DI float gelu(float x) { return 0.5f * x * (1.f + erf_as(x * 0.70710678118654752f)); }
; DI void vgt_tile(const Ctx& c, int ti, bf16* lds) {
;     ...
;   for (int rr = 0; rr < 32; ++rr) {
;     const int t = wave * 32 + rr;
;     const unsigned u = *(const unsigned*)(c.P() + (size_t)(row0 + t) * LDP + C_V + g * 128 + 2 * lane);
;     const float a = gelu(__uint_as_float(u << 16)), b = gelu(__uint_as_float(u & 0xffff0000u));
;     const float mean = wave_sum(a + b) * (1.f / 128.f);
;     const float da = a - mean, db = b - mean;
;     const float rstd = rsqrtf(wave_sum(da * da + db * db) * (1.f / 128.f) + LN_EPS);
;     lds[(2 * lane) * LDT + t] = f2bf(da * rstd);
;     lds[(2 * lane + 1) * LDT + t] = f2bf(db * rstd);
;   }
	v_lshlrev_b32_e32 v8, 16, v47
	v_mul_f32_e32 v9, 0.5, v8
	v_mul_f32_e32 v8, 0x3f3504f3, v8
	v_fma_f32 v10, |v8|, s2, 1.0
	v_rcp_f32_e32 v10, v10
	v_and_b32_e32 v7, 0xffff0000, v47
	v_fmamk_f32 v11, v10, 0x3f87dc22, v176
	v_fmaak_f32 v11, v10, v11, 0x3fb5f0e3
	v_fmaak_f32 v11, v10, v11, 0xbe91a98e
	v_fmaak_f32 v11, v10, v11, 0x3e827906
	v_mul_f32_e32 v10, v10, v11
	v_mul_f32_e64 v11, |v8|, s3
	v_mul_f32_e64 v11, |v8|, v11
	v_exp_f32_e32 v11, v11
	s_nop 0
	v_fma_f32 v10, -v11, v10, 1.0
	v_bfi_b32 v8, s13, v10, v8
	v_mul_f32_e32 v10, 0.5, v7
	v_mul_f32_e32 v7, 0x3f3504f3, v7
	v_fma_f32 v11, |v7|, s2, 1.0
	v_rcp_f32_e32 v11, v11
	v_add_f32_e32 v8, 1.0, v8
	v_fmamk_f32 v12, v11, 0x3f87dc22, v176
	v_fmaak_f32 v12, v11, v12, 0x3fb5f0e3
	v_fmaak_f32 v12, v11, v12, 0xbe91a98e
	v_fmaak_f32 v12, v11, v12, 0x3e827906
	v_mul_f32_e32 v11, v11, v12
	v_mul_f32_e64 v12, |v7|, s3
	v_mul_f32_e64 v12, |v7|, v12
	v_exp_f32_e32 v12, v12
	s_nop 0
	v_fma_f32 v11, -v12, v11, 1.0
	v_bfi_b32 v7, s13, v11, v7
	v_add_f32_e32 v7, 1.0, v7
	v_mul_f32_e32 v11, v10, v7
	v_fmac_f32_e32 v11, v9, v8
	s_nop 1
	v_add_f32_dpp v11, v11, v11 row_ror:8 row_mask:0xf bank_mask:0xf bound_ctrl:1
	s_nop 1
	v_add_f32_dpp v11, v11, v11 row_ror:4 row_mask:0xf bank_mask:0xf bound_ctrl:1
	s_nop 1
	v_add_f32_dpp v11, v11, v11 row_ror:2 row_mask:0xf bank_mask:0xf bound_ctrl:1
	s_nop 1
	v_add_f32_dpp v11, v11, v11 row_ror:1 row_mask:0xf bank_mask:0xf bound_ctrl:1
	ds_bpermute_b32 v12, v3, v11
	s_waitcnt lgkmcnt(0)
	v_add_f32_e32 v11, v11, v12
	v_mov_b32_e32 v12, v11
	s_nop 1
	v_permlane32_swap_b32_e32 v11, v12
	v_add_f32_e32 v11, v11, v12
	v_mul_f32_e32 v11, 0x3c000000, v11
	v_fma_f32 v7, v10, v7, -v11
	v_fma_f32 v8, v9, v8, -v11
	v_mul_f32_e32 v9, v7, v7
	v_fmac_f32_e32 v9, v8, v8
	s_nop 1
	v_add_f32_dpp v9, v9, v9 row_ror:8 row_mask:0xf bank_mask:0xf bound_ctrl:1
	s_nop 1
	v_add_f32_dpp v9, v9, v9 row_ror:4 row_mask:0xf bank_mask:0xf bound_ctrl:1
	s_nop 1
	v_add_f32_dpp v9, v9, v9 row_ror:2 row_mask:0xf bank_mask:0xf bound_ctrl:1
	s_nop 1
	v_add_f32_dpp v9, v9, v9 row_ror:1 row_mask:0xf bank_mask:0xf bound_ctrl:1
	ds_bpermute_b32 v10, v3, v9
	s_waitcnt lgkmcnt(0)
	v_add_f32_e32 v9, v9, v10
	v_mov_b32_e32 v10, v9
	s_nop 1
	v_permlane32_swap_b32_e32 v9, v10
	v_add_f32_e32 v9, v9, v10
	v_fmamk_f32 v9, v9, 0x3c000000, v177
	v_cmp_gt_f32_e32 vcc, s16, v9
	v_mul_f32_e32 v10, 0x4b800000, v9
	s_nop 0
	v_cndmask_b32_e32 v9, v9, v10, vcc
	v_rsq_f32_e32 v9, v9
	s_nop 0
	v_mul_f32_e32 v10, 0x45800000, v9
	v_cndmask_b32_e32 v9, v9, v10, vcc
	v_mul_f32_e32 v8, v8, v9
	v_bfe_u32 v10, v8, 16, 1
	v_add3_u32 v8, v8, v10, s83
	v_add_u32_e32 v10, s5, v6
	v_mul_f32_e32 v7, v7, v9
	ds_write_b16_d16_hi v10, v8
	v_bfe_u32 v8, v7, 16, 1
	s_add_i32 s5, s5, 2
	v_add3_u32 v7, v7, v8, s83
	ds_write_b16_d16_hi v10, v7 offset:272
	s_waitcnt vmcnt(3)
	v_lshlrev_b32_e32 v8, 16, v48
	v_mul_f32_e32 v9, 0.5, v8
	v_mul_f32_e32 v8, 0x3f3504f3, v8
	v_fma_f32 v10, |v8|, s2, 1.0
	v_rcp_f32_e32 v10, v10
	v_and_b32_e32 v7, 0xffff0000, v48
	v_fmamk_f32 v11, v10, 0x3f87dc22, v176
	v_fmaak_f32 v11, v10, v11, 0x3fb5f0e3
	v_fmaak_f32 v11, v10, v11, 0xbe91a98e
	v_fmaak_f32 v11, v10, v11, 0x3e827906
	v_mul_f32_e32 v10, v10, v11
	v_mul_f32_e64 v11, |v8|, s3
	v_mul_f32_e64 v11, |v8|, v11
	v_exp_f32_e32 v11, v11
	s_nop 0
	v_fma_f32 v10, -v11, v10, 1.0
	v_bfi_b32 v8, s13, v10, v8
	v_mul_f32_e32 v10, 0.5, v7
	v_mul_f32_e32 v7, 0x3f3504f3, v7
	v_fma_f32 v11, |v7|, s2, 1.0
	v_rcp_f32_e32 v11, v11
	v_add_f32_e32 v8, 1.0, v8
	v_fmamk_f32 v12, v11, 0x3f87dc22, v176
	v_fmaak_f32 v12, v11, v12, 0x3fb5f0e3
	v_fmaak_f32 v12, v11, v12, 0xbe91a98e
	v_fmaak_f32 v12, v11, v12, 0x3e827906
	v_mul_f32_e32 v11, v11, v12
	v_mul_f32_e64 v12, |v7|, s3
	v_mul_f32_e64 v12, |v7|, v12
	v_exp_f32_e32 v12, v12
	s_nop 0
	v_fma_f32 v11, -v12, v11, 1.0
	v_bfi_b32 v7, s13, v11, v7
	v_add_f32_e32 v7, 1.0, v7
	v_mul_f32_e32 v11, v10, v7
	v_fmac_f32_e32 v11, v9, v8
	s_nop 1
	v_add_f32_dpp v11, v11, v11 row_ror:8 row_mask:0xf bank_mask:0xf bound_ctrl:1
	s_nop 1
	v_add_f32_dpp v11, v11, v11 row_ror:4 row_mask:0xf bank_mask:0xf bound_ctrl:1
	s_nop 1
	v_add_f32_dpp v11, v11, v11 row_ror:2 row_mask:0xf bank_mask:0xf bound_ctrl:1
	s_nop 1
	v_add_f32_dpp v11, v11, v11 row_ror:1 row_mask:0xf bank_mask:0xf bound_ctrl:1
	ds_bpermute_b32 v12, v3, v11
	s_waitcnt lgkmcnt(0)
	v_add_f32_e32 v11, v11, v12
	v_mov_b32_e32 v12, v11
	s_nop 1
	v_permlane32_swap_b32_e32 v11, v12
	v_add_f32_e32 v11, v11, v12
	v_mul_f32_e32 v11, 0x3c000000, v11
	v_fma_f32 v7, v10, v7, -v11
	v_fma_f32 v8, v9, v8, -v11
	v_mul_f32_e32 v9, v7, v7
	v_fmac_f32_e32 v9, v8, v8
	s_nop 1
	v_add_f32_dpp v9, v9, v9 row_ror:8 row_mask:0xf bank_mask:0xf bound_ctrl:1
	s_nop 1
	v_add_f32_dpp v9, v9, v9 row_ror:4 row_mask:0xf bank_mask:0xf bound_ctrl:1
	s_nop 1
	v_add_f32_dpp v9, v9, v9 row_ror:2 row_mask:0xf bank_mask:0xf bound_ctrl:1
	s_nop 1
	v_add_f32_dpp v9, v9, v9 row_ror:1 row_mask:0xf bank_mask:0xf bound_ctrl:1
	ds_bpermute_b32 v10, v3, v9
	s_waitcnt lgkmcnt(0)
	v_add_f32_e32 v9, v9, v10
	v_mov_b32_e32 v10, v9
	s_nop 1
	v_permlane32_swap_b32_e32 v9, v10
	v_add_f32_e32 v9, v9, v10
	v_fmamk_f32 v9, v9, 0x3c000000, v177
	v_cmp_gt_f32_e32 vcc, s16, v9
	v_mul_f32_e32 v10, 0x4b800000, v9
	s_nop 0
	v_cndmask_b32_e32 v9, v9, v10, vcc
	v_rsq_f32_e32 v9, v9
	s_nop 0
	v_mul_f32_e32 v10, 0x45800000, v9
	v_cndmask_b32_e32 v9, v9, v10, vcc
	v_mul_f32_e32 v8, v8, v9
	v_bfe_u32 v10, v8, 16, 1
	v_add3_u32 v8, v8, v10, s83
	v_add_u32_e32 v10, s5, v6
	v_mul_f32_e32 v7, v7, v9
	ds_write_b16_d16_hi v10, v8
	v_bfe_u32 v8, v7, 16, 1
	s_add_i32 s5, s5, 2
	v_add3_u32 v7, v7, v8, s83
	ds_write_b16_d16_hi v10, v7 offset:272
	s_waitcnt vmcnt(2)
; DI bf16 f2bf(float f) { unsigned u = __float_as_uint(f); u += 0x7fffu + ((u >> 16) & 1u); return (bf16)(u >> 16); }
;   DI bf16* P() const { return (bf16*)(p.ws + WS_P); }
; DI float erf_as(float x) {
;   const float ax = fabsf(x);
;   const float t = __builtin_amdgcn_rcpf(1.f + 0.3275911f * ax);
;   const float poly = t * (0.254829592f + t * (-0.284496736f + t * (1.421413741f + t * (-1.453152027f + t * 1.061405429f))));
;   const float y = 1.f - poly * __builtin_amdgcn_exp2f(-1.4426950408889634f * ax * ax);
;   return copysignf(y, x);
; }
; DI float gelu(float x) { return 0.5f * x * (1.f + erf_as(x * 0.70710678118654752f)); }
; DI void vgt_tile(const Ctx& c, int ti, bf16* lds) {
;     ...
;   for (int rr = 0; rr < 32; ++rr) {
;     const int t = wave * 32 + rr;
;     const unsigned u = *(const unsigned*)(c.P() + (size_t)(row0 + t) * LDP + C_V + g * 128 + 2 * lane);
;     const float a = gelu(__uint_as_float(u << 16)), b = gelu(__uint_as_float(u & 0xffff0000u));
;     const float mean = wave_sum(a + b) * (1.f / 128.f);
;     const float da = a - mean, db = b - mean;
;     const float rstd = rsqrtf(wave_sum(da * da + db * db) * (1.f / 128.f) + LN_EPS);
;     lds[(2 * lane) * LDT + t] = f2bf(da * rstd);
;     lds[(2 * lane + 1) * LDT + t] = f2bf(db * rstd);
;   }
	v_lshlrev_b32_e32 v8, 16, v49
	v_mul_f32_e32 v9, 0.5, v8
	v_mul_f32_e32 v8, 0x3f3504f3, v8
	v_fma_f32 v10, |v8|, s2, 1.0
	v_rcp_f32_e32 v10, v10
	v_and_b32_e32 v7, 0xffff0000, v49
	v_fmamk_f32 v11, v10, 0x3f87dc22, v176
	v_fmaak_f32 v11, v10, v11, 0x3fb5f0e3
	v_fmaak_f32 v11, v10, v11, 0xbe91a98e
	v_fmaak_f32 v11, v10, v11, 0x3e827906
	v_mul_f32_e32 v10, v10, v11
	v_mul_f32_e64 v11, |v8|, s3
	v_mul_f32_e64 v11, |v8|, v11
	v_exp_f32_e32 v11, v11
	s_nop 0
	v_fma_f32 v10, -v11, v10, 1.0
	v_bfi_b32 v8, s13, v10, v8
	v_mul_f32_e32 v10, 0.5, v7
	v_mul_f32_e32 v7, 0x3f3504f3, v7
	v_fma_f32 v11, |v7|, s2, 1.0
	v_rcp_f32_e32 v11, v11
	v_add_f32_e32 v8, 1.0, v8
	v_fmamk_f32 v12, v11, 0x3f87dc22, v176
	v_fmaak_f32 v12, v11, v12, 0x3fb5f0e3
	v_fmaak_f32 v12, v11, v12, 0xbe91a98e
	v_fmaak_f32 v12, v11, v12, 0x3e827906
	v_mul_f32_e32 v11, v11, v12
	v_mul_f32_e64 v12, |v7|, s3
	v_mul_f32_e64 v12, |v7|, v12
	v_exp_f32_e32 v12, v12
	s_nop 0
	v_fma_f32 v11, -v12, v11, 1.0
	v_bfi_b32 v7, s13, v11, v7
	v_add_f32_e32 v7, 1.0, v7
	v_mul_f32_e32 v11, v10, v7
	v_fmac_f32_e32 v11, v9, v8
	s_nop 1
	v_add_f32_dpp v11, v11, v11 row_ror:8 row_mask:0xf bank_mask:0xf bound_ctrl:1
	s_nop 1
	v_add_f32_dpp v11, v11, v11 row_ror:4 row_mask:0xf bank_mask:0xf bound_ctrl:1
	s_nop 1
	v_add_f32_dpp v11, v11, v11 row_ror:2 row_mask:0xf bank_mask:0xf bound_ctrl:1
	s_nop 1
	v_add_f32_dpp v11, v11, v11 row_ror:1 row_mask:0xf bank_mask:0xf bound_ctrl:1
	ds_bpermute_b32 v12, v3, v11
	s_waitcnt lgkmcnt(0)
	v_add_f32_e32 v11, v11, v12
	v_mov_b32_e32 v12, v11
	s_nop 1
	v_permlane32_swap_b32_e32 v11, v12
	v_add_f32_e32 v11, v11, v12
	v_mul_f32_e32 v11, 0x3c000000, v11
	v_fma_f32 v7, v10, v7, -v11
	v_fma_f32 v8, v9, v8, -v11
	v_mul_f32_e32 v9, v7, v7
	v_fmac_f32_e32 v9, v8, v8
	s_nop 1
	v_add_f32_dpp v9, v9, v9 row_ror:8 row_mask:0xf bank_mask:0xf bound_ctrl:1
	s_nop 1
	v_add_f32_dpp v9, v9, v9 row_ror:4 row_mask:0xf bank_mask:0xf bound_ctrl:1
	s_nop 1
	v_add_f32_dpp v9, v9, v9 row_ror:2 row_mask:0xf bank_mask:0xf bound_ctrl:1
	s_nop 1
	v_add_f32_dpp v9, v9, v9 row_ror:1 row_mask:0xf bank_mask:0xf bound_ctrl:1
	ds_bpermute_b32 v10, v3, v9
	s_waitcnt lgkmcnt(0)
	v_add_f32_e32 v9, v9, v10
	v_mov_b32_e32 v10, v9
	s_nop 1
	v_permlane32_swap_b32_e32 v9, v10
	v_add_f32_e32 v9, v9, v10
	v_fmamk_f32 v9, v9, 0x3c000000, v177
	v_cmp_gt_f32_e32 vcc, s16, v9
	v_mul_f32_e32 v10, 0x4b800000, v9
	s_nop 0
	v_cndmask_b32_e32 v9, v9, v10, vcc
	v_rsq_f32_e32 v9, v9
	s_nop 0
	v_mul_f32_e32 v10, 0x45800000, v9
	v_cndmask_b32_e32 v9, v9, v10, vcc
	v_mul_f32_e32 v8, v8, v9
	v_bfe_u32 v10, v8, 16, 1
	v_add3_u32 v8, v8, v10, s83
	v_add_u32_e32 v10, s5, v6
	v_mul_f32_e32 v7, v7, v9
	ds_write_b16_d16_hi v10, v8
	v_bfe_u32 v8, v7, 16, 1
	s_add_i32 s5, s5, 2
	v_add3_u32 v7, v7, v8, s83
	ds_write_b16_d16_hi v10, v7 offset:272
	s_waitcnt vmcnt(1)
	v_lshlrev_b32_e32 v8, 16, v50
	v_mul_f32_e32 v9, 0.5, v8
	v_mul_f32_e32 v8, 0x3f3504f3, v8
	v_fma_f32 v10, |v8|, s2, 1.0
	v_rcp_f32_e32 v10, v10
	v_and_b32_e32 v7, 0xffff0000, v50
	v_fmamk_f32 v11, v10, 0x3f87dc22, v176
	v_fmaak_f32 v11, v10, v11, 0x3fb5f0e3
	v_fmaak_f32 v11, v10, v11, 0xbe91a98e
	v_fmaak_f32 v11, v10, v11, 0x3e827906
	v_mul_f32_e32 v10, v10, v11
	v_mul_f32_e64 v11, |v8|, s3
	v_mul_f32_e64 v11, |v8|, v11
	v_exp_f32_e32 v11, v11
	s_nop 0
	v_fma_f32 v10, -v11, v10, 1.0
	v_bfi_b32 v8, s13, v10, v8
	v_mul_f32_e32 v10, 0.5, v7
	v_mul_f32_e32 v7, 0x3f3504f3, v7
	v_fma_f32 v11, |v7|, s2, 1.0
	v_rcp_f32_e32 v11, v11
	v_add_f32_e32 v8, 1.0, v8
	v_fmamk_f32 v12, v11, 0x3f87dc22, v176
	v_fmaak_f32 v12, v11, v12, 0x3fb5f0e3
	v_fmaak_f32 v12, v11, v12, 0xbe91a98e
	v_fmaak_f32 v12, v11, v12, 0x3e827906
	v_mul_f32_e32 v11, v11, v12
	v_mul_f32_e64 v12, |v7|, s3
	v_mul_f32_e64 v12, |v7|, v12
	v_exp_f32_e32 v12, v12
	s_nop 0
	v_fma_f32 v11, -v12, v11, 1.0
	v_bfi_b32 v7, s13, v11, v7
	v_add_f32_e32 v7, 1.0, v7
	v_mul_f32_e32 v11, v10, v7
	v_fmac_f32_e32 v11, v9, v8
	s_nop 1
	v_add_f32_dpp v11, v11, v11 row_ror:8 row_mask:0xf bank_mask:0xf bound_ctrl:1
	s_nop 1
	v_add_f32_dpp v11, v11, v11 row_ror:4 row_mask:0xf bank_mask:0xf bound_ctrl:1
	s_nop 1
	v_add_f32_dpp v11, v11, v11 row_ror:2 row_mask:0xf bank_mask:0xf bound_ctrl:1
	s_nop 1
	v_add_f32_dpp v11, v11, v11 row_ror:1 row_mask:0xf bank_mask:0xf bound_ctrl:1
	ds_bpermute_b32 v12, v3, v11
	s_waitcnt lgkmcnt(0)
	v_add_f32_e32 v11, v11, v12
	v_mov_b32_e32 v12, v11
	s_nop 1
	v_permlane32_swap_b32_e32 v11, v12
	v_add_f32_e32 v11, v11, v12
	v_mul_f32_e32 v11, 0x3c000000, v11
	v_fma_f32 v7, v10, v7, -v11
	v_fma_f32 v8, v9, v8, -v11
	v_mul_f32_e32 v9, v7, v7
	v_fmac_f32_e32 v9, v8, v8
	s_nop 1
	v_add_f32_dpp v9, v9, v9 row_ror:8 row_mask:0xf bank_mask:0xf bound_ctrl:1
	s_nop 1
	v_add_f32_dpp v9, v9, v9 row_ror:4 row_mask:0xf bank_mask:0xf bound_ctrl:1
	s_nop 1
	v_add_f32_dpp v9, v9, v9 row_ror:2 row_mask:0xf bank_mask:0xf bound_ctrl:1
	s_nop 1
	v_add_f32_dpp v9, v9, v9 row_ror:1 row_mask:0xf bank_mask:0xf bound_ctrl:1
	ds_bpermute_b32 v10, v3, v9
	s_waitcnt lgkmcnt(0)
; DI bf16 f2bf(float f) { unsigned u = __float_as_uint(f); u += 0x7fffu + ((u >> 16) & 1u); return (bf16)(u >> 16); }
; DI float gelu(float x) { return 0.5f * x * (1.f + erf_as(x * 0.70710678118654752f)); }
;   DI bf16* P() const { return (bf16*)(p.ws + WS_P); }
;   DI bf16* VGT() const { return (bf16*)(p.ws + WS_VGT); }
; DI int vblock() { const int G = gridDim.x, b = blockIdx.x; return ((G & 7) == 0) ? (b & 7) * (G >> 3) + (b >> 3) : b; }
; DI void vgt_tile(const Ctx& c, int ti, bf16* lds) {
;     ...
;   for (int rr = 0; rr < 32; ++rr) {
;     const int t = wave * 32 + rr;
;     const unsigned u = *(const unsigned*)(c.P() + (size_t)(row0 + t) * LDP + C_V + g * 128 + 2 * lane);
;     const float a = gelu(__uint_as_float(u << 16)), b = gelu(__uint_as_float(u & 0xffff0000u));
;     const float mean = wave_sum(a + b) * (1.f / 128.f);
;     const float da = a - mean, db = b - mean;
;     const float rstd = rsqrtf(wave_sum(da * da + db * db) * (1.f / 128.f) + LN_EPS);
;     lds[(2 * lane) * LDT + t] = f2bf(da * rstd);
;     lds[(2 * lane + 1) * LDT + t] = f2bf(db * rstd);
;   }
;   __syncthreads();
;   {
;     const int d = tid >> 1, half = tid & 1;
;     bf16* dst = c.VGT() + ((size_t)ti * 128 + d) * 128 + half * 64;
;     const bf16* src = lds + d * LDT + half * 64;
; #pragma unroll
;     for (int i = 0; i < 8; ++i) *(u32x4*)(dst + i * 8) = *(const u32x4*)(src + i * 8);
;   }
;   __syncthreads();
; DI void phase_odd_b(const Ctx& c, int l, bf16* lds) {
;     ...
;   for (int it0 = vblock(); it0 < total; it0 += gridDim.x) {
;     const int it = (it0 < n_ctx) ? (n_s1 + n_sgu + it0) : (it0 < n_ctx + n_sgu ? n_s1 + (it0 - n_ctx) : it0 - n_ctx - n_sgu);
	v_add_f32_e32 v9, v9, v10
	v_mov_b32_e32 v10, v9
	s_nop 1
	v_permlane32_swap_b32_e32 v9, v10
	v_add_f32_e32 v9, v9, v10
	v_fmamk_f32 v9, v9, 0x3c000000, v177
	v_cmp_gt_f32_e32 vcc, s16, v9
	v_mul_f32_e32 v10, 0x4b800000, v9
	s_nop 0
	v_cndmask_b32_e32 v9, v9, v10, vcc
	v_rsq_f32_e32 v9, v9
	s_nop 0
	v_mul_f32_e32 v10, 0x45800000, v9
	v_cndmask_b32_e32 v9, v9, v10, vcc
	v_mul_f32_e32 v8, v8, v9
	v_bfe_u32 v10, v8, 16, 1
	v_add3_u32 v8, v8, v10, s83
	v_add_u32_e32 v10, s5, v6
	v_mul_f32_e32 v7, v7, v9
	ds_write_b16_d16_hi v10, v8
	v_bfe_u32 v8, v7, 16, 1
	s_add_i32 s5, s5, 2
	v_add3_u32 v7, v7, v8, s83
	ds_write_b16_d16_hi v10, v7 offset:272
	s_waitcnt vmcnt(0)
	v_lshlrev_b32_e32 v8, 16, v51
	v_mul_f32_e32 v9, 0.5, v8
	v_mul_f32_e32 v8, 0x3f3504f3, v8
	v_fma_f32 v10, |v8|, s2, 1.0
	v_rcp_f32_e32 v10, v10
	v_and_b32_e32 v7, 0xffff0000, v51
	v_fmamk_f32 v11, v10, 0x3f87dc22, v176
	v_fmaak_f32 v11, v10, v11, 0x3fb5f0e3
	v_fmaak_f32 v11, v10, v11, 0xbe91a98e
	v_fmaak_f32 v11, v10, v11, 0x3e827906
	v_mul_f32_e32 v10, v10, v11
	v_mul_f32_e64 v11, |v8|, s3
	v_mul_f32_e64 v11, |v8|, v11
	v_exp_f32_e32 v11, v11
	s_nop 0
	v_fma_f32 v10, -v11, v10, 1.0
	v_bfi_b32 v8, s13, v10, v8
	v_mul_f32_e32 v10, 0.5, v7
	v_mul_f32_e32 v7, 0x3f3504f3, v7
	v_fma_f32 v11, |v7|, s2, 1.0
	v_rcp_f32_e32 v11, v11
	v_add_f32_e32 v8, 1.0, v8
	v_fmamk_f32 v12, v11, 0x3f87dc22, v176
	v_fmaak_f32 v12, v11, v12, 0x3fb5f0e3
	v_fmaak_f32 v12, v11, v12, 0xbe91a98e
	v_fmaak_f32 v12, v11, v12, 0x3e827906
	v_mul_f32_e32 v11, v11, v12
	v_mul_f32_e64 v12, |v7|, s3
	v_mul_f32_e64 v12, |v7|, v12
	v_exp_f32_e32 v12, v12
	s_nop 0
	v_fma_f32 v11, -v12, v11, 1.0
	v_bfi_b32 v7, s13, v11, v7
	v_add_f32_e32 v7, 1.0, v7
	v_mul_f32_e32 v11, v10, v7
	v_fmac_f32_e32 v11, v9, v8
	s_nop 1
	v_add_f32_dpp v11, v11, v11 row_ror:8 row_mask:0xf bank_mask:0xf bound_ctrl:1
	s_nop 1
	v_add_f32_dpp v11, v11, v11 row_ror:4 row_mask:0xf bank_mask:0xf bound_ctrl:1
	s_nop 1
	v_add_f32_dpp v11, v11, v11 row_ror:2 row_mask:0xf bank_mask:0xf bound_ctrl:1
	s_nop 1
	v_add_f32_dpp v11, v11, v11 row_ror:1 row_mask:0xf bank_mask:0xf bound_ctrl:1
	ds_bpermute_b32 v12, v3, v11
	s_waitcnt lgkmcnt(0)
	v_add_f32_e32 v11, v11, v12
	v_mov_b32_e32 v12, v11
	s_nop 1
	v_permlane32_swap_b32_e32 v11, v12
	v_add_f32_e32 v11, v11, v12
	v_mul_f32_e32 v11, 0x3c000000, v11
	v_fma_f32 v7, v10, v7, -v11
	v_fma_f32 v8, v9, v8, -v11
	v_mul_f32_e32 v9, v7, v7
	v_fmac_f32_e32 v9, v8, v8
	s_nop 1
	v_add_f32_dpp v9, v9, v9 row_ror:8 row_mask:0xf bank_mask:0xf bound_ctrl:1
	s_nop 1
	v_add_f32_dpp v9, v9, v9 row_ror:4 row_mask:0xf bank_mask:0xf bound_ctrl:1
	s_nop 1
	v_add_f32_dpp v9, v9, v9 row_ror:2 row_mask:0xf bank_mask:0xf bound_ctrl:1
	s_nop 1
	v_add_f32_dpp v9, v9, v9 row_ror:1 row_mask:0xf bank_mask:0xf bound_ctrl:1
	ds_bpermute_b32 v10, v3, v9
	s_waitcnt lgkmcnt(0)
	v_add_f32_e32 v9, v9, v10
	v_mov_b32_e32 v10, v9
	s_nop 1
	v_permlane32_swap_b32_e32 v9, v10
	v_add_f32_e32 v9, v9, v10
	v_fmamk_f32 v9, v9, 0x3c000000, v177
	v_cmp_gt_f32_e32 vcc, s16, v9
	v_mul_f32_e32 v10, 0x4b800000, v9
	s_nop 0
	v_cndmask_b32_e32 v9, v9, v10, vcc
	v_rsq_f32_e32 v9, v9
	s_nop 0
	v_mul_f32_e32 v10, 0x45800000, v9
	v_cndmask_b32_e32 v9, v9, v10, vcc
	v_mul_f32_e32 v8, v8, v9
	v_bfe_u32 v10, v8, 16, 1
	v_add3_u32 v8, v8, v10, s83
	v_add_u32_e32 v10, s5, v6
	v_mul_f32_e32 v7, v7, v9
	ds_write_b16_d16_hi v10, v8
	v_bfe_u32 v8, v7, 16, 1
	s_add_i32 s5, s5, 2
	v_add3_u32 v7, v7, v8, s83
	ds_write_b16_d16_hi v10, v7 offset:272
	s_ashr_i32 s5, s4, 31
	s_lshl_b64 s[6:7], s[4:5], 15
	v_readlane_b32 s2, v253, 13
	v_ashrrev_i32_e32 v3, 31, v2
	s_add_u32 s6, s2, s6
	v_readlane_b32 s2, v253, 14
	v_lshlrev_b32_e32 v0, 7, v0
	s_addc_u32 s7, s2, s7
	v_lshlrev_b64 v[4:5], 8, v[2:3]
	v_and_b32_e32 v0, 0x80, v0
	v_lshl_add_u64 v[4:5], s[6:7], 0, v[4:5]
	v_mad_u64_u32 v[20:21], s[6:7], v2, s79, v[0:1]
	s_waitcnt lgkmcnt(0)
	s_barrier
	v_lshl_add_u64 v[18:19], v[4:5], 0, v[0:1]
	ds_read_b128 v[2:5], v20
	ds_read_b128 v[6:9], v20 offset:16
	ds_read_b128 v[10:13], v20 offset:32
	ds_read_b128 v[14:17], v20 offset:48
	s_waitcnt lgkmcnt(3)
	global_store_dwordx4 v[18:19], v[2:5], off
	s_waitcnt lgkmcnt(2)
	global_store_dwordx4 v[18:19], v[6:9], off offset:16
	s_waitcnt lgkmcnt(1)
	global_store_dwordx4 v[18:19], v[10:13], off offset:32
	s_waitcnt lgkmcnt(0)
	global_store_dwordx4 v[18:19], v[14:17], off offset:48
	ds_read_b128 v[2:5], v20 offset:64
	s_waitcnt lgkmcnt(0)
	global_store_dwordx4 v[18:19], v[2:5], off offset:64
	ds_read_b128 v[2:5], v20 offset:80
	s_waitcnt lgkmcnt(0)
	global_store_dwordx4 v[18:19], v[2:5], off offset:80
	ds_read_b128 v[2:5], v20 offset:96
	s_waitcnt lgkmcnt(0)
	global_store_dwordx4 v[18:19], v[2:5], off offset:96
	ds_read_b128 v[2:5], v20 offset:112
	s_waitcnt lgkmcnt(0)
	global_store_dwordx4 v[18:19], v[2:5], off offset:112
	s_barrier
	s_branch .LBB0_312
.LBB0_372:
	s_or_b64 exec, exec, s[4:5]
	s_and_b64 s[4:5], s[0:1], exec
	s_movk_i32 s4, 0x620
	s_cselect_b32 s4, s4, 0x600
	v_readlane_b32 s2, v253, 60
	s_cmp_ge_i32 s2, s4
	s_waitcnt lgkmcnt(0)
	s_barrier
	s_cbranch_scc1 .LBB0_383
	s_and_b64 s[0:1], s[0:1], exec
	s_movk_i32 s0, 0x610
	s_cselect_b32 s6, s0, 0x600
	s_movk_i32 s0, 0x220
	s_cselect_b32 s7, s0, 0x200
	s_movk_i32 s0, 0xfde0
	s_cselect_b32 s8, s0, 0xfffffe00
	s_movk_i32 s0, 0x3f0
	s_cselect_b32 s9, s0, 0x400
	s_movk_i32 s0, 0xf9f0
	s_cselect_b32 s5, 16, 0
	s_cselect_b32 s10, s0, 0xfffffa00
	s_lshl_b32 s0, s86, 1
	s_and_b32 s11, s0, 4
	v_readlane_b32 s12, v253, 60
	s_branch .LBB0_375

; DI unsigned xb_ld(unsigned* p) { return __hip_atomic_load(p, __ATOMIC_RELAXED, __HIP_MEMORY_SCOPE_AGENT); }
; DI unsigned xb_add(unsigned* p, unsigned v) { return __hip_atomic_fetch_add(p, v, __ATOMIC_RELAXED, __HIP_MEMORY_SCOPE_AGENT); }
; #define XB_SPIN(cond, bar) do { unsigned _sp = 0; while (cond) { __builtin_amdgcn_s_sleep(1); \
;     if ((++_sp & 255u) == 0u) { if (xb_ld(&(bar)[XB_TMO])) break; if (_sp > XB_SPIN_CAP) { atomicAdd(&(bar)[XB_TMO], 1u); break; } } } } while (0)
; DI void xcd_barrier(const XcdBarrier& b) {
;   asm volatile("s_waitcnt vmcnt(0)" ::: "memory");
;   __syncthreads();
;   if (threadIdx.x == 0) {
;     unsigned* bar = b.bar;
;     __builtin_amdgcn_s_waitcnt(0);
;     unsigned nloc = b.st[0], nx = b.st[1];
;     if (nloc == 0u) { xcd_barrier_complete(bar, b.x, nloc, nx); b.st[0] = nloc; b.st[1] = nx; }
;     const unsigned old = xb_add(&bar[XB_XSUB(b.x)], 1u);
;     const unsigned gen = old / nloc;
;     if (old + 1u == (gen + 1u) * nloc) {
;       __builtin_amdgcn_fence(__ATOMIC_RELEASE, "agent");
;       asm volatile("s_waitcnt vmcnt(0)" ::: "memory");
;       const unsigned og = xb_add(&bar[XB_TOP], 1u);
;       const unsigned tg = og / nx;
;       if (og + 1u == (tg + 1u) * nx) xb_add(&bar[XB_TOPGEN], 1u);
;       else XB_SPIN(xb_ld(&bar[XB_TOPGEN]) == tg, bar);
;       __builtin_amdgcn_fence(__ATOMIC_ACQUIRE, "agent");
;       xb_add(&bar[XB_XGEN(b.x)], 1u);
.LBB0_383:
	s_getreg_b32 s4, hwreg(HW_REG_XCC_ID, 0, 4)
	s_waitcnt vmcnt(0)
	s_barrier
	s_mov_b64 s[0:1], exec
	v_readlane_b32 s6, v252, 14
	v_readlane_b32 s7, v252, 15
	s_and_b64 s[6:7], s[0:1], s[6:7]
	s_mov_b64 exec, s[6:7]
	s_cbranch_execz .LBB0_435
	s_getreg_b32 s4, hwreg(HW_REG_XCC_ID, 0, 4)
	v_mov_b32_e32 v0, 0x12200
	ds_read_b64 v[2:3], v0
	s_lshl_b32 s4, s4, 8
	s_and_b32 s4, s4, 0xf00
	s_add_u32 s2, s88, s4
	s_addc_u32 s3, s89, 0
	v_mov_b32_e32 v5, 1
	v_mov_b32_e32 v6, 0x1000
	global_atomic_add v5, v6, v5, s[2:3] offset:1024 sc0
	v_readlane_b32 s5, v255, 1
	s_add_i32 s5, s5, 1
	s_nop 0
	v_writelane_b32 v255, s5, 1
	v_mov_b32_e32 v6, 0x3400
	s_waitcnt lgkmcnt(0)
	v_readfirstlane_b32 s6, v2
	v_readfirstlane_b32 s7, v3
	s_mul_i32 s10, s5, s6
	s_mul_i32 s12, s5, s7
	s_mov_b32 s20, 0
	s_waitcnt vmcnt(0)
	v_readfirstlane_b32 s15, v5
	s_add_i32 s15, s15, 1
	s_cmp_lg_u32 s15, s10
	s_cbranch_scc1 .Lsy3_inv
	buffer_wbl2 sc1
	v_mov_b32_e32 v5, 1
	s_waitcnt vmcnt(0)
	global_atomic_add v6, v5, s[88:89]

; DI int vblock() { const int G = gridDim.x, b = blockIdx.x; return ((G & 7) == 0) ? (b & 7) * (G >> 3) + (b >> 3) : b; }
; DI unsigned xb_ld(unsigned* p) { return __hip_atomic_load(p, __ATOMIC_RELAXED, __HIP_MEMORY_SCOPE_AGENT); }
; DI unsigned xb_add(unsigned* p, unsigned v) { return __hip_atomic_fetch_add(p, v, __ATOMIC_RELAXED, __HIP_MEMORY_SCOPE_AGENT); }
; #define XB_SPIN(cond, bar) do { unsigned _sp = 0; while (cond) { __builtin_amdgcn_s_sleep(1); \
;     if ((++_sp & 255u) == 0u) { if (xb_ld(&(bar)[XB_TMO])) break; if (_sp > XB_SPIN_CAP) { atomicAdd(&(bar)[XB_TMO], 1u); break; } } } } while (0)
; DI void phase_odd_c(const Ctx& c, bf16* lds) {
;   for (int it = vblock(); it < 512; it += gridDim.x) {
; DI void xcd_barrier(const XcdBarrier& b) {
;     ...
;       else XB_SPIN(xb_ld(&bar[XB_TOPGEN]) == tg, bar);
;       __builtin_amdgcn_fence(__ATOMIC_ACQUIRE, "agent");
;       xb_add(&bar[XB_XGEN(b.x)], 1u);
;       asm volatile("s_waitcnt vmcnt(0)" ::: "memory");
;     } else {
;       XB_SPIN(xb_ld(&bar[XB_XGEN(b.x)]) == gen, bar);
;       __builtin_amdgcn_fence(__ATOMIC_ACQUIRE, "agent");
;       asm volatile("s_waitcnt vmcnt(0)" ::: "memory");
;     }
;   }
;   __syncthreads();
; }
.Lsy3_poll:
	global_load_dword v5, v6, s[88:89] sc1
	s_waitcnt vmcnt(0)
	v_readfirstlane_b32 s15, v5
	s_sub_i32 s15, s15, s12
	s_cmp_ge_i32 s15, 0
	s_cbranch_scc1 .Lsy3_done
	s_add_i32 s20, s20, 1
	s_sleep 1
	s_cmp_lt_u32 s20, 0x400000
	s_cbranch_scc1 .Lsy3_poll
.Lsy3_done:
.LBB0_435:
	s_or_b64 exec, exec, s[0:1]
	v_readlane_b32 s0, v253, 43
	v_readlane_b32 s1, v253, 44
	v_readlane_b32 s56, v252, 39
	s_mov_b32 s79, s14
	s_mov_b32 s15, s41
	s_mov_b64 s[52:53], s[48:49]
	s_mov_b32 s41, s70
	s_mov_b32 s70, s67
	s_mov_b32 s67, s75
	s_mov_b32 s14, s74
	s_mov_b64 s[74:75], s[94:95]
	s_mov_b32 s97, s65
	s_mov_b32 s84, s64
	s_mov_b64 s[64:65], s[92:93]
	s_mov_b64 s[48:49], s[90:91]
	s_andn2_b64 vcc, exec, s[0:1]
	v_readlane_b32 s4, v253, 61
	v_readlane_b32 s5, v253, 59
	v_readlane_b32 s6, v253, 60
	s_mov_b64 s[2:3], 0x4000
	s_mov_b64 s[26:27], 0x80
	s_mov_b64 s[28:29], 0x4080
	s_mov_b64 s[30:31], 0x8000
	s_mov_b64 s[34:35], 0x8080
	s_mov_b64 s[86:87], 0x100
	s_mov_b64 s[90:91], 0x8100
	s_mov_b64 s[92:93], 0x180
	s_mov_b64 s[94:95], 0x8180
	s_mov_b64 s[46:47], 0xc000
	s_mov_b64 s[36:37], 0xc080
	s_mov_b64 s[42:43], 0x4100
	s_mov_b64 s[38:39], 0xc100
	s_mov_b64 s[50:51], 0x4180
	s_mov_b64 s[54:55], 0xc180
	s_mov_b32 s80, 0x3a800000
	v_readlane_b32 s57, v252, 40
	s_waitcnt lgkmcnt(0)
	s_barrier
	s_cbranch_vccnz .LBB0_437

; DI unsigned xb_ld(unsigned* p) { return __hip_atomic_load(p, __ATOMIC_RELAXED, __HIP_MEMORY_SCOPE_AGENT); }
; DI unsigned xb_add(unsigned* p, unsigned v) { return __hip_atomic_fetch_add(p, v, __ATOMIC_RELAXED, __HIP_MEMORY_SCOPE_AGENT); }
; #define XB_SPIN(cond, bar) do { unsigned _sp = 0; while (cond) { __builtin_amdgcn_s_sleep(1); \
;     if ((++_sp & 255u) == 0u) { if (xb_ld(&(bar)[XB_TMO])) break; if (_sp > XB_SPIN_CAP) { atomicAdd(&(bar)[XB_TMO], 1u); break; } } } } while (0)
; DI void xcd_barrier(const XcdBarrier& b) {
;   asm volatile("s_waitcnt vmcnt(0)" ::: "memory");
;   __syncthreads();
;   if (threadIdx.x == 0) {
;     unsigned* bar = b.bar;
;     __builtin_amdgcn_s_waitcnt(0);
;     unsigned nloc = b.st[0], nx = b.st[1];
;     if (nloc == 0u) { xcd_barrier_complete(bar, b.x, nloc, nx); b.st[0] = nloc; b.st[1] = nx; }
;     const unsigned old = xb_add(&bar[XB_XSUB(b.x)], 1u);
;     const unsigned gen = old / nloc;
;     if (old + 1u == (gen + 1u) * nloc) {
;       __builtin_amdgcn_fence(__ATOMIC_RELEASE, "agent");
;       asm volatile("s_waitcnt vmcnt(0)" ::: "memory");
;       const unsigned og = xb_add(&bar[XB_TOP], 1u);
;       const unsigned tg = og / nx;
;       if (og + 1u == (tg + 1u) * nx) xb_add(&bar[XB_TOPGEN], 1u);
;       else XB_SPIN(xb_ld(&bar[XB_TOPGEN]) == tg, bar);
;       __builtin_amdgcn_fence(__ATOMIC_ACQUIRE, "agent");
;       xb_add(&bar[XB_XGEN(b.x)], 1u);
.LBB0_437:
	s_getreg_b32 s4, hwreg(HW_REG_XCC_ID, 0, 4)
	s_waitcnt vmcnt(0)
	s_barrier
	s_mov_b64 s[0:1], exec
	v_readlane_b32 s6, v252, 14
	v_readlane_b32 s7, v252, 15
	v_readlane_b32 s86, v254, 57
	s_mov_b64 s[90:91], s[48:49]
	s_mov_b64 s[48:49], s[52:53]
	v_readlane_b32 s52, v254, 15
	v_readlane_b32 s56, v254, 20
	v_readlane_b32 s34, v254, 25
	s_and_b64 s[6:7], s[0:1], s[6:7]
	s_mov_b64 s[46:47], 0xc080
	s_mov_b64 s[36:37], 0xc180
	s_mov_b64 s[38:39], 0x4ffff
	s_mov_b64 s[42:43], 0xc0
	s_mov_b64 s[50:51], 0x30000
	s_mov_b64 s[54:55], 0x20080
	v_readlane_b32 s87, v254, 58
	s_mov_b64 s[92:93], s[64:65]
	s_mov_b32 s64, s84
	s_mov_b32 s65, s97
	s_mov_b64 s[94:95], s[74:75]
	s_mov_b32 s74, s14
	s_mov_b32 s75, s67
	s_mov_b32 s67, s70
	s_mov_b32 s70, s41
	v_readlane_b32 s53, v254, 16
	v_readlane_b32 s57, v254, 21
	s_mov_b32 s41, s15
	v_readlane_b32 s35, v254, 26
	s_mov_b32 s14, s79
	s_movk_i32 s79, 0x110
	s_mov_b64 exec, s[6:7]
	s_cbranch_execz .LBB0_489
	s_getreg_b32 s4, hwreg(HW_REG_XCC_ID, 0, 4)
	v_mov_b32_e32 v0, 0x12200
	ds_read_b64 v[2:3], v0
	s_lshl_b32 s4, s4, 8
	s_and_b32 s4, s4, 0xf00
	s_add_u32 s2, s88, s4
	s_addc_u32 s3, s89, 0
	v_mov_b32_e32 v5, 1
	v_mov_b32_e32 v6, 0x1000
	global_atomic_add v5, v6, v5, s[2:3] offset:1024 sc0
	v_readlane_b32 s5, v255, 1
	s_add_i32 s5, s5, 1
	s_nop 0
	v_writelane_b32 v255, s5, 1
	v_mov_b32_e32 v6, 0x3400
	s_waitcnt lgkmcnt(0)
	v_readfirstlane_b32 s6, v2
	v_readfirstlane_b32 s7, v3
	s_mul_i32 s10, s5, s6
	s_mul_i32 s12, s5, s7
	s_mov_b32 s22, 0
	s_waitcnt vmcnt(0)
	v_readfirstlane_b32 s20, v5
	s_add_i32 s20, s20, 1
	s_cmp_lg_u32 s20, s10
	s_cbranch_scc1 .Lsy4_inv
	buffer_wbl2 sc1
	v_mov_b32_e32 v5, 1
	s_waitcnt vmcnt(0)
	global_atomic_add v6, v5, s[88:89]

; DI unsigned xb_ld(unsigned* p) { return __hip_atomic_load(p, __ATOMIC_RELAXED, __HIP_MEMORY_SCOPE_AGENT); }
; DI unsigned xb_add(unsigned* p, unsigned v) { return __hip_atomic_fetch_add(p, v, __ATOMIC_RELAXED, __HIP_MEMORY_SCOPE_AGENT); }
; #define XB_SPIN(cond, bar) do { unsigned _sp = 0; while (cond) { __builtin_amdgcn_s_sleep(1); \
;     if ((++_sp & 255u) == 0u) { if (xb_ld(&(bar)[XB_TMO])) break; if (_sp > XB_SPIN_CAP) { atomicAdd(&(bar)[XB_TMO], 1u); break; } } } } while (0)
; DI void xcd_barrier(const XcdBarrier& b) {
;     ...
;       else XB_SPIN(xb_ld(&bar[XB_TOPGEN]) == tg, bar);
;       __builtin_amdgcn_fence(__ATOMIC_ACQUIRE, "agent");
;       xb_add(&bar[XB_XGEN(b.x)], 1u);
;       asm volatile("s_waitcnt vmcnt(0)" ::: "memory");
;     } else {
;       XB_SPIN(xb_ld(&bar[XB_XGEN(b.x)]) == gen, bar);
;       __builtin_amdgcn_fence(__ATOMIC_ACQUIRE, "agent");
;       asm volatile("s_waitcnt vmcnt(0)" ::: "memory");
;     }
;   }
;   __syncthreads();
; }
.Lsy4_poll:
	global_load_dword v5, v6, s[88:89] sc1
	s_waitcnt vmcnt(0)
	v_readfirstlane_b32 s20, v5
	s_sub_i32 s20, s20, s12
	s_cmp_ge_i32 s20, 0
	s_cbranch_scc1 .Lsy4_done
	s_add_i32 s22, s22, 1
	s_sleep 1
	s_cmp_lt_u32 s22, 0x400000
	s_cbranch_scc1 .Lsy4_poll
.Lsy4_done:
.LBB0_489:
	s_or_b64 exec, exec, s[0:1]
	s_mov_b64 s[0:1], 0
	s_waitcnt lgkmcnt(0)
	s_barrier

; DI unsigned xb_ld(unsigned* p) { return __hip_atomic_load(p, __ATOMIC_RELAXED, __HIP_MEMORY_SCOPE_AGENT); }
; DI unsigned xb_add(unsigned* p, unsigned v) { return __hip_atomic_fetch_add(p, v, __ATOMIC_RELAXED, __HIP_MEMORY_SCOPE_AGENT); }
; #define XB_SPIN(cond, bar) do { unsigned _sp = 0; while (cond) { __builtin_amdgcn_s_sleep(1); \
;     if ((++_sp & 255u) == 0u) { if (xb_ld(&(bar)[XB_TMO])) break; if (_sp > XB_SPIN_CAP) { atomicAdd(&(bar)[XB_TMO], 1u); break; } } } } while (0)
; DI void xcd_barrier(const XcdBarrier& b) {
;   asm volatile("s_waitcnt vmcnt(0)" ::: "memory");
;   __syncthreads();
;   if (threadIdx.x == 0) {
;     unsigned* bar = b.bar;
;     __builtin_amdgcn_s_waitcnt(0);
;     unsigned nloc = b.st[0], nx = b.st[1];
;     if (nloc == 0u) { xcd_barrier_complete(bar, b.x, nloc, nx); b.st[0] = nloc; b.st[1] = nx; }
;     const unsigned old = xb_add(&bar[XB_XSUB(b.x)], 1u);
;     const unsigned gen = old / nloc;
;     if (old + 1u == (gen + 1u) * nloc) {
;       __builtin_amdgcn_fence(__ATOMIC_RELEASE, "agent");
;       asm volatile("s_waitcnt vmcnt(0)" ::: "memory");
;       const unsigned og = xb_add(&bar[XB_TOP], 1u);
;       const unsigned tg = og / nx;
;       if (og + 1u == (tg + 1u) * nx) xb_add(&bar[XB_TOPGEN], 1u);
;       else XB_SPIN(xb_ld(&bar[XB_TOPGEN]) == tg, bar);
;       __builtin_amdgcn_fence(__ATOMIC_ACQUIRE, "agent");
;       xb_add(&bar[XB_XGEN(b.x)], 1u);
.LBB0_516:
	s_getreg_b32 s4, hwreg(HW_REG_XCC_ID, 0, 4)
	s_waitcnt vmcnt(0)
	s_barrier
	s_mov_b64 s[0:1], exec
	v_readlane_b32 s6, v252, 14
	v_readlane_b32 s7, v252, 15
	s_and_b64 s[6:7], s[0:1], s[6:7]
	s_mov_b64 exec, s[6:7]
	s_cbranch_execz .LBB0_568
	s_getreg_b32 s2, hwreg(HW_REG_XCC_ID, 0, 4)
	v_mov_b32_e32 v0, 0x12200
	ds_read_b64 v[2:3], v0
	s_lshl_b32 s2, s2, 8
	s_and_b32 s2, s2, 0xf00
	s_add_u32 s4, s88, s2
	s_addc_u32 s5, s89, 0
	v_mov_b32_e32 v4, 1
	v_mov_b32_e32 v5, 0x1000
	global_atomic_add v4, v5, v4, s[4:5] offset:1024 sc0
	v_readlane_b32 s6, v255, 1
	s_add_i32 s6, s6, 1
	s_nop 0
	v_writelane_b32 v255, s6, 1
	v_mov_b32_e32 v5, 0x3400
	s_waitcnt lgkmcnt(0)
	v_readfirstlane_b32 s7, v2
	v_readfirstlane_b32 s10, v3
	s_mul_i32 s12, s6, s7
	s_mul_i32 s15, s6, s10
	s_mov_b32 s17, 0
	s_waitcnt vmcnt(0)
	v_readfirstlane_b32 s16, v4
	s_add_i32 s16, s16, 1
	s_cmp_lg_u32 s16, s12
	s_cbranch_scc1 .Lsy5_inv
	buffer_wbl2 sc1
	v_mov_b32_e32 v4, 1
	s_waitcnt vmcnt(0)
	global_atomic_add v5, v4, s[88:89]

; DI int vblock() { const int G = gridDim.x, b = blockIdx.x; return ((G & 7) == 0) ? (b & 7) * (G >> 3) + (b >> 3) : b; }
; DI unsigned xb_ld(unsigned* p) { return __hip_atomic_load(p, __ATOMIC_RELAXED, __HIP_MEMORY_SCOPE_AGENT); }
; DI unsigned xb_add(unsigned* p, unsigned v) { return __hip_atomic_fetch_add(p, v, __ATOMIC_RELAXED, __HIP_MEMORY_SCOPE_AGENT); }
; #define XB_SPIN(cond, bar) do { unsigned _sp = 0; while (cond) { __builtin_amdgcn_s_sleep(1); \
;     if ((++_sp & 255u) == 0u) { if (xb_ld(&(bar)[XB_TMO])) break; if (_sp > XB_SPIN_CAP) { atomicAdd(&(bar)[XB_TMO], 1u); break; } } } } while (0)
; DI void phase_even_b(const Ctx& c, int l, bf16* lds) {
;   float* rs = (float*)(lds + GEMM_LDS_BF16);
;   const int qrows = (l == 0) ? MT : MLAT;
;   const int n_q = (qrows / 128) * 6, n_k = 132 * 4, n_v = 132 * 4, n_g1 = 8 * 132;
;   const int total = n_q + n_k + n_v + n_g1;
;   for (int it0 = vblock(); it0 < total; it0 += gridDim.x) {
;     const int it = (it0 < n_g1) ? (n_q + n_k + n_v + it0) : (it0 - n_g1);
; DI void xcd_barrier(const XcdBarrier& b) {
;     ...
;       else XB_SPIN(xb_ld(&bar[XB_TOPGEN]) == tg, bar);
;       __builtin_amdgcn_fence(__ATOMIC_ACQUIRE, "agent");
;       xb_add(&bar[XB_XGEN(b.x)], 1u);
;       asm volatile("s_waitcnt vmcnt(0)" ::: "memory");
;     } else {
;       XB_SPIN(xb_ld(&bar[XB_XGEN(b.x)]) == gen, bar);
;       __builtin_amdgcn_fence(__ATOMIC_ACQUIRE, "agent");
;       asm volatile("s_waitcnt vmcnt(0)" ::: "memory");
;     }
;   }
;   __syncthreads();
; }
.Lsy5_poll:
	global_load_dword v4, v5, s[88:89] sc1
	s_waitcnt vmcnt(0)
	v_readfirstlane_b32 s16, v4
	s_sub_i32 s16, s16, s15
	s_cmp_ge_i32 s16, 0
	s_cbranch_scc1 .Lsy5_done
	s_add_i32 s17, s17, 1
	s_sleep 1
	s_cmp_lt_u32 s17, 0x400000
	s_cbranch_scc1 .Lsy5_poll
.Lsy5_done:
.LBB0_568:
	s_or_b64 exec, exec, s[0:1]
	s_cmp_eq_u32 s86, 0
	s_cselect_b64 s[16:17], -1, 0
	s_and_b64 s[0:1], s[16:17], exec
	s_movk_i32 s0, 0x318
	s_cselect_b32 s15, s0, 0x300
	s_or_b32 s18, s15, 0x840
	v_readlane_b32 s0, v253, 60
	s_cmp_ge_i32 s0, s18
	s_waitcnt lgkmcnt(0)
	s_barrier
	s_cbranch_scc1 .LBB0_737
	s_add_i32 s19, s15, 0x210
	s_or_b32 s20, s15, 0x420
	v_readlane_b32 s21, v253, 60
	s_branch .LBB0_571

; DI unsigned xb_ld(unsigned* p) { return __hip_atomic_load(p, __ATOMIC_RELAXED, __HIP_MEMORY_SCOPE_AGENT); }
; DI unsigned xb_add(unsigned* p, unsigned v) { return __hip_atomic_fetch_add(p, v, __ATOMIC_RELAXED, __HIP_MEMORY_SCOPE_AGENT); }
; #define XB_SPIN(cond, bar) do { unsigned _sp = 0; while (cond) { __builtin_amdgcn_s_sleep(1); \
;     if ((++_sp & 255u) == 0u) { if (xb_ld(&(bar)[XB_TMO])) break; if (_sp > XB_SPIN_CAP) { atomicAdd(&(bar)[XB_TMO], 1u); break; } } } } while (0)
; DI void xcd_barrier(const XcdBarrier& b) {
;   asm volatile("s_waitcnt vmcnt(0)" ::: "memory");
;   __syncthreads();
;   if (threadIdx.x == 0) {
;     unsigned* bar = b.bar;
;     __builtin_amdgcn_s_waitcnt(0);
;     unsigned nloc = b.st[0], nx = b.st[1];
;     if (nloc == 0u) { xcd_barrier_complete(bar, b.x, nloc, nx); b.st[0] = nloc; b.st[1] = nx; }
;     const unsigned old = xb_add(&bar[XB_XSUB(b.x)], 1u);
;     const unsigned gen = old / nloc;
;     if (old + 1u == (gen + 1u) * nloc) {
;       __builtin_amdgcn_fence(__ATOMIC_RELEASE, "agent");
;       asm volatile("s_waitcnt vmcnt(0)" ::: "memory");
;       const unsigned og = xb_add(&bar[XB_TOP], 1u);
;       const unsigned tg = og / nx;
;       if (og + 1u == (tg + 1u) * nx) xb_add(&bar[XB_TOPGEN], 1u);
;       else XB_SPIN(xb_ld(&bar[XB_TOPGEN]) == tg, bar);
;       __builtin_amdgcn_fence(__ATOMIC_ACQUIRE, "agent");
;       xb_add(&bar[XB_XGEN(b.x)], 1u);
.LBB0_742:
	s_or_b64 exec, exec, s[4:5]
	s_getreg_b32 s4, hwreg(HW_REG_XCC_ID, 0, 4)
	s_waitcnt vmcnt(0)
	s_barrier
	s_mov_b64 s[0:1], exec
	v_readlane_b32 s6, v252, 14
	v_readlane_b32 s7, v252, 15
	s_and_b64 s[6:7], s[0:1], s[6:7]
	s_mov_b64 exec, s[6:7]
	s_cbranch_execz .LBB0_794
	s_getreg_b32 s4, hwreg(HW_REG_XCC_ID, 0, 4)
	v_mov_b32_e32 v0, 0x12200
	ds_read_b64 v[2:3], v0
	s_lshl_b32 s4, s4, 8
	s_and_b32 s4, s4, 0xf00
	s_add_u32 s2, s88, s4
	s_addc_u32 s3, s89, 0
	v_mov_b32_e32 v5, 1
	v_mov_b32_e32 v6, 0x1000
	global_atomic_add v5, v6, v5, s[2:3] offset:1024 sc0
	v_readlane_b32 s5, v255, 1
	s_add_i32 s5, s5, 1
	s_nop 0
	v_writelane_b32 v255, s5, 1
	v_mov_b32_e32 v6, 0x3400
	s_waitcnt lgkmcnt(0)
	v_readfirstlane_b32 s6, v2
	v_readfirstlane_b32 s7, v3
	s_mul_i32 s10, s5, s6
	s_mul_i32 s12, s5, s7
	s_mov_b32 s22, 0
	s_waitcnt vmcnt(0)
	v_readfirstlane_b32 s20, v5
	s_add_i32 s20, s20, 1
	s_cmp_lg_u32 s20, s10
	s_cbranch_scc1 .Lsy6_inv
	buffer_wbl2 sc1
	v_mov_b32_e32 v5, 1
	s_waitcnt vmcnt(0)
	global_atomic_add v6, v5, s[88:89]

; DI int otid() { int t = threadIdx.x; asm volatile("" : "+v"(t)); return t; }
; DI unsigned xb_ld(unsigned* p) { return __hip_atomic_load(p, __ATOMIC_RELAXED, __HIP_MEMORY_SCOPE_AGENT); }
; DI unsigned xb_add(unsigned* p, unsigned v) { return __hip_atomic_fetch_add(p, v, __ATOMIC_RELAXED, __HIP_MEMORY_SCOPE_AGENT); }
; #define XB_SPIN(cond, bar) do { unsigned _sp = 0; while (cond) { __builtin_amdgcn_s_sleep(1); \
;     if ((++_sp & 255u) == 0u) { if (xb_ld(&(bar)[XB_TMO])) break; if (_sp > XB_SPIN_CAP) { atomicAdd(&(bar)[XB_TMO], 1u); break; } } } } while (0)
; DI void gla_g2(const Ctx& c) {
;   const int gt = blockIdx.x * NT + otid(), gs = gridDim.x * NT;
;   for (int i = gt; i < 16 * 8192; i += gs) {
; DI void xcd_barrier(const XcdBarrier& b) {
;     ...
;       else XB_SPIN(xb_ld(&bar[XB_TOPGEN]) == tg, bar);
;       __builtin_amdgcn_fence(__ATOMIC_ACQUIRE, "agent");
;       xb_add(&bar[XB_XGEN(b.x)], 1u);
;       asm volatile("s_waitcnt vmcnt(0)" ::: "memory");
;     } else {
;       XB_SPIN(xb_ld(&bar[XB_XGEN(b.x)]) == gen, bar);
;       __builtin_amdgcn_fence(__ATOMIC_ACQUIRE, "agent");
;       asm volatile("s_waitcnt vmcnt(0)" ::: "memory");
;     }
;   }
;   __syncthreads();
; }
.Lsy6_done:
.LBB0_794:
	s_or_b64 exec, exec, s[0:1]
	v_mov_b32_e32 v0, v172
	v_readlane_b32 s0, v252, 32
	s_waitcnt lgkmcnt(0)
	s_barrier
	s_nop 0
	v_add_u32_e32 v5, s0, v0
	s_mov_b32 s0, 0x20000
	v_cmp_gt_i32_e32 vcc, s0, v5
	s_and_saveexec_b64 s[0:1], vcc
	s_cbranch_execz .LBB0_799

; DI unsigned xb_ld(unsigned* p) { return __hip_atomic_load(p, __ATOMIC_RELAXED, __HIP_MEMORY_SCOPE_AGENT); }
; DI unsigned xb_add(unsigned* p, unsigned v) { return __hip_atomic_fetch_add(p, v, __ATOMIC_RELAXED, __HIP_MEMORY_SCOPE_AGENT); }
; #define XB_SPIN(cond, bar) do { unsigned _sp = 0; while (cond) { __builtin_amdgcn_s_sleep(1); \
;     if ((++_sp & 255u) == 0u) { if (xb_ld(&(bar)[XB_TMO])) break; if (_sp > XB_SPIN_CAP) { atomicAdd(&(bar)[XB_TMO], 1u); break; } } } } while (0)
; DI void xcd_barrier(const XcdBarrier& b) {
;   asm volatile("s_waitcnt vmcnt(0)" ::: "memory");
;   __syncthreads();
;   if (threadIdx.x == 0) {
;     unsigned* bar = b.bar;
;     __builtin_amdgcn_s_waitcnt(0);
;     unsigned nloc = b.st[0], nx = b.st[1];
;     if (nloc == 0u) { xcd_barrier_complete(bar, b.x, nloc, nx); b.st[0] = nloc; b.st[1] = nx; }
;     const unsigned old = xb_add(&bar[XB_XSUB(b.x)], 1u);
;     const unsigned gen = old / nloc;
;     if (old + 1u == (gen + 1u) * nloc) {
;       __builtin_amdgcn_fence(__ATOMIC_RELEASE, "agent");
;       asm volatile("s_waitcnt vmcnt(0)" ::: "memory");
;       const unsigned og = xb_add(&bar[XB_TOP], 1u);
;       const unsigned tg = og / nx;
;       if (og + 1u == (tg + 1u) * nx) xb_add(&bar[XB_TOPGEN], 1u);
;       else XB_SPIN(xb_ld(&bar[XB_TOPGEN]) == tg, bar);
;       __builtin_amdgcn_fence(__ATOMIC_ACQUIRE, "agent");
;       xb_add(&bar[XB_XGEN(b.x)], 1u);
.LBB0_804:
	s_getreg_b32 s4, hwreg(HW_REG_XCC_ID, 0, 4)
	s_waitcnt vmcnt(0)
	s_barrier
	s_mov_b64 s[0:1], exec
	v_readlane_b32 s6, v252, 14
	v_readlane_b32 s7, v252, 15
	s_and_b64 s[6:7], s[0:1], s[6:7]
	s_mov_b64 exec, s[6:7]
	s_cbranch_execz .LBB0_882
	s_getreg_b32 s4, hwreg(HW_REG_XCC_ID, 0, 4)
	v_mov_b32_e32 v0, 0x12200
	ds_read_b64 v[2:3], v0
	s_lshl_b32 s4, s4, 8
	s_and_b32 s4, s4, 0xf00
	s_add_u32 s2, s88, s4
	s_addc_u32 s3, s89, 0
	v_mov_b32_e32 v5, 1
	v_mov_b32_e32 v6, 0x1000
	global_atomic_add v5, v6, v5, s[2:3] offset:1024 sc0
	v_readlane_b32 s5, v255, 1
	s_add_i32 s5, s5, 1
	s_nop 0
	v_writelane_b32 v255, s5, 1
	v_mov_b32_e32 v6, 0x3400
	s_waitcnt lgkmcnt(0)
	v_readfirstlane_b32 s10, v2
	v_readfirstlane_b32 s12, v3
	s_mul_i32 s20, s5, s10
	s_mul_i32 s22, s5, s12
	s_mov_b32 s25, 0
	s_waitcnt vmcnt(0)
	v_readfirstlane_b32 s24, v5
	s_add_i32 s24, s24, 1
	s_cmp_lg_u32 s24, s20
	s_cbranch_scc1 .Lsy7_inv
	buffer_wbl2 sc1
	v_mov_b32_e32 v5, 1
	s_waitcnt vmcnt(0)
	global_atomic_add v6, v5, s[88:89]

; DI float silu(float x) { return x * __builtin_amdgcn_rcpf(1.f + __expf(-x)); }
;   DI bf16* HY() const { return (bf16*)(p.ws + WS_HY); }
;   DI bf16* P() const { return (bf16*)(p.ws + WS_P); }
; DI u32x2 pk4(f32x4 v) { return u32x2{pk2(v[0], v[1]), pk2(v[2], v[3])}; }
; DI f32x4 unpk4(u32x2 u) { return f32x4{__uint_as_float(u[0] << 16), __uint_as_float(u[0] & 0xffff0000u), __uint_as_float(u[1] << 16), __uint_as_float(u[1] & 0xffff0000u)}; }
; DI unsigned xb_ld(unsigned* p) { return __hip_atomic_load(p, __ATOMIC_RELAXED, __HIP_MEMORY_SCOPE_AGENT); }
; DI unsigned xb_add(unsigned* p, unsigned v) { return __hip_atomic_fetch_add(p, v, __ATOMIC_RELAXED, __HIP_MEMORY_SCOPE_AGENT); }
; #define XB_SPIN(cond, bar) do { unsigned _sp = 0; while (cond) { __builtin_amdgcn_s_sleep(1); \
;     if ((++_sp & 255u) == 0u) { if (xb_ld(&(bar)[XB_TMO])) break; if (_sp > XB_SPIN_CAP) { atomicAdd(&(bar)[XB_TMO], 1u); break; } } } } while (0)
; DI void attn_item(const Ctx& c, int item, bf16* lds) {
;     ...
;   __syncthreads();
; #pragma unroll
;   for (int qs = 0; qs < 2; ++qs) {
;     const float inv = 1.f / xhalf_sum(lsum[qs]);
;     const int row = rowbase + wave * 64 + qs * 32 + r;
;     const bf16* mg = c.P() + (size_t)row * LDP + C_MG + h * 64;
;     bf16* dst = c.HY() + (size_t)row * D + 512 + h * 64;
; #pragma unroll
;     for (int vt = 0; vt < 2; ++vt)
; #pragma unroll
;       for (int g = 0; g < 4; ++g) {
;         const int vd = 32 * vt + 8 * g + 4 * hh;
;         const f32x4 g4 = unpk4(*(const u32x2*)(mg + vd));
;         f32x4 o = {ot[qs][vt][4 * g] * inv * silu(g4[0]), ot[qs][vt][4 * g + 1] * inv * silu(g4[1]), ot[qs][vt][4 * g + 2] * inv * silu(g4[2]), ot[qs][vt][4 * g + 3] * inv * silu(g4[3])};
;         *(u32x2*)(dst + vd) = pk4(o);
; DI void xcd_barrier(const XcdBarrier& b) {
;     ...
;       else XB_SPIN(xb_ld(&bar[XB_TOPGEN]) == tg, bar);
;       __builtin_amdgcn_fence(__ATOMIC_ACQUIRE, "agent");
;       xb_add(&bar[XB_XGEN(b.x)], 1u);
;       asm volatile("s_waitcnt vmcnt(0)" ::: "memory");
;     } else {
;       XB_SPIN(xb_ld(&bar[XB_XGEN(b.x)]) == gen, bar);
;       __builtin_amdgcn_fence(__ATOMIC_ACQUIRE, "agent");
;       asm volatile("s_waitcnt vmcnt(0)" ::: "memory");
;     }
;   }
;   __syncthreads();
; }
.Lsy7_poll:
	global_load_dword v5, v6, s[88:89] sc1
	s_waitcnt vmcnt(0)
	v_readfirstlane_b32 s24, v5
	s_sub_i32 s24, s24, s22
	s_cmp_ge_i32 s24, 0
	s_cbranch_scc1 .Lsy7_done
	s_add_i32 s25, s25, 1
	s_sleep 1
	s_cmp_lt_u32 s25, 0x400000
	s_cbranch_scc1 .Lsy7_poll
.Lsy7_done:
	s_branch .LBB0_882
.LBB0_807:
	v_mov_b32_e32 v2, v0
	s_nop 1
	v_permlane32_swap_b32_e32 v0, v2
	v_add_f32_e32 v0, v0, v2
	v_div_scale_f32 v2, s[4:5], v0, v0, 1.0
	v_rcp_f32_e32 v3, v2
	s_lshl_b32 s1, s6, 5
	s_and_b32 s1, s1, 0xffffe000
	s_or_b32 s1, s1, s7
	v_fma_f32 v4, -v2, v3, 1.0
	v_fmac_f32_e32 v3, v4, v3
	v_div_scale_f32 v4, vcc, 1.0, v0, 1.0
	v_mul_f32_e32 v5, v4, v3
	v_fma_f32 v6, -v2, v5, v4
	v_fmac_f32_e32 v5, v6, v3
	v_fma_f32 v2, -v2, v5, v4
	v_div_fmas_f32 v2, v2, v3, v5
	v_add_u32_e32 v9, s1, v157
	v_div_fixup_f32 v0, v2, v0, 1.0
	v_mov_b64_e32 v[2:3], s[88:89]
	v_mad_i64_i32 v[4:5], s[4:5], v9, s78, v[2:3]
	s_lshl_b32 s0, s0, 7
	s_mov_b32 s5, s85
	s_and_b32 s4, s0, 0x380
	v_lshl_add_u64 v[6:7], v[4:5], 0, s[4:5]
	s_movk_i32 s2, 0xf400
	v_mov_b32_e32 v157, v1
	v_mad_i64_i32 v[4:5], s[0:1], v9, s2, v[4:5]
	v_lshl_add_u64 v[6:7], v[6:7], 0, v[156:157]
	s_mov_b64 s[8:9], 0x3228f80
	v_lshl_add_u64 v[10:11], v[4:5], 0, s[4:5]
	v_lshl_add_u64 v[4:5], v[6:7], 0, s[8:9]
	v_add_co_u32_e32 v6, vcc, s81, v6
	s_nop 1
	v_addc_co_u32_e32 v7, vcc, 0, v7, vcc
	s_barrier
	global_load_dwordx2 v[6:7], v[6:7], off offset:3968
	v_pk_mul_f32 v[64:65], v[64:65], v[0:1] op_sel_hi:[1,0]
	v_lshl_add_u64 v[10:11], v[10:11], 0, v[156:157]
	s_mov_b64 s[10:11], 0x1128400
	s_mov_b32 s3, 0x1128000
	v_pk_mul_f32 v[48:49], v[48:49], v[0:1] op_sel_hi:[1,0]
	s_add_i32 s6, s6, s40
	s_cmpk_lt_i32 s6, 0x200
	s_waitcnt vmcnt(0)
	v_lshlrev_b32_e32 v12, 16, v6
	v_and_b32_e32 v13, 0xffff0000, v6
	v_mul_f32_e32 v6, 0xbfb8aa3b, v12
	v_exp_f32_e32 v6, v6
	s_nop 0
	v_add_f32_e32 v6, 1.0, v6
	v_rcp_f32_e32 v14, v6
	v_mul_f32_e32 v6, 0xbfb8aa3b, v13
	v_exp_f32_e32 v6, v6
	s_nop 0
	v_add_f32_e32 v6, 1.0, v6
	v_rcp_f32_e32 v15, v6
	v_lshlrev_b32_e32 v6, 16, v7
	v_and_b32_e32 v7, 0xffff0000, v7
	v_pk_mul_f32 v[12:13], v[14:15], v[12:13]
	s_nop 0
	v_pk_mul_f32 v[12:13], v[64:65], v[12:13]
	v_pk_mul_f32 v[64:65], v[66:67], v[0:1] op_sel_hi:[1,0]
	v_cvt_pk_bf16_f32 v12, v12, v13
	v_mul_f32_e32 v13, 0xbfb8aa3b, v6
	v_exp_f32_e32 v13, v13
	s_nop 0
	v_add_f32_e32 v13, 1.0, v13
	v_rcp_f32_e32 v14, v13
	v_mul_f32_e32 v13, 0xbfb8aa3b, v7
	v_exp_f32_e32 v13, v13
	s_nop 0
	v_add_f32_e32 v13, 1.0, v13
	v_rcp_f32_e32 v15, v13
	s_nop 0
	v_pk_mul_f32 v[6:7], v[14:15], v[6:7]
	s_nop 0
	v_pk_mul_f32 v[6:7], v[64:65], v[6:7]
	v_pk_mul_f32 v[64:65], v[68:69], v[0:1] op_sel_hi:[1,0]
	v_cvt_pk_bf16_f32 v13, v6, v7
	v_lshl_add_u64 v[6:7], v[10:11], 0, s[10:11]
	v_add_co_u32_e32 v10, vcc, s3, v10
	s_nop 1
	v_addc_co_u32_e32 v11, vcc, 0, v11, vcc
	global_store_dwordx2 v[10:11], v[12:13], off offset:1024
	global_load_dwordx2 v[10:11], v[4:5], off offset:16
	s_waitcnt vmcnt(0)
	v_lshlrev_b32_e32 v12, 16, v10
	v_and_b32_e32 v13, 0xffff0000, v10
	v_mul_f32_e32 v10, 0xbfb8aa3b, v12
	v_exp_f32_e32 v10, v10
	s_nop 0
	v_add_f32_e32 v10, 1.0, v10
	v_rcp_f32_e32 v14, v10
	v_mul_f32_e32 v10, 0xbfb8aa3b, v13
	v_exp_f32_e32 v10, v10
	s_nop 0
	v_add_f32_e32 v10, 1.0, v10
	v_rcp_f32_e32 v15, v10
	s_nop 0
	v_pk_mul_f32 v[12:13], v[14:15], v[12:13]
	s_nop 0
	v_pk_mul_f32 v[12:13], v[64:65], v[12:13]
	v_pk_mul_f32 v[64:65], v[70:71], v[0:1] op_sel_hi:[1,0]
	v_cvt_pk_bf16_f32 v10, v12, v13
	v_lshlrev_b32_e32 v12, 16, v11
	v_and_b32_e32 v13, 0xffff0000, v11
	v_mul_f32_e32 v11, 0xbfb8aa3b, v12
	v_exp_f32_e32 v11, v11
	s_nop 0
	v_add_f32_e32 v11, 1.0, v11
	v_rcp_f32_e32 v14, v11
	v_mul_f32_e32 v11, 0xbfb8aa3b, v13
	v_exp_f32_e32 v11, v11
	s_nop 0
	v_add_f32_e32 v11, 1.0, v11
	v_rcp_f32_e32 v15, v11
	s_nop 0
	v_pk_mul_f32 v[12:13], v[14:15], v[12:13]
	s_nop 0
	v_pk_mul_f32 v[12:13], v[64:65], v[12:13]
	v_pk_mul_f32 v[64:65], v[72:73], v[0:1] op_sel_hi:[1,0]
	v_cvt_pk_bf16_f32 v11, v12, v13
	global_store_dwordx2 v[6:7], v[10:11], off offset:16
	global_load_dwordx2 v[10:11], v[4:5], off offset:32
	s_waitcnt vmcnt(0)
	v_lshlrev_b32_e32 v12, 16, v10
	v_and_b32_e32 v13, 0xffff0000, v10
	v_mul_f32_e32 v10, 0xbfb8aa3b, v12
	v_exp_f32_e32 v10, v10
	s_nop 0
	v_add_f32_e32 v10, 1.0, v10
	v_rcp_f32_e32 v14, v10
	v_mul_f32_e32 v10, 0xbfb8aa3b, v13
	v_exp_f32_e32 v10, v10
	s_nop 0
	v_add_f32_e32 v10, 1.0, v10
	v_rcp_f32_e32 v15, v10
	s_nop 0
	v_pk_mul_f32 v[12:13], v[14:15], v[12:13]
	s_nop 0
	v_pk_mul_f32 v[12:13], v[64:65], v[12:13]
	v_pk_mul_f32 v[64:65], v[74:75], v[0:1] op_sel_hi:[1,0]
	v_cvt_pk_bf16_f32 v10, v12, v13
	v_lshlrev_b32_e32 v12, 16, v11
	v_and_b32_e32 v13, 0xffff0000, v11
	v_mul_f32_e32 v11, 0xbfb8aa3b, v12
	v_exp_f32_e32 v11, v11
	s_nop 0
	v_add_f32_e32 v11, 1.0, v11
	v_rcp_f32_e32 v14, v11
	v_mul_f32_e32 v11, 0xbfb8aa3b, v13
	v_exp_f32_e32 v11, v11
	s_nop 0
	v_add_f32_e32 v11, 1.0, v11
	v_rcp_f32_e32 v15, v11
	s_nop 0
	v_pk_mul_f32 v[12:13], v[14:15], v[12:13]
	s_nop 0
	v_pk_mul_f32 v[12:13], v[64:65], v[12:13]
	v_pk_mul_f32 v[64:65], v[76:77], v[0:1] op_sel_hi:[1,0]
	v_cvt_pk_bf16_f32 v11, v12, v13
	global_store_dwordx2 v[6:7], v[10:11], off offset:32
	global_load_dwordx2 v[10:11], v[4:5], off offset:48
	s_waitcnt vmcnt(0)
; DI float silu(float x) { return x * __builtin_amdgcn_rcpf(1.f + __expf(-x)); }
;   DI bf16* HY() const { return (bf16*)(p.ws + WS_HY); }
;   DI bf16* P() const { return (bf16*)(p.ws + WS_P); }
; DI u32x2 pk4(f32x4 v) { return u32x2{pk2(v[0], v[1]), pk2(v[2], v[3])}; }
; DI f32x4 unpk4(u32x2 u) { return f32x4{__uint_as_float(u[0] << 16), __uint_as_float(u[0] & 0xffff0000u), __uint_as_float(u[1] << 16), __uint_as_float(u[1] & 0xffff0000u)}; }
; DI void attn_item(const Ctx& c, int item, bf16* lds) {
;     ...
;   for (int qs = 0; qs < 2; ++qs) {
;     const float inv = 1.f / xhalf_sum(lsum[qs]);
;     const int row = rowbase + wave * 64 + qs * 32 + r;
;     const bf16* mg = c.P() + (size_t)row * LDP + C_MG + h * 64;
;     bf16* dst = c.HY() + (size_t)row * D + 512 + h * 64;
; #pragma unroll
;     for (int vt = 0; vt < 2; ++vt)
; #pragma unroll
;       for (int g = 0; g < 4; ++g) {
;         const int vd = 32 * vt + 8 * g + 4 * hh;
;         const f32x4 g4 = unpk4(*(const u32x2*)(mg + vd));
;         f32x4 o = {ot[qs][vt][4 * g] * inv * silu(g4[0]), ot[qs][vt][4 * g + 1] * inv * silu(g4[1]), ot[qs][vt][4 * g + 2] * inv * silu(g4[2]), ot[qs][vt][4 * g + 3] * inv * silu(g4[3])};
;         *(u32x2*)(dst + vd) = pk4(o);
;       }
	v_lshlrev_b32_e32 v12, 16, v10
	v_and_b32_e32 v13, 0xffff0000, v10
	v_mul_f32_e32 v10, 0xbfb8aa3b, v12
	v_exp_f32_e32 v10, v10
	s_nop 0
	v_add_f32_e32 v10, 1.0, v10
	v_rcp_f32_e32 v14, v10
	v_mul_f32_e32 v10, 0xbfb8aa3b, v13
	v_exp_f32_e32 v10, v10
	s_nop 0
	v_add_f32_e32 v10, 1.0, v10
	v_rcp_f32_e32 v15, v10
	s_nop 0
	v_pk_mul_f32 v[12:13], v[14:15], v[12:13]
	s_nop 0
	v_pk_mul_f32 v[12:13], v[64:65], v[12:13]
	v_pk_mul_f32 v[64:65], v[78:79], v[0:1] op_sel_hi:[1,0]
	v_cvt_pk_bf16_f32 v10, v12, v13
	v_lshlrev_b32_e32 v12, 16, v11
	v_and_b32_e32 v13, 0xffff0000, v11
	v_mul_f32_e32 v11, 0xbfb8aa3b, v12
	v_exp_f32_e32 v11, v11
	s_nop 0
	v_add_f32_e32 v11, 1.0, v11
	v_rcp_f32_e32 v14, v11
	v_mul_f32_e32 v11, 0xbfb8aa3b, v13
	v_exp_f32_e32 v11, v11
	s_nop 0
	v_add_f32_e32 v11, 1.0, v11
	v_rcp_f32_e32 v15, v11
	s_nop 0
	v_pk_mul_f32 v[12:13], v[14:15], v[12:13]
	s_nop 0
	v_pk_mul_f32 v[12:13], v[64:65], v[12:13]
	s_nop 0
	v_cvt_pk_bf16_f32 v11, v12, v13
	global_store_dwordx2 v[6:7], v[10:11], off offset:48
	global_load_dwordx2 v[10:11], v[4:5], off offset:64
	s_waitcnt vmcnt(0)
	v_lshlrev_b32_e32 v12, 16, v10
	v_and_b32_e32 v13, 0xffff0000, v10
	v_mul_f32_e32 v10, 0xbfb8aa3b, v12
	v_exp_f32_e32 v10, v10
	s_nop 0
	v_add_f32_e32 v10, 1.0, v10
	v_rcp_f32_e32 v14, v10
	v_mul_f32_e32 v10, 0xbfb8aa3b, v13
	v_exp_f32_e32 v10, v10
	s_nop 0
	v_add_f32_e32 v10, 1.0, v10
	v_rcp_f32_e32 v15, v10
	s_nop 0
	v_pk_mul_f32 v[12:13], v[14:15], v[12:13]
	s_nop 0
	v_pk_mul_f32 v[12:13], v[48:49], v[12:13]
	v_pk_mul_f32 v[48:49], v[50:51], v[0:1] op_sel_hi:[1,0]
	v_cvt_pk_bf16_f32 v10, v12, v13
	v_lshlrev_b32_e32 v12, 16, v11
	v_and_b32_e32 v13, 0xffff0000, v11
	v_mul_f32_e32 v11, 0xbfb8aa3b, v12
	v_exp_f32_e32 v11, v11
	s_nop 0
	v_add_f32_e32 v11, 1.0, v11
	v_rcp_f32_e32 v14, v11
	v_mul_f32_e32 v11, 0xbfb8aa3b, v13
	v_exp_f32_e32 v11, v11
	s_nop 0
	v_add_f32_e32 v11, 1.0, v11
	v_rcp_f32_e32 v15, v11
	s_nop 0
	v_pk_mul_f32 v[12:13], v[14:15], v[12:13]
	s_nop 0
	v_pk_mul_f32 v[12:13], v[48:49], v[12:13]
	v_pk_mul_f32 v[48:49], v[52:53], v[0:1] op_sel_hi:[1,0]
	v_cvt_pk_bf16_f32 v11, v12, v13
	global_store_dwordx2 v[6:7], v[10:11], off offset:64
	global_load_dwordx2 v[10:11], v[4:5], off offset:80
	s_waitcnt vmcnt(0)
	v_lshlrev_b32_e32 v12, 16, v10
	v_and_b32_e32 v13, 0xffff0000, v10
	v_mul_f32_e32 v10, 0xbfb8aa3b, v12
	v_exp_f32_e32 v10, v10
	s_nop 0
	v_add_f32_e32 v10, 1.0, v10
	v_rcp_f32_e32 v14, v10
	v_mul_f32_e32 v10, 0xbfb8aa3b, v13
	v_exp_f32_e32 v10, v10
	s_nop 0
	v_add_f32_e32 v10, 1.0, v10
	v_rcp_f32_e32 v15, v10
	s_nop 0
	v_pk_mul_f32 v[12:13], v[14:15], v[12:13]
	s_nop 0
	v_pk_mul_f32 v[12:13], v[48:49], v[12:13]
	v_pk_mul_f32 v[48:49], v[54:55], v[0:1] op_sel_hi:[1,0]
	v_cvt_pk_bf16_f32 v10, v12, v13
	v_lshlrev_b32_e32 v12, 16, v11
	v_and_b32_e32 v13, 0xffff0000, v11
	v_mul_f32_e32 v11, 0xbfb8aa3b, v12
	v_exp_f32_e32 v11, v11
	s_nop 0
	v_add_f32_e32 v11, 1.0, v11
	v_rcp_f32_e32 v14, v11
	v_mul_f32_e32 v11, 0xbfb8aa3b, v13
	v_exp_f32_e32 v11, v11
	s_nop 0
	v_add_f32_e32 v11, 1.0, v11
	v_rcp_f32_e32 v15, v11
	s_nop 0
	v_pk_mul_f32 v[12:13], v[14:15], v[12:13]
	s_nop 0
	v_pk_mul_f32 v[12:13], v[48:49], v[12:13]
	v_pk_mul_f32 v[48:49], v[56:57], v[0:1] op_sel_hi:[1,0]
	v_cvt_pk_bf16_f32 v11, v12, v13
	global_store_dwordx2 v[6:7], v[10:11], off offset:80
	global_load_dwordx2 v[10:11], v[4:5], off offset:96
	s_waitcnt vmcnt(0)
	v_lshlrev_b32_e32 v12, 16, v10
	global_load_dwordx2 v[4:5], v[4:5], off offset:112
	v_and_b32_e32 v13, 0xffff0000, v10
	v_mul_f32_e32 v10, 0xbfb8aa3b, v12
	v_exp_f32_e32 v10, v10
	s_nop 0
	v_add_f32_e32 v10, 1.0, v10
	v_rcp_f32_e32 v14, v10
	v_mul_f32_e32 v10, 0xbfb8aa3b, v13
	v_exp_f32_e32 v10, v10
	s_nop 0
	v_add_f32_e32 v10, 1.0, v10
	v_rcp_f32_e32 v15, v10
	s_nop 0
	v_pk_mul_f32 v[12:13], v[14:15], v[12:13]
	s_nop 0
	v_pk_mul_f32 v[12:13], v[48:49], v[12:13]
	v_pk_mul_f32 v[48:49], v[58:59], v[0:1] op_sel_hi:[1,0]
	v_cvt_pk_bf16_f32 v10, v12, v13
	v_lshlrev_b32_e32 v12, 16, v11
	v_and_b32_e32 v13, 0xffff0000, v11
	v_mul_f32_e32 v11, 0xbfb8aa3b, v12
	v_exp_f32_e32 v11, v11
	s_nop 0
	v_add_f32_e32 v11, 1.0, v11
	v_rcp_f32_e32 v14, v11
	v_mul_f32_e32 v11, 0xbfb8aa3b, v13
	v_exp_f32_e32 v11, v11
	s_nop 0
	v_add_f32_e32 v11, 1.0, v11
	v_rcp_f32_e32 v15, v11
	s_nop 0
	v_pk_mul_f32 v[12:13], v[14:15], v[12:13]
	s_nop 0
	v_pk_mul_f32 v[12:13], v[48:49], v[12:13]
	v_pk_mul_f32 v[14:15], v[60:61], v[0:1] op_sel_hi:[1,0]
	v_cvt_pk_bf16_f32 v11, v12, v13
	global_store_dwordx2 v[6:7], v[10:11], off offset:96
	s_waitcnt vmcnt(1)
	v_lshlrev_b32_e32 v10, 16, v4
	v_and_b32_e32 v11, 0xffff0000, v4
	v_mul_f32_e32 v4, 0xbfb8aa3b, v10
	v_exp_f32_e32 v4, v4
	s_nop 0
	v_add_f32_e32 v4, 1.0, v4
	v_rcp_f32_e32 v12, v4
	v_mul_f32_e32 v4, 0xbfb8aa3b, v11
	v_exp_f32_e32 v4, v4
	s_nop 0
	v_add_f32_e32 v4, 1.0, v4
	v_rcp_f32_e32 v13, v4
	s_nop 0
	v_pk_mul_f32 v[10:11], v[12:13], v[10:11]
	s_nop 0
	v_pk_mul_f32 v[10:11], v[14:15], v[10:11]
	v_pk_mul_f32 v[14:15], v[62:63], v[0:1] op_sel_hi:[1,0]
	v_cvt_pk_bf16_f32 v4, v10, v11
	v_lshlrev_b32_e32 v10, 16, v5
	v_and_b32_e32 v11, 0xffff0000, v5
	v_mul_f32_e32 v5, 0xbfb8aa3b, v10
	v_mul_f32_e32 v0, 0xbfb8aa3b, v11
	v_exp_f32_e32 v5, v5
	v_exp_f32_e32 v0, v0
	v_add_f32_e32 v5, 1.0, v5
	v_add_f32_e32 v0, 1.0, v0
	v_rcp_f32_e32 v12, v5
	v_rcp_f32_e32 v13, v0
	v_mov_b32_e32 v0, v8
	s_nop 1
	v_permlane32_swap_b32_e32 v8, v0
	v_pk_mul_f32 v[10:11], v[12:13], v[10:11]
	v_add_f32_e32 v0, v8, v0
	v_pk_mul_f32 v[10:11], v[14:15], v[10:11]
	s_nop 0
	v_cvt_pk_bf16_f32 v5, v10, v11
	global_store_dwordx2 v[6:7], v[4:5], off offset:112
	v_div_scale_f32 v4, s[0:1], v0, v0, 1.0
	v_rcp_f32_e32 v5, v4
	s_nop 0
	v_fma_f32 v6, -v4, v5, 1.0
	v_fmac_f32_e32 v5, v6, v5
	v_div_scale_f32 v6, vcc, 1.0, v0, 1.0
	v_mul_f32_e32 v7, v6, v5
	v_fma_f32 v8, -v4, v7, v6
	v_fmac_f32_e32 v7, v8, v5
	v_fma_f32 v4, -v4, v7, v6
	v_or_b32_e32 v6, 32, v9
	v_div_fmas_f32 v4, v4, v5, v7
	v_mad_i64_i32 v[2:3], s[0:1], v6, s78, v[2:3]
	v_div_fixup_f32 v0, v4, v0, 1.0
	v_lshl_add_u64 v[4:5], v[2:3], 0, s[4:5]
	v_mad_i64_i32 v[2:3], s[0:1], v6, s2, v[2:3]
	v_lshl_add_u64 v[6:7], v[4:5], 0, v[156:157]
	v_lshl_add_u64 v[4:5], v[6:7], 0, s[8:9]
	v_add_co_u32_e32 v6, vcc, s81, v6
	v_pk_mul_f32 v[12:13], v[32:33], v[0:1] op_sel_hi:[1,0]
	s_nop 0
	v_addc_co_u32_e32 v7, vcc, 0, v7, vcc
	global_load_dwordx2 v[6:7], v[6:7], off offset:3968
	v_lshl_add_u64 v[2:3], v[2:3], 0, s[4:5]
	s_waitcnt vmcnt(0)
; DI float silu(float x) { return x * __builtin_amdgcn_rcpf(1.f + __expf(-x)); }
;   DI bf16* HY() const { return (bf16*)(p.ws + WS_HY); }
;   DI bf16* P() const { return (bf16*)(p.ws + WS_P); }
; DI u32x2 pk4(f32x4 v) { return u32x2{pk2(v[0], v[1]), pk2(v[2], v[3])}; }
; DI f32x4 unpk4(u32x2 u) { return f32x4{__uint_as_float(u[0] << 16), __uint_as_float(u[0] & 0xffff0000u), __uint_as_float(u[1] << 16), __uint_as_float(u[1] & 0xffff0000u)}; }
; DI void attn_item(const Ctx& c, int item, bf16* lds) {
;     ...
;   for (int qs = 0; qs < 2; ++qs) {
;     const float inv = 1.f / xhalf_sum(lsum[qs]);
;     const int row = rowbase + wave * 64 + qs * 32 + r;
;     const bf16* mg = c.P() + (size_t)row * LDP + C_MG + h * 64;
;     bf16* dst = c.HY() + (size_t)row * D + 512 + h * 64;
; #pragma unroll
;     for (int vt = 0; vt < 2; ++vt)
; #pragma unroll
;       for (int g = 0; g < 4; ++g) {
;         const int vd = 32 * vt + 8 * g + 4 * hh;
;         const f32x4 g4 = unpk4(*(const u32x2*)(mg + vd));
;         f32x4 o = {ot[qs][vt][4 * g] * inv * silu(g4[0]), ot[qs][vt][4 * g + 1] * inv * silu(g4[1]), ot[qs][vt][4 * g + 2] * inv * silu(g4[2]), ot[qs][vt][4 * g + 3] * inv * silu(g4[3])};
;         *(u32x2*)(dst + vd) = pk4(o);
;       }
	v_lshlrev_b32_e32 v8, 16, v6
	v_and_b32_e32 v9, 0xffff0000, v6
	v_mul_f32_e32 v6, 0xbfb8aa3b, v8
	v_exp_f32_e32 v6, v6
	s_nop 0
	v_add_f32_e32 v6, 1.0, v6
	v_rcp_f32_e32 v10, v6
	v_mul_f32_e32 v6, 0xbfb8aa3b, v9
	v_exp_f32_e32 v6, v6
	s_nop 0
	v_add_f32_e32 v6, 1.0, v6
	v_rcp_f32_e32 v11, v6
	s_nop 0
	v_pk_mul_f32 v[8:9], v[10:11], v[8:9]
	s_nop 0
	v_pk_mul_f32 v[8:9], v[12:13], v[8:9]
	v_pk_mul_f32 v[12:13], v[34:35], v[0:1] op_sel_hi:[1,0]
	v_cvt_pk_bf16_f32 v6, v8, v9
	v_lshlrev_b32_e32 v8, 16, v7
	v_and_b32_e32 v9, 0xffff0000, v7
	v_mul_f32_e32 v7, 0xbfb8aa3b, v8
	v_exp_f32_e32 v7, v7
	s_nop 0
	v_add_f32_e32 v7, 1.0, v7
	v_rcp_f32_e32 v10, v7
	v_mul_f32_e32 v7, 0xbfb8aa3b, v9
	v_exp_f32_e32 v7, v7
	s_nop 0
	v_add_f32_e32 v7, 1.0, v7
	v_rcp_f32_e32 v11, v7
	s_nop 0
	v_pk_mul_f32 v[8:9], v[10:11], v[8:9]
	s_nop 0
	v_pk_mul_f32 v[8:9], v[12:13], v[8:9]
	v_pk_mul_f32 v[12:13], v[36:37], v[0:1] op_sel_hi:[1,0]
	v_cvt_pk_bf16_f32 v7, v8, v9
	v_lshl_add_u64 v[8:9], v[2:3], 0, v[156:157]
	v_lshl_add_u64 v[2:3], v[8:9], 0, s[10:11]
	v_add_co_u32_e32 v8, vcc, s3, v8
	s_nop 1
	v_addc_co_u32_e32 v9, vcc, 0, v9, vcc
	global_store_dwordx2 v[8:9], v[6:7], off offset:1024
	global_load_dwordx2 v[6:7], v[4:5], off offset:16
	s_waitcnt vmcnt(0)
	v_lshlrev_b32_e32 v8, 16, v6
	v_and_b32_e32 v9, 0xffff0000, v6
	v_mul_f32_e32 v6, 0xbfb8aa3b, v8
	v_exp_f32_e32 v6, v6
	s_nop 0
	v_add_f32_e32 v6, 1.0, v6
	v_rcp_f32_e32 v10, v6
	v_mul_f32_e32 v6, 0xbfb8aa3b, v9
	v_exp_f32_e32 v6, v6
	s_nop 0
	v_add_f32_e32 v6, 1.0, v6
	v_rcp_f32_e32 v11, v6
	s_nop 0
	v_pk_mul_f32 v[8:9], v[10:11], v[8:9]
	s_nop 0
	v_pk_mul_f32 v[8:9], v[12:13], v[8:9]
	v_pk_mul_f32 v[12:13], v[38:39], v[0:1] op_sel_hi:[1,0]
	v_cvt_pk_bf16_f32 v6, v8, v9
	v_lshlrev_b32_e32 v8, 16, v7
	v_and_b32_e32 v9, 0xffff0000, v7
	v_mul_f32_e32 v7, 0xbfb8aa3b, v8
	v_exp_f32_e32 v7, v7
	s_nop 0
	v_add_f32_e32 v7, 1.0, v7
	v_rcp_f32_e32 v10, v7
	v_mul_f32_e32 v7, 0xbfb8aa3b, v9
	v_exp_f32_e32 v7, v7
	s_nop 0
	v_add_f32_e32 v7, 1.0, v7
	v_rcp_f32_e32 v11, v7
	s_nop 0
	v_pk_mul_f32 v[8:9], v[10:11], v[8:9]
	s_nop 0
	v_pk_mul_f32 v[8:9], v[12:13], v[8:9]
	v_pk_mul_f32 v[12:13], v[40:41], v[0:1] op_sel_hi:[1,0]
	v_cvt_pk_bf16_f32 v7, v8, v9
	global_store_dwordx2 v[2:3], v[6:7], off offset:16
	global_load_dwordx2 v[6:7], v[4:5], off offset:32
	s_waitcnt vmcnt(0)
	v_lshlrev_b32_e32 v8, 16, v6
	v_and_b32_e32 v9, 0xffff0000, v6
	v_mul_f32_e32 v6, 0xbfb8aa3b, v8
	v_exp_f32_e32 v6, v6
	s_nop 0
	v_add_f32_e32 v6, 1.0, v6
	v_rcp_f32_e32 v10, v6
	v_mul_f32_e32 v6, 0xbfb8aa3b, v9
	v_exp_f32_e32 v6, v6
	s_nop 0
	v_add_f32_e32 v6, 1.0, v6
	v_rcp_f32_e32 v11, v6
	s_nop 0
	v_pk_mul_f32 v[8:9], v[10:11], v[8:9]
	s_nop 0
	v_pk_mul_f32 v[8:9], v[12:13], v[8:9]
	v_pk_mul_f32 v[12:13], v[42:43], v[0:1] op_sel_hi:[1,0]
	v_cvt_pk_bf16_f32 v6, v8, v9
	v_lshlrev_b32_e32 v8, 16, v7
	v_and_b32_e32 v9, 0xffff0000, v7
	v_mul_f32_e32 v7, 0xbfb8aa3b, v8
	v_exp_f32_e32 v7, v7
	s_nop 0
	v_add_f32_e32 v7, 1.0, v7
	v_rcp_f32_e32 v10, v7
	v_mul_f32_e32 v7, 0xbfb8aa3b, v9
	v_exp_f32_e32 v7, v7
	s_nop 0
	v_add_f32_e32 v7, 1.0, v7
	v_rcp_f32_e32 v11, v7
	s_nop 0
	v_pk_mul_f32 v[8:9], v[10:11], v[8:9]
	s_nop 0
	v_pk_mul_f32 v[8:9], v[12:13], v[8:9]
	v_pk_mul_f32 v[12:13], v[44:45], v[0:1] op_sel_hi:[1,0]
	v_cvt_pk_bf16_f32 v7, v8, v9
	global_store_dwordx2 v[2:3], v[6:7], off offset:32
	global_load_dwordx2 v[6:7], v[4:5], off offset:48
	s_waitcnt vmcnt(0)
	v_lshlrev_b32_e32 v8, 16, v6
	v_and_b32_e32 v9, 0xffff0000, v6
	v_mul_f32_e32 v6, 0xbfb8aa3b, v8
	v_exp_f32_e32 v6, v6
	s_nop 0
	v_add_f32_e32 v6, 1.0, v6
	v_rcp_f32_e32 v10, v6
	v_mul_f32_e32 v6, 0xbfb8aa3b, v9
	v_exp_f32_e32 v6, v6
	s_nop 0
	v_add_f32_e32 v6, 1.0, v6
	v_rcp_f32_e32 v11, v6
	s_nop 0
	v_pk_mul_f32 v[8:9], v[10:11], v[8:9]
	s_nop 0
	v_pk_mul_f32 v[8:9], v[12:13], v[8:9]
	v_pk_mul_f32 v[12:13], v[46:47], v[0:1] op_sel_hi:[1,0]
	v_cvt_pk_bf16_f32 v6, v8, v9
	v_lshlrev_b32_e32 v8, 16, v7
	v_and_b32_e32 v9, 0xffff0000, v7
	v_mul_f32_e32 v7, 0xbfb8aa3b, v8
	v_exp_f32_e32 v7, v7
	s_nop 0
	v_add_f32_e32 v7, 1.0, v7
	v_rcp_f32_e32 v10, v7
	v_mul_f32_e32 v7, 0xbfb8aa3b, v9
	v_exp_f32_e32 v7, v7
	s_nop 0
	v_add_f32_e32 v7, 1.0, v7
	v_rcp_f32_e32 v11, v7
	s_nop 0
	v_pk_mul_f32 v[8:9], v[10:11], v[8:9]
	s_nop 0
	v_pk_mul_f32 v[8:9], v[12:13], v[8:9]
	v_pk_mul_f32 v[12:13], v[16:17], v[0:1] op_sel_hi:[1,0]
	v_cvt_pk_bf16_f32 v7, v8, v9
	global_store_dwordx2 v[2:3], v[6:7], off offset:48
	global_load_dwordx2 v[6:7], v[4:5], off offset:64
	s_waitcnt vmcnt(0)
; DI float silu(float x) { return x * __builtin_amdgcn_rcpf(1.f + __expf(-x)); }
;   DI bf16* HY() const { return (bf16*)(p.ws + WS_HY); }
;   DI bf16* P() const { return (bf16*)(p.ws + WS_P); }
; DI u32x2 pk4(f32x4 v) { return u32x2{pk2(v[0], v[1]), pk2(v[2], v[3])}; }
; DI f32x4 unpk4(u32x2 u) { return f32x4{__uint_as_float(u[0] << 16), __uint_as_float(u[0] & 0xffff0000u), __uint_as_float(u[1] << 16), __uint_as_float(u[1] & 0xffff0000u)}; }
; DI void attn_item(const Ctx& c, int item, bf16* lds) {
;     ...
;   for (int qs = 0; qs < 2; ++qs) {
;     const float inv = 1.f / xhalf_sum(lsum[qs]);
;     const int row = rowbase + wave * 64 + qs * 32 + r;
;     const bf16* mg = c.P() + (size_t)row * LDP + C_MG + h * 64;
;     bf16* dst = c.HY() + (size_t)row * D + 512 + h * 64;
; #pragma unroll
;     for (int vt = 0; vt < 2; ++vt)
; #pragma unroll
;       for (int g = 0; g < 4; ++g) {
;         const int vd = 32 * vt + 8 * g + 4 * hh;
;         const f32x4 g4 = unpk4(*(const u32x2*)(mg + vd));
;         f32x4 o = {ot[qs][vt][4 * g] * inv * silu(g4[0]), ot[qs][vt][4 * g + 1] * inv * silu(g4[1]), ot[qs][vt][4 * g + 2] * inv * silu(g4[2]), ot[qs][vt][4 * g + 3] * inv * silu(g4[3])};
;         *(u32x2*)(dst + vd) = pk4(o);
;       }
	v_lshlrev_b32_e32 v8, 16, v6
	v_and_b32_e32 v9, 0xffff0000, v6
	v_mul_f32_e32 v6, 0xbfb8aa3b, v8
	v_exp_f32_e32 v6, v6
	s_nop 0
	v_add_f32_e32 v6, 1.0, v6
	v_rcp_f32_e32 v10, v6
	v_mul_f32_e32 v6, 0xbfb8aa3b, v9
	v_exp_f32_e32 v6, v6
	s_nop 0
	v_add_f32_e32 v6, 1.0, v6
	v_rcp_f32_e32 v11, v6
	s_nop 0
	v_pk_mul_f32 v[8:9], v[10:11], v[8:9]
	s_nop 0
	v_pk_mul_f32 v[8:9], v[12:13], v[8:9]
	v_pk_mul_f32 v[12:13], v[18:19], v[0:1] op_sel_hi:[1,0]
	v_cvt_pk_bf16_f32 v6, v8, v9
	v_lshlrev_b32_e32 v8, 16, v7
	v_and_b32_e32 v9, 0xffff0000, v7
	v_mul_f32_e32 v7, 0xbfb8aa3b, v8
	v_exp_f32_e32 v7, v7
	s_nop 0
	v_add_f32_e32 v7, 1.0, v7
	v_rcp_f32_e32 v10, v7
	v_mul_f32_e32 v7, 0xbfb8aa3b, v9
	v_exp_f32_e32 v7, v7
	s_nop 0
	v_add_f32_e32 v7, 1.0, v7
	v_rcp_f32_e32 v11, v7
	s_nop 0
	v_pk_mul_f32 v[8:9], v[10:11], v[8:9]
	s_nop 0
	v_pk_mul_f32 v[8:9], v[12:13], v[8:9]
	v_pk_mul_f32 v[12:13], v[20:21], v[0:1] op_sel_hi:[1,0]
	v_cvt_pk_bf16_f32 v7, v8, v9
	global_store_dwordx2 v[2:3], v[6:7], off offset:64
	global_load_dwordx2 v[6:7], v[4:5], off offset:80
	s_waitcnt vmcnt(0)
	v_lshlrev_b32_e32 v8, 16, v6
	v_and_b32_e32 v9, 0xffff0000, v6
	v_mul_f32_e32 v6, 0xbfb8aa3b, v8
	v_exp_f32_e32 v6, v6
	s_nop 0
	v_add_f32_e32 v6, 1.0, v6
	v_rcp_f32_e32 v10, v6
	v_mul_f32_e32 v6, 0xbfb8aa3b, v9
	v_exp_f32_e32 v6, v6
	s_nop 0
	v_add_f32_e32 v6, 1.0, v6
	v_rcp_f32_e32 v11, v6
	s_nop 0
	v_pk_mul_f32 v[8:9], v[10:11], v[8:9]
	s_nop 0
	v_pk_mul_f32 v[8:9], v[12:13], v[8:9]
	v_pk_mul_f32 v[12:13], v[22:23], v[0:1] op_sel_hi:[1,0]
	v_cvt_pk_bf16_f32 v6, v8, v9
	v_lshlrev_b32_e32 v8, 16, v7
	v_and_b32_e32 v9, 0xffff0000, v7
	v_mul_f32_e32 v7, 0xbfb8aa3b, v8
	v_exp_f32_e32 v7, v7
	s_nop 0
	v_add_f32_e32 v7, 1.0, v7
	v_rcp_f32_e32 v10, v7
	v_mul_f32_e32 v7, 0xbfb8aa3b, v9
	v_exp_f32_e32 v7, v7
	s_nop 0
	v_add_f32_e32 v7, 1.0, v7
	v_rcp_f32_e32 v11, v7
	s_nop 0
	v_pk_mul_f32 v[8:9], v[10:11], v[8:9]
	s_nop 0
	v_pk_mul_f32 v[8:9], v[12:13], v[8:9]
	v_pk_mul_f32 v[12:13], v[24:25], v[0:1] op_sel_hi:[1,0]
	v_cvt_pk_bf16_f32 v7, v8, v9
	global_store_dwordx2 v[2:3], v[6:7], off offset:80
	global_load_dwordx2 v[6:7], v[4:5], off offset:96
	s_waitcnt vmcnt(0)
	v_lshlrev_b32_e32 v8, 16, v6
	global_load_dwordx2 v[4:5], v[4:5], off offset:112
	v_and_b32_e32 v9, 0xffff0000, v6
	v_mul_f32_e32 v6, 0xbfb8aa3b, v8
	v_exp_f32_e32 v6, v6
	s_nop 0
	v_add_f32_e32 v6, 1.0, v6
	v_rcp_f32_e32 v10, v6
	v_mul_f32_e32 v6, 0xbfb8aa3b, v9
	v_exp_f32_e32 v6, v6
	s_nop 0
	v_add_f32_e32 v6, 1.0, v6
	v_rcp_f32_e32 v11, v6
	s_nop 0
	v_pk_mul_f32 v[8:9], v[10:11], v[8:9]
	s_nop 0
	v_pk_mul_f32 v[8:9], v[12:13], v[8:9]
	v_pk_mul_f32 v[12:13], v[26:27], v[0:1] op_sel_hi:[1,0]
	v_cvt_pk_bf16_f32 v6, v8, v9
	v_lshlrev_b32_e32 v8, 16, v7
	v_and_b32_e32 v9, 0xffff0000, v7
	v_mul_f32_e32 v7, 0xbfb8aa3b, v8
	v_exp_f32_e32 v7, v7
	s_nop 0
	v_add_f32_e32 v7, 1.0, v7
	v_rcp_f32_e32 v10, v7
	v_mul_f32_e32 v7, 0xbfb8aa3b, v9
	v_exp_f32_e32 v7, v7
	s_nop 0
	v_add_f32_e32 v7, 1.0, v7
	v_rcp_f32_e32 v11, v7
	s_nop 0
	v_pk_mul_f32 v[8:9], v[10:11], v[8:9]
	s_nop 0
	v_pk_mul_f32 v[8:9], v[12:13], v[8:9]
	v_pk_mul_f32 v[10:11], v[28:29], v[0:1] op_sel_hi:[1,0]
	v_cvt_pk_bf16_f32 v7, v8, v9
	global_store_dwordx2 v[2:3], v[6:7], off offset:96
	s_waitcnt vmcnt(1)
	v_lshlrev_b32_e32 v6, 16, v4
	v_and_b32_e32 v7, 0xffff0000, v4
	v_mul_f32_e32 v4, 0xbfb8aa3b, v6
	v_exp_f32_e32 v4, v4
	s_nop 0
	v_add_f32_e32 v4, 1.0, v4
	v_rcp_f32_e32 v8, v4
	v_mul_f32_e32 v4, 0xbfb8aa3b, v7
	v_exp_f32_e32 v4, v4
	s_nop 0
	v_add_f32_e32 v4, 1.0, v4
	v_rcp_f32_e32 v9, v4
	s_nop 0
	v_pk_mul_f32 v[6:7], v[8:9], v[6:7]
	s_nop 0
	v_pk_mul_f32 v[6:7], v[10:11], v[6:7]
	v_pk_mul_f32 v[10:11], v[30:31], v[0:1] op_sel_hi:[1,0]
	v_cvt_pk_bf16_f32 v4, v6, v7
	v_lshlrev_b32_e32 v6, 16, v5
	v_and_b32_e32 v7, 0xffff0000, v5
	v_mul_f32_e32 v5, 0xbfb8aa3b, v6
	v_mul_f32_e32 v0, 0xbfb8aa3b, v7
	v_exp_f32_e32 v5, v5
	v_exp_f32_e32 v0, v0
	v_add_f32_e32 v5, 1.0, v5
	v_add_f32_e32 v0, 1.0, v0
	v_rcp_f32_e32 v8, v5
	v_rcp_f32_e32 v9, v0
	s_nop 0
	v_pk_mul_f32 v[6:7], v[8:9], v[6:7]
	s_nop 0
	v_pk_mul_f32 v[6:7], v[10:11], v[6:7]
	s_nop 0
	v_cvt_pk_bf16_f32 v5, v6, v7
	global_store_dwordx2 v[2:3], v[4:5], off offset:112
	s_cbranch_scc0 .LBB0_801

; DI int vblock() { const int G = gridDim.x, b = blockIdx.x; return ((G & 7) == 0) ? (b & 7) * (G >> 3) + (b >> 3) : b; }
; DI void attn_item(const Ctx& c, int item, bf16* lds) {
;     ...
;       if (__builtin_amdgcn_ballot_w64((kt == 0) ? (fabsf(mx) > 16.f) : (mx > 16.f)) != 0ull) {
;         const float d = (kt == 0) ? mx : fmaxf(mx, 0.f);
;         const float alpha = __builtin_amdgcn_exp2f(-d);
;         m[qs] += d; lsum[qs] *= alpha;
; #pragma unroll
;         for (int i = 0; i < 16; ++i) { ot[qs][0][i] *= alpha; ot[qs][1][i] *= alpha; st[0][i] -= d; st[1][i] -= d; }
;       }
; DI void phase_even_d(const Ctx& c, int l, bf16* lds) {
;   const int n_ctx = (l == 0 ? 16 : 0), n_g3 = 8 * ((l == 0) ? 132 : 128);
;   for (int it = vblock(); it < n_ctx + n_g3; it += gridDim.x) {
;     if (it < n_ctx) attn_item(c, 512 + it, lds);
;     else gla_g3_item(c, l, it - n_ctx, lds);
;   }
.Lattn_21_B_rare:
	s_mov_b32 s12, 1
	v_mov_b32_e32 v191, v185
	s_nop 1
	v_permlane32_swap_b32_e32 v185, v191
	v_max_f32_e32 v185, v185, v191
	v_max_f32_e32 v197, 0, v185
	v_exp_f32_e64 v198, -v197
	v_add_f32_e32 v201, v201, v197
	v_sub_f32_e32 v96, v96, v197
	v_sub_f32_e32 v97, v97, v197
	v_sub_f32_e32 v98, v98, v197
	v_sub_f32_e32 v99, v99, v197
	v_sub_f32_e32 v100, v100, v197
	v_sub_f32_e32 v101, v101, v197
	v_sub_f32_e32 v102, v102, v197
	v_sub_f32_e32 v103, v103, v197
	v_sub_f32_e32 v104, v104, v197
	v_sub_f32_e32 v105, v105, v197
	v_sub_f32_e32 v106, v106, v197
	v_sub_f32_e32 v107, v107, v197
	v_sub_f32_e32 v108, v108, v197
	v_sub_f32_e32 v109, v109, v197
	v_sub_f32_e32 v110, v110, v197
	v_sub_f32_e32 v111, v111, v197
	v_mul_f32_e32 v203, v203, v198
	v_mul_f32_e32 v32, v32, v198
	v_mul_f32_e32 v33, v33, v198
	v_mul_f32_e32 v34, v34, v198
	v_mul_f32_e32 v35, v35, v198
	v_mul_f32_e32 v36, v36, v198
	v_mul_f32_e32 v37, v37, v198
	v_mul_f32_e32 v38, v38, v198
	v_mul_f32_e32 v39, v39, v198
	v_mul_f32_e32 v40, v40, v198
	v_mul_f32_e32 v41, v41, v198
	v_mul_f32_e32 v42, v42, v198
	v_mul_f32_e32 v43, v43, v198
	v_mul_f32_e32 v44, v44, v198
	v_mul_f32_e32 v45, v45, v198
	v_mul_f32_e32 v46, v46, v198
	v_mul_f32_e32 v47, v47, v198
	v_mul_f32_e32 v16, v16, v198
	v_mul_f32_e32 v17, v17, v198
	v_mul_f32_e32 v18, v18, v198
	v_mul_f32_e32 v19, v19, v198
	v_mul_f32_e32 v20, v20, v198
	v_mul_f32_e32 v21, v21, v198
	v_mul_f32_e32 v22, v22, v198
	v_mul_f32_e32 v23, v23, v198
	v_mul_f32_e32 v24, v24, v198
	v_mul_f32_e32 v25, v25, v198
	v_mul_f32_e32 v26, v26, v198
	v_mul_f32_e32 v27, v27, v198
	v_mul_f32_e32 v28, v28, v198
	v_mul_f32_e32 v29, v29, v198
	v_mul_f32_e32 v30, v30, v198
	v_mul_f32_e32 v31, v31, v198
	s_branch .Lattn_21_B_back
.LBB0_882:
	s_or_b64 exec, exec, s[0:1]
	s_and_b64 s[0:1], s[16:17], exec
	s_movk_i32 s0, 0x430
	s_cselect_b32 s1, s0, 0x400
	v_readlane_b32 s0, v253, 60
	v_writelane_b32 v254, s1, 59
	s_cmp_ge_i32 s0, s1
	s_waitcnt lgkmcnt(0)
	s_barrier
	s_cbranch_scc1 .LBB0_1022
	s_and_b64 s[0:1], s[16:17], exec
	v_readlane_b32 s0, v254, 49
	v_readlane_b32 s1, v254, 50
	s_cselect_b32 s18, 16, 0
	s_lshl_b32 s1, s0, 9
	s_lshl_b32 s84, s0, 7
	v_readlane_b32 s44, v252, 16
	v_writelane_b32 v254, s1, 60
	s_lshl_b64 s[0:1], s[84:85], 2
	v_readlane_b32 s50, v252, 22
	v_readlane_b32 s51, v252, 23
	s_add_u32 s0, s50, s0
	s_addc_u32 s1, s51, s1
	s_and_b64 s[4:5], s[16:17], exec
	v_writelane_b32 v254, s0, 61
	s_movk_i32 s4, 0x84
	v_readlane_b32 s45, v252, 17
	v_writelane_b32 v254, s1, 62
	s_cselect_b32 s0, s4, 0x80
	v_cvt_f32_ubyte0_e32 v159, s0
	v_rcp_iflag_f32_e32 v161, v159
	v_writelane_b32 v254, s0, 63
	v_readlane_b32 s0, v253, 60
	s_mov_b32 s84, s0
	v_writelane_b32 v255, s18, 0
	v_readlane_b32 s46, v252, 18
	v_readlane_b32 s47, v252, 19
	v_readlane_b32 s48, v252, 20
	v_readlane_b32 s49, v252, 21
	v_readlane_b32 s52, v252, 24
	v_readlane_b32 s53, v252, 25
	v_readlane_b32 s54, v252, 26
	v_readlane_b32 s55, v252, 27
	v_readlane_b32 s56, v252, 28
	v_readlane_b32 s57, v252, 29
	v_readlane_b32 s58, v252, 30
	v_readlane_b32 s59, v252, 31
	s_branch .LBB0_886

; DI unsigned xb_ld(unsigned* p) { return __hip_atomic_load(p, __ATOMIC_RELAXED, __HIP_MEMORY_SCOPE_AGENT); }
; DI unsigned xb_add(unsigned* p, unsigned v) { return __hip_atomic_fetch_add(p, v, __ATOMIC_RELAXED, __HIP_MEMORY_SCOPE_AGENT); }
; #define XB_SPIN(cond, bar) do { unsigned _sp = 0; while (cond) { __builtin_amdgcn_s_sleep(1); \
;     if ((++_sp & 255u) == 0u) { if (xb_ld(&(bar)[XB_TMO])) break; if (_sp > XB_SPIN_CAP) { atomicAdd(&(bar)[XB_TMO], 1u); break; } } } } while (0)
; DI void xcd_barrier(const XcdBarrier& b) {
;   asm volatile("s_waitcnt vmcnt(0)" ::: "memory");
;   __syncthreads();
;   if (threadIdx.x == 0) {
;     unsigned* bar = b.bar;
;     __builtin_amdgcn_s_waitcnt(0);
;     unsigned nloc = b.st[0], nx = b.st[1];
;     if (nloc == 0u) { xcd_barrier_complete(bar, b.x, nloc, nx); b.st[0] = nloc; b.st[1] = nx; }
;     const unsigned old = xb_add(&bar[XB_XSUB(b.x)], 1u);
;     const unsigned gen = old / nloc;
;     if (old + 1u == (gen + 1u) * nloc) {
;       __builtin_amdgcn_fence(__ATOMIC_RELEASE, "agent");
;       asm volatile("s_waitcnt vmcnt(0)" ::: "memory");
;       const unsigned og = xb_add(&bar[XB_TOP], 1u);
;       const unsigned tg = og / nx;
;       if (og + 1u == (tg + 1u) * nx) xb_add(&bar[XB_TOPGEN], 1u);
;       else XB_SPIN(xb_ld(&bar[XB_TOPGEN]) == tg, bar);
;       __builtin_amdgcn_fence(__ATOMIC_ACQUIRE, "agent");
;       xb_add(&bar[XB_XGEN(b.x)], 1u);
.LBB0_1022:
	s_getreg_b32 s4, hwreg(HW_REG_XCC_ID, 0, 4)
	s_waitcnt vmcnt(0)
	s_barrier
	s_mov_b64 s[0:1], exec
	v_readlane_b32 s6, v252, 14
	v_readlane_b32 s7, v252, 15
	s_and_b64 s[6:7], s[0:1], s[6:7]
	s_mov_b64 exec, s[6:7]
	s_cbranch_execz .LBB0_1074
	s_getreg_b32 s4, hwreg(HW_REG_XCC_ID, 0, 4)
	v_mov_b32_e32 v0, 0x12200
	ds_read_b64 v[2:3], v0
	s_lshl_b32 s4, s4, 8
	s_and_b32 s4, s4, 0xf00
	s_add_u32 s2, s88, s4
	s_addc_u32 s3, s89, 0
	v_mov_b32_e32 v5, 1
	v_mov_b32_e32 v6, 0x1000
	global_atomic_add v5, v6, v5, s[2:3] offset:1024 sc0
	v_readlane_b32 s5, v255, 1
	s_add_i32 s5, s5, 1
	s_nop 0
	v_writelane_b32 v255, s5, 1
	v_mov_b32_e32 v6, 0x3400
	s_waitcnt lgkmcnt(0)
	v_readfirstlane_b32 s6, v2
	v_readfirstlane_b32 s7, v3
	s_mul_i32 s8, s5, s6
	s_mul_i32 s9, s5, s7
	s_mov_b32 s12, 0
	s_waitcnt vmcnt(0)
	v_readfirstlane_b32 s10, v5
	s_add_i32 s10, s10, 1
	s_cmp_lg_u32 s10, s8
	s_cbranch_scc1 .Lsy8_inv
	buffer_wbl2 sc1
	v_mov_b32_e32 v5, 1
	s_waitcnt vmcnt(0)
	global_atomic_add v6, v5, s[88:89]

; DI unsigned xb_ld(unsigned* p) { return __hip_atomic_load(p, __ATOMIC_RELAXED, __HIP_MEMORY_SCOPE_AGENT); }
; DI unsigned xb_add(unsigned* p, unsigned v) { return __hip_atomic_fetch_add(p, v, __ATOMIC_RELAXED, __HIP_MEMORY_SCOPE_AGENT); }
; #define XB_SPIN(cond, bar) do { unsigned _sp = 0; while (cond) { __builtin_amdgcn_s_sleep(1); \
;     if ((++_sp & 255u) == 0u) { if (xb_ld(&(bar)[XB_TMO])) break; if (_sp > XB_SPIN_CAP) { atomicAdd(&(bar)[XB_TMO], 1u); break; } } } } while (0)
; DI void xcd_barrier(const XcdBarrier& b) {
;     ...
;       else XB_SPIN(xb_ld(&bar[XB_TOPGEN]) == tg, bar);
;       __builtin_amdgcn_fence(__ATOMIC_ACQUIRE, "agent");
;       xb_add(&bar[XB_XGEN(b.x)], 1u);
;       asm volatile("s_waitcnt vmcnt(0)" ::: "memory");
;     } else {
;       XB_SPIN(xb_ld(&bar[XB_XGEN(b.x)]) == gen, bar);
;       __builtin_amdgcn_fence(__ATOMIC_ACQUIRE, "agent");
;       asm volatile("s_waitcnt vmcnt(0)" ::: "memory");
;     }
;   }
;   __syncthreads();
; }
.Lsy8_poll:
	global_load_dword v5, v6, s[88:89] sc1
	s_waitcnt vmcnt(0)
	v_readfirstlane_b32 s10, v5
	s_sub_i32 s10, s10, s9
	s_cmp_ge_i32 s10, 0
	s_cbranch_scc1 .Lsy8_done
	s_add_i32 s12, s12, 1
	s_sleep 1
	s_cmp_lt_u32 s12, 0x400000
	s_cbranch_scc1 .Lsy8_poll
.Lsy8_done:
.LBB0_1074:
	s_or_b64 exec, exec, s[0:1]
	s_waitcnt lgkmcnt(0)
	s_barrier

; DI unsigned xb_ld(unsigned* p) { return __hip_atomic_load(p, __ATOMIC_RELAXED, __HIP_MEMORY_SCOPE_AGENT); }
; DI unsigned xb_add(unsigned* p, unsigned v) { return __hip_atomic_fetch_add(p, v, __ATOMIC_RELAXED, __HIP_MEMORY_SCOPE_AGENT); }
; #define XB_SPIN(cond, bar) do { unsigned _sp = 0; while (cond) { __builtin_amdgcn_s_sleep(1); \
;     if ((++_sp & 255u) == 0u) { if (xb_ld(&(bar)[XB_TMO])) break; if (_sp > XB_SPIN_CAP) { atomicAdd(&(bar)[XB_TMO], 1u); break; } } } } while (0)
; DI void xcd_barrier(const XcdBarrier& b) {
;   asm volatile("s_waitcnt vmcnt(0)" ::: "memory");
;   __syncthreads();
;   if (threadIdx.x == 0) {
;     unsigned* bar = b.bar;
;     __builtin_amdgcn_s_waitcnt(0);
;     unsigned nloc = b.st[0], nx = b.st[1];
;     if (nloc == 0u) { xcd_barrier_complete(bar, b.x, nloc, nx); b.st[0] = nloc; b.st[1] = nx; }
;     const unsigned old = xb_add(&bar[XB_XSUB(b.x)], 1u);
;     const unsigned gen = old / nloc;
;     if (old + 1u == (gen + 1u) * nloc) {
;       __builtin_amdgcn_fence(__ATOMIC_RELEASE, "agent");
;       asm volatile("s_waitcnt vmcnt(0)" ::: "memory");
;       const unsigned og = xb_add(&bar[XB_TOP], 1u);
;       const unsigned tg = og / nx;
;       if (og + 1u == (tg + 1u) * nx) xb_add(&bar[XB_TOPGEN], 1u);
;       else XB_SPIN(xb_ld(&bar[XB_TOPGEN]) == tg, bar);
;       __builtin_amdgcn_fence(__ATOMIC_ACQUIRE, "agent");
;       xb_add(&bar[XB_XGEN(b.x)], 1u);
.LBB0_1118:
	s_getreg_b32 s6, hwreg(HW_REG_XCC_ID, 0, 4)
	s_waitcnt vmcnt(0)
	s_barrier
	s_mov_b64 s[0:1], exec
	v_readlane_b32 s8, v252, 14
	v_readlane_b32 s9, v252, 15
	s_and_b64 s[8:9], s[0:1], s[8:9]
	s_mov_b64 exec, s[8:9]
	s_cbranch_execz .LBB0_1170
	s_getreg_b32 s6, hwreg(HW_REG_XCC_ID, 0, 4)
	v_mov_b32_e32 v0, 0x12200
	ds_read_b64 v[2:3], v0
	s_lshl_b32 s6, s6, 8
	s_and_b32 s6, s6, 0xf00
	s_add_u32 s2, s88, s6
	s_addc_u32 s3, s89, 0
	v_mov_b32_e32 v5, 1
	v_mov_b32_e32 v6, 0x1000
	global_atomic_add v5, v6, v5, s[2:3] offset:1024 sc0
	v_readlane_b32 s7, v255, 1
	s_add_i32 s7, s7, 1
	s_nop 0
	v_writelane_b32 v255, s7, 1
	v_mov_b32_e32 v6, 0x3400
	s_waitcnt lgkmcnt(0)
	v_readfirstlane_b32 s8, v2
	v_readfirstlane_b32 s9, v3
	s_mul_i32 s10, s7, s8
	s_mul_i32 s12, s7, s9
	s_mov_b32 s20, 0
	s_waitcnt vmcnt(0)
	v_readfirstlane_b32 s14, v5
	s_add_i32 s14, s14, 1
	s_cmp_lg_u32 s14, s10
	s_cbranch_scc1 .Lsy9_inv
	buffer_wbl2 sc1
	v_mov_b32_e32 v5, 1
	s_waitcnt vmcnt(0)
	global_atomic_add v6, v5, s[88:89]

; DI int otid() { int t = threadIdx.x; asm volatile("" : "+v"(t)); return t; }
; DI unsigned xb_ld(unsigned* p) { return __hip_atomic_load(p, __ATOMIC_RELAXED, __HIP_MEMORY_SCOPE_AGENT); }
; DI unsigned xb_add(unsigned* p, unsigned v) { return __hip_atomic_fetch_add(p, v, __ATOMIC_RELAXED, __HIP_MEMORY_SCOPE_AGENT); }
; #define XB_SPIN(cond, bar) do { unsigned _sp = 0; while (cond) { __builtin_amdgcn_s_sleep(1); \
;     if ((++_sp & 255u) == 0u) { if (xb_ld(&(bar)[XB_TMO])) break; if (_sp > XB_SPIN_CAP) { atomicAdd(&(bar)[XB_TMO], 1u); break; } } } } while (0)
; DI void phase_ln(const Ctx& c, int l_post, int l_next) {
;   const int tid = otid(), lane = tid & 63;
;   const int wv = (blockIdx.x * NT + tid) >> 6, nw = (gridDim.x * NT) >> 6;
;   for (int row = wv; row < MT; row += 2 * nw) { ln_row(c, row, l_post, l_next, lane); if (row + nw < MT) ln_row(c, row + nw, l_post, l_next, lane); }
; DI void xcd_barrier(const XcdBarrier& b) {
;   asm volatile("s_waitcnt vmcnt(0)" ::: "memory");
;   __syncthreads();
;   if (threadIdx.x == 0) {
;     unsigned* bar = b.bar;
;     __builtin_amdgcn_s_waitcnt(0);
;     unsigned nloc = b.st[0], nx = b.st[1];
;     if (nloc == 0u) { xcd_barrier_complete(bar, b.x, nloc, nx); b.st[0] = nloc; b.st[1] = nx; }
;     const unsigned old = xb_add(&bar[XB_XSUB(b.x)], 1u);
;     const unsigned gen = old / nloc;
;     if (old + 1u == (gen + 1u) * nloc) {
;       __builtin_amdgcn_fence(__ATOMIC_RELEASE, "agent");
;       asm volatile("s_waitcnt vmcnt(0)" ::: "memory");
;       const unsigned og = xb_add(&bar[XB_TOP], 1u);
;       const unsigned tg = og / nx;
;       if (og + 1u == (tg + 1u) * nx) xb_add(&bar[XB_TOPGEN], 1u);
;       else XB_SPIN(xb_ld(&bar[XB_TOPGEN]) == tg, bar);
;       __builtin_amdgcn_fence(__ATOMIC_ACQUIRE, "agent");
;       xb_add(&bar[XB_XGEN(b.x)], 1u);
;       asm volatile("s_waitcnt vmcnt(0)" ::: "memory");
;     } else {
;       XB_SPIN(xb_ld(&bar[XB_XGEN(b.x)]) == gen, bar);
;       __builtin_amdgcn_fence(__ATOMIC_ACQUIRE, "agent");
;       asm volatile("s_waitcnt vmcnt(0)" ::: "memory");
;     }
;   }
;   __syncthreads();
; }
.Lsy9_poll:
	global_load_dword v5, v6, s[88:89] sc1
	s_waitcnt vmcnt(0)
	v_readfirstlane_b32 s14, v5
	s_sub_i32 s14, s14, s12
	s_cmp_ge_i32 s14, 0
	s_cbranch_scc1 .Lsy9_done
	s_add_i32 s20, s20, 1
	s_sleep 1
	s_cmp_lt_u32 s20, 0x400000
	s_cbranch_scc1 .Lsy9_poll
.Lsy9_done:
.LBB0_1170:
	s_or_b64 exec, exec, s[0:1]
	v_mov_b32_e32 v0, v172
	v_readlane_b32 s0, v252, 32
	s_waitcnt lgkmcnt(0)
	s_barrier
	s_add_u32 s6, s86, 1
	s_addc_u32 s7, s87, 0
	v_add_u32_e32 v2, s0, v0
	s_mov_b32 s0, 0x108000
	v_cmp_gt_u32_e32 vcc, s0, v2
	s_and_saveexec_b64 s[8:9], vcc
	s_cbranch_execz .LBB0_1180
	v_readlane_b32 s0, v254, 55
	v_readlane_b32 s1, v254, 56
	s_and_b64 s[0:1], s[0:1], exec
	s_cselect_b32 s20, -1, s6
	s_cmp_lt_u32 s86, 2
	s_cselect_b64 s[10:11], -1, 0
	s_cmp_gt_i32 s20, -1
	s_cselect_b64 s[12:13], -1, 0
	s_cmp_lt_i32 s20, 3
	s_cselect_b64 s[14:15], -1, 0
	s_mov_b32 s1, s85
	s_lshl_b32 s0, s86, 10
	v_readlane_b32 s44, v252, 41
	v_readlane_b32 s16, v254, 22
	s_lshl_b64 s[0:1], s[0:1], 2
	v_readlane_b32 s48, v252, 45
	v_readlane_b32 s49, v252, 46
	v_readlane_b32 s56, v252, 53
	v_readlane_b32 s17, v254, 23
	v_readlane_b32 s57, v252, 54
	s_mov_b64 s[48:49], s[16:17]
	s_add_u32 s16, s56, s0
	v_lshlrev_b32_e32 v0, 2, v0
	v_readlane_b32 s58, v252, 55
	s_addc_u32 s17, s57, s1
	v_lshrrev_b32_e32 v3, 6, v2
	v_and_b32_e32 v2, 0xfc, v0
	v_readlane_b32 s59, v252, 56
	s_add_u32 s0, s58, s0
	v_readlane_b32 s45, v252, 42
	v_readlane_b32 s52, v252, 49
	v_readlane_b32 s53, v252, 50
	v_readlane_b32 s18, v254, 20
	v_lshlrev_b32_e32 v0, 2, v2
	s_addc_u32 s1, s59, s1
	v_readlane_b32 s46, v252, 43
	v_readlane_b32 s47, v252, 44
	v_readlane_b32 s50, v252, 47
	v_readlane_b32 s51, v252, 48
	v_readlane_b32 s54, v252, 51
	v_readlane_b32 s55, v252, 52
	v_readlane_b32 s52, v254, 15
	v_readlane_b32 s94, v254, 13
	v_readlane_b32 s92, v254, 11
	v_readlane_b32 s90, v254, 9
	v_readlane_b32 s19, v254, 21
	v_readlane_b32 s44, v254, 18
	v_readlane_b32 s34, v254, 25
	v_lshl_add_u64 v[10:11], s[16:17], 0, v[0:1]
	v_readlane_b32 s58, v254, 27
	v_lshl_add_u64 v[12:13], s[0:1], 0, v[0:1]
	v_lshlrev_b32_e32 v0, 1, v2
	v_or_b32_e32 v4, 0x100, v2
	v_or_b32_e32 v6, 0x200, v2
	v_or_b32_e32 v8, 0x300, v2
	s_mul_i32 s20, s20, 3
	s_mov_b64 s[54:55], 0x20080
	s_mov_b64 s[50:51], 0x30000
	s_mov_b64 s[42:43], 0xc0
	s_mov_b64 s[38:39], 0x4ffff
	s_mov_b64 s[36:37], 0xc180
	s_mov_b64 s[46:47], 0xc080
	v_readlane_b32 s2, v254, 17
	v_readlane_b32 s53, v254, 16
	v_readlane_b32 s95, v254, 14
	v_readlane_b32 s93, v254, 12
	v_readlane_b32 s91, v254, 10
	v_readlane_b32 s45, v254, 19
	v_readlane_b32 s41, v254, 24
	s_mov_b64 s[56:57], s[18:19]
	v_readlane_b32 s35, v254, 26
	v_readlane_b32 s59, v254, 28
	v_lshl_add_u64 v[14:15], s[60:61], 0, v[0:1]
	v_lshlrev_b32_e32 v16, 11, v3
	s_mov_b64 s[16:17], 0

; DI unsigned xb_ld(unsigned* p) { return __hip_atomic_load(p, __ATOMIC_RELAXED, __HIP_MEMORY_SCOPE_AGENT); }
; DI unsigned xb_add(unsigned* p, unsigned v) { return __hip_atomic_fetch_add(p, v, __ATOMIC_RELAXED, __HIP_MEMORY_SCOPE_AGENT); }
; #define XB_SPIN(cond, bar) do { unsigned _sp = 0; while (cond) { __builtin_amdgcn_s_sleep(1); \
;     if ((++_sp & 255u) == 0u) { if (xb_ld(&(bar)[XB_TMO])) break; if (_sp > XB_SPIN_CAP) { atomicAdd(&(bar)[XB_TMO], 1u); break; } } } } while (0)
; DI void xcd_barrier(const XcdBarrier& b) {
;   asm volatile("s_waitcnt vmcnt(0)" ::: "memory");
;   __syncthreads();
;   if (threadIdx.x == 0) {
;     unsigned* bar = b.bar;
;     __builtin_amdgcn_s_waitcnt(0);
;     unsigned nloc = b.st[0], nx = b.st[1];
;     if (nloc == 0u) { xcd_barrier_complete(bar, b.x, nloc, nx); b.st[0] = nloc; b.st[1] = nx; }
;     const unsigned old = xb_add(&bar[XB_XSUB(b.x)], 1u);
;     const unsigned gen = old / nloc;
;     if (old + 1u == (gen + 1u) * nloc) {
;       __builtin_amdgcn_fence(__ATOMIC_RELEASE, "agent");
;       asm volatile("s_waitcnt vmcnt(0)" ::: "memory");
;       const unsigned og = xb_add(&bar[XB_TOP], 1u);
;       const unsigned tg = og / nx;
;       if (og + 1u == (tg + 1u) * nx) xb_add(&bar[XB_TOPGEN], 1u);
;       else XB_SPIN(xb_ld(&bar[XB_TOPGEN]) == tg, bar);
;       __builtin_amdgcn_fence(__ATOMIC_ACQUIRE, "agent");
;       xb_add(&bar[XB_XGEN(b.x)], 1u);
.LBB0_1182:
	s_getreg_b32 s4, hwreg(HW_REG_XCC_ID, 0, 4)
	v_mov_b32_e32 v5, 0x12200
	ds_read_b64 v[2:3], v5
	s_lshl_b32 s4, s4, 8
	s_and_b32 s4, s4, 0xf00
	s_add_u32 s2, s88, s4
	s_addc_u32 s3, s89, 0
	v_mov_b32_e32 v6, 1
	v_mov_b32_e32 v7, 0x1000
	global_atomic_add v6, v7, v6, s[2:3] offset:1024 sc0
	v_readlane_b32 s5, v255, 1
	s_add_i32 s5, s5, 1
	s_nop 0
	v_writelane_b32 v255, s5, 1
	v_mov_b32_e32 v7, 0x3400
	s_waitcnt lgkmcnt(0)
	v_readfirstlane_b32 s10, v2
	v_readfirstlane_b32 s12, v3
	s_mul_i32 s14, s5, s10
	s_mul_i32 s20, s5, s12
	s_mov_b32 s24, 0
	s_waitcnt vmcnt(0)
	v_readfirstlane_b32 s22, v6
	s_add_i32 s22, s22, 1
	s_cmp_lg_u32 s22, s14
	s_cbranch_scc1 .Lsy10_inv
	buffer_wbl2 sc1
	v_mov_b32_e32 v6, 1
	s_waitcnt vmcnt(0)
	global_atomic_add v7, v6, s[88:89]

; DI unsigned xb_ld(unsigned* p) { return __hip_atomic_load(p, __ATOMIC_RELAXED, __HIP_MEMORY_SCOPE_AGENT); }
; DI unsigned xb_add(unsigned* p, unsigned v) { return __hip_atomic_fetch_add(p, v, __ATOMIC_RELAXED, __HIP_MEMORY_SCOPE_AGENT); }
; #define XB_SPIN(cond, bar) do { unsigned _sp = 0; while (cond) { __builtin_amdgcn_s_sleep(1); \
;     if ((++_sp & 255u) == 0u) { if (xb_ld(&(bar)[XB_TMO])) break; if (_sp > XB_SPIN_CAP) { atomicAdd(&(bar)[XB_TMO], 1u); break; } } } } while (0)
; DI void xcd_barrier(const XcdBarrier& b) {
;   asm volatile("s_waitcnt vmcnt(0)" ::: "memory");
;   __syncthreads();
;   if (threadIdx.x == 0) {
;     unsigned* bar = b.bar;
;     __builtin_amdgcn_s_waitcnt(0);
;     unsigned nloc = b.st[0], nx = b.st[1];
;     if (nloc == 0u) { xcd_barrier_complete(bar, b.x, nloc, nx); b.st[0] = nloc; b.st[1] = nx; }
;     const unsigned old = xb_add(&bar[XB_XSUB(b.x)], 1u);
;     const unsigned gen = old / nloc;
;     if (old + 1u == (gen + 1u) * nloc) {
;       __builtin_amdgcn_fence(__ATOMIC_RELEASE, "agent");
;       asm volatile("s_waitcnt vmcnt(0)" ::: "memory");
;       const unsigned og = xb_add(&bar[XB_TOP], 1u);
;       const unsigned tg = og / nx;
;       if (og + 1u == (tg + 1u) * nx) xb_add(&bar[XB_TOPGEN], 1u);
;       else XB_SPIN(xb_ld(&bar[XB_TOPGEN]) == tg, bar);
;       __builtin_amdgcn_fence(__ATOMIC_ACQUIRE, "agent");
;       xb_add(&bar[XB_XGEN(b.x)], 1u);
;       asm volatile("s_waitcnt vmcnt(0)" ::: "memory");
;     } else {
;       XB_SPIN(xb_ld(&bar[XB_XGEN(b.x)]) == gen, bar);
;       __builtin_amdgcn_fence(__ATOMIC_ACQUIRE, "agent");
;       asm volatile("s_waitcnt vmcnt(0)" ::: "memory");
;     }
;   }
;   __syncthreads();
; }
.Lsy10_poll:
	global_load_dword v6, v7, s[88:89] sc1
	s_waitcnt vmcnt(0)
	v_readfirstlane_b32 s22, v6
	s_sub_i32 s22, s22, s20
	s_cmp_ge_i32 s22, 0
	s_cbranch_scc1 .Lsy10_done
	s_add_i32 s24, s24, 1
	s_sleep 1
	s_cmp_lt_u32 s24, 0x400000
	s_cbranch_scc1 .Lsy10_poll
.Lsy10_done:
	s_getpc_b64 s[98:99]
